# unit boundary: younger wave group runs its epilogue before (not after) the barrier closing its last MFMA segment, so both groups' epilogues overlap (WIN, SSM1, WOUT, FFI, FFO, PLE_1)
# speedup vs baseline: 1.0125x; 1.0125x over previous
;     ...
;     for (;;) {
;         const bool has_next = sched_next<PH, SUB>(E.ws, E.layer, ui + 1, nxt, E.x);
.LBB0_206:
	s_cmpk_gt_u32 s101, 0xff
	s_cbranch_scc0 .Ldb_WIN_nob
	s_barrier

; #define G_STAGE(bufoff, gbase, o0, h64) do { \
;         __builtin_amdgcn_global_load_lds((const unsigned*)((const char*)(gbase) + (o0)), (LAS unsigned*)(lds + (bufoff) + ldsw), 16, 0, 0); \
;         __builtin_amdgcn_global_load_lds((const unsigned*)((const char*)(gbase) + (h64) + (o0)), (LAS unsigned*)(lds + (bufoff) + ldsw + 8192), 16, 0, 0); } while (0)
; #define G_LDA(dst, b, h) do { _Pragma("unroll") for (int m = 0; m < 4; ++m) _Pragma("unroll") for (int k = 0; k < 2; ++k) dst[m][k] = *(const LAS bf16x8*)(lds + G_SA(b, h) + aoff + m * 2048 + k * 1024); } while (0)
; #define G_LDB(dst, b, h) do { _Pragma("unroll") for (int n = 0; n < 2; ++n) _Pragma("unroll") for (int k = 0; k < 2; ++k) dst[n][k] = *(const LAS bf16x8*)(lds + G_SB(b, h) + boff + n * 2048 + k * 1024); } while (0)
; #define G_WAIT_V(n) asm volatile("s_waitcnt vmcnt(" #n ")" ::: "memory")
; #define G_WAIT_L(n) asm volatile("s_waitcnt lgkmcnt(" #n ")" ::: "memory")
; #define G_BAR __builtin_amdgcn_s_barrier()
; #define G_SCHED __builtin_amdgcn_sched_barrier(0)
;     ...
;         for (int t = 0; t < nt; t += 2) {
;             const bool last = (t == nt - 2);
;             const char* a1 = cA + (size_t)(t + 1) * ckA;
;             const char* a2 = last ? nA : cA + (size_t)(t + 2) * ckA; const char* b2 = last ? nB : cB + (size_t)(t + 2) * kB;
;             const char* a3 = a2 + ckA; const char* b3 = b2 + kB;
;             G_LDB(B0, 0, 0); G_SCHED; G_LDA(At, 0, 0); G_STAGE(G_SA(1, 1), a1 + chA, cA0, qA);
;             G_WAIT_L(8); G_BAR; G_WAIT_L(0); G_MMA(0, 0, At, B0); G_BAR; G_SCHED;
;             G_LDB(B1, 0, 1); G_STAGE(G_SB(0, 0), b2, cB0, qB);
;             G_BAR; G_WAIT_L(0); G_MMA(0, 1, At, B1); G_BAR;
;             G_LDA(At, 0, 1); G_STAGE(G_SA(0, 0), a2, cA0, qA);
;             G_BAR; G_WAIT_L(0); G_MMA(1, 0, At, B0); G_BAR; G_SCHED;
;             G_STAGE(G_SB(0, 1), b2 + chB, cB0, qB);
;             G_WAIT_V(6); G_BAR; G_MMA(1, 1, At, B1); G_BAR;
.LBB0_212:
	s_add_u32 s4, s2, 0xfffc0080
	s_addc_u32 s5, s3, -1
	s_add_i32 s41, 0, 0x10000
	v_add_u32_e32 v0, s41, v167
	ds_read_b128 v[136:139], v0
	ds_read_b128 v[144:147], v0 offset:1024
	ds_read_b128 v[148:151], v0 offset:2048
	ds_read_b128 v[152:155], v0 offset:3072
	s_cmp_eq_u32 s23, 12
	s_cselect_b32 s43, s19, s5
	s_cselect_b32 s42, s18, s4
	s_cselect_b32 s51, s21, s22
	s_cselect_b32 s50, s20, s7
	v_lshl_add_u64 v[164:165], s[2:3], 0, v[142:143]
	s_add_i32 m0, s27, 0xc000
	ds_read_b128 v[156:159], v172
	ds_read_b128 v[160:163], v172 offset:1024
	ds_read_b128 v[174:177], v172 offset:2048
	ds_read_b128 v[178:181], v172 offset:3072
	ds_read_b128 v[182:185], v172 offset:4096
	ds_read_b128 v[196:199], v172 offset:5120
	ds_read_b128 v[200:203], v172 offset:6144
	ds_read_b128 v[204:207], v172 offset:7168
	global_load_lds_dwordx4 v[164:165], off
	v_lshl_add_u64 v[164:165], v[164:165], 0, s[0:1]
	s_add_i32 m0, s27, 0xe000
	s_nop 0
	global_load_lds_dwordx4 v[164:165], off
	s_waitcnt lgkmcnt(8)
	s_barrier
	s_waitcnt lgkmcnt(0)
	s_setprio 3
	s_waitcnt lgkmcnt(0)
	v_mfma_f32_16x16x32_bf16 v[132:135], v[136:139], v[156:159], v[132:135]
	v_mfma_f32_16x16x32_bf16 v[128:131], v[148:151], v[156:159], v[128:131]
	v_mfma_f32_16x16x32_bf16 v[116:119], v[136:139], v[174:177], v[116:119]
	v_mfma_f32_16x16x32_bf16 v[112:115], v[148:151], v[174:177], v[112:115]
	v_mfma_f32_16x16x32_bf16 v[100:103], v[136:139], v[182:185], v[100:103]
	v_mfma_f32_16x16x32_bf16 v[96:99], v[148:151], v[182:185], v[96:99]
	v_mfma_f32_16x16x32_bf16 v[84:87], v[136:139], v[200:203], v[84:87]
	v_mfma_f32_16x16x32_bf16 v[80:83], v[148:151], v[200:203], v[80:83]
	v_mfma_f32_16x16x32_bf16 v[132:135], v[144:147], v[160:163], v[132:135]
	v_mfma_f32_16x16x32_bf16 v[128:131], v[152:155], v[160:163], v[128:131]
	v_mfma_f32_16x16x32_bf16 v[116:119], v[144:147], v[178:181], v[116:119]
	v_mfma_f32_16x16x32_bf16 v[112:115], v[152:155], v[178:181], v[112:115]
	v_mfma_f32_16x16x32_bf16 v[100:103], v[144:147], v[196:199], v[100:103]
	v_mfma_f32_16x16x32_bf16 v[96:99], v[152:155], v[196:199], v[96:99]
	v_mfma_f32_16x16x32_bf16 v[84:87], v[144:147], v[204:207], v[84:87]
	v_mfma_f32_16x16x32_bf16 v[80:83], v[152:155], v[204:207], v[80:83]
	s_setprio 0
	s_barrier
	s_add_i32 s4, 0, 0x14000
	s_add_i32 s5, s41, s26
	v_add_u32_e32 v0, s4, v167
	v_lshl_add_u64 v[164:165], s[50:51], 0, v[140:141]
	s_mov_b32 m0, s5
	ds_read_b128 v[208:211], v0
	ds_read_b128 v[212:215], v0 offset:1024
	ds_read_b128 v[216:219], v0 offset:2048
	ds_read_b128 v[220:223], v0 offset:3072
	global_load_lds_dwordx4 v[164:165], off
	v_lshl_add_u64 v[224:225], v[164:165], 0, s[0:1]
	s_add_i32 m0, s5, 0x2000
	s_nop 0
	global_load_lds_dwordx4 v[224:225], off
	s_barrier
	s_waitcnt lgkmcnt(0)
	s_setprio 3
	s_waitcnt lgkmcnt(0)
	v_mfma_f32_16x16x32_bf16 v[124:127], v[208:211], v[156:159], v[124:127]
	v_mfma_f32_16x16x32_bf16 v[120:123], v[216:219], v[156:159], v[120:123]
	v_mfma_f32_16x16x32_bf16 v[108:111], v[208:211], v[174:177], v[108:111]
	v_mfma_f32_16x16x32_bf16 v[104:107], v[216:219], v[174:177], v[104:107]
	v_mfma_f32_16x16x32_bf16 v[92:95], v[208:211], v[182:185], v[92:95]
	v_mfma_f32_16x16x32_bf16 v[88:91], v[216:219], v[182:185], v[88:91]
	v_mfma_f32_16x16x32_bf16 v[76:79], v[208:211], v[200:203], v[76:79]
	v_mfma_f32_16x16x32_bf16 v[72:75], v[216:219], v[200:203], v[72:75]
	v_mfma_f32_16x16x32_bf16 v[124:127], v[212:215], v[160:163], v[124:127]
	v_mfma_f32_16x16x32_bf16 v[120:123], v[220:223], v[160:163], v[120:123]
	v_mfma_f32_16x16x32_bf16 v[108:111], v[212:215], v[178:181], v[108:111]
	v_mfma_f32_16x16x32_bf16 v[104:107], v[220:223], v[178:181], v[104:107]
	v_mfma_f32_16x16x32_bf16 v[92:95], v[212:215], v[196:199], v[92:95]
	v_mfma_f32_16x16x32_bf16 v[88:91], v[220:223], v[196:199], v[88:91]
	v_mfma_f32_16x16x32_bf16 v[76:79], v[212:215], v[204:207], v[76:79]
	v_mfma_f32_16x16x32_bf16 v[72:75], v[220:223], v[204:207], v[72:75]
	s_setprio 0
	s_mov_b32 m0, s27
	v_lshl_add_u64 v[224:225], s[42:43], 0, v[2:3]
	s_barrier
	ds_read_b128 v[156:159], v172 offset:16384
	ds_read_b128 v[160:163], v172 offset:17408
	ds_read_b128 v[174:177], v172 offset:18432
	ds_read_b128 v[178:181], v172 offset:19456
	ds_read_b128 v[182:185], v172 offset:20480
	ds_read_b128 v[196:199], v172 offset:21504
	ds_read_b128 v[200:203], v172 offset:22528
	ds_read_b128 v[204:207], v172 offset:23552
	global_load_lds_dwordx4 v[224:225], off
	v_lshl_add_u64 v[226:227], v[224:225], 0, s[0:1]
	s_mov_b32 m0, s28
	s_nop 0
	global_load_lds_dwordx4 v[226:227], off
	s_barrier
	s_waitcnt lgkmcnt(0)
	s_setprio 3
	s_waitcnt lgkmcnt(0)
	v_mfma_f32_16x16x32_bf16 v[68:71], v[136:139], v[156:159], v[68:71]
	v_mfma_f32_16x16x32_bf16 v[64:67], v[148:151], v[156:159], v[64:67]
	v_mfma_f32_16x16x32_bf16 v[52:55], v[136:139], v[174:177], v[52:55]
	v_mfma_f32_16x16x32_bf16 v[48:51], v[148:151], v[174:177], v[48:51]
	v_mfma_f32_16x16x32_bf16 v[36:39], v[136:139], v[182:185], v[36:39]
	v_mfma_f32_16x16x32_bf16 v[32:35], v[148:151], v[182:185], v[32:35]
	v_mfma_f32_16x16x32_bf16 v[20:23], v[136:139], v[200:203], v[20:23]
	v_mfma_f32_16x16x32_bf16 v[16:19], v[148:151], v[200:203], v[16:19]
	v_mfma_f32_16x16x32_bf16 v[68:71], v[144:147], v[160:163], v[68:71]
	v_mfma_f32_16x16x32_bf16 v[64:67], v[152:155], v[160:163], v[64:67]
	v_mfma_f32_16x16x32_bf16 v[52:55], v[144:147], v[178:181], v[52:55]
	v_mfma_f32_16x16x32_bf16 v[48:51], v[152:155], v[178:181], v[48:51]
	v_mfma_f32_16x16x32_bf16 v[36:39], v[144:147], v[196:199], v[36:39]
	v_mfma_f32_16x16x32_bf16 v[32:35], v[152:155], v[196:199], v[32:35]
	v_mfma_f32_16x16x32_bf16 v[20:23], v[144:147], v[204:207], v[20:23]
	v_mfma_f32_16x16x32_bf16 v[16:19], v[152:155], v[204:207], v[16:19]
	s_setprio 0
	s_barrier
; #define G_STAGE(bufoff, gbase, o0, h64) do { \
;         __builtin_amdgcn_global_load_lds((const unsigned*)((const char*)(gbase) + (o0)), (LAS unsigned*)(lds + (bufoff) + ldsw), 16, 0, 0); \
;         __builtin_amdgcn_global_load_lds((const unsigned*)((const char*)(gbase) + (h64) + (o0)), (LAS unsigned*)(lds + (bufoff) + ldsw + 8192), 16, 0, 0); } while (0)
; #define G_LDA(dst, b, h) do { _Pragma("unroll") for (int m = 0; m < 4; ++m) _Pragma("unroll") for (int k = 0; k < 2; ++k) dst[m][k] = *(const LAS bf16x8*)(lds + G_SA(b, h) + aoff + m * 2048 + k * 1024); } while (0)
; #define G_LDB(dst, b, h) do { _Pragma("unroll") for (int n = 0; n < 2; ++n) _Pragma("unroll") for (int k = 0; k < 2; ++k) dst[n][k] = *(const LAS bf16x8*)(lds + G_SB(b, h) + boff + n * 2048 + k * 1024); } while (0)
; #define G_WAIT_V(n) asm volatile("s_waitcnt vmcnt(" #n ")" ::: "memory")
; #define G_WAIT_L(n) asm volatile("s_waitcnt lgkmcnt(" #n ")" ::: "memory")
; #define G_BAR __builtin_amdgcn_s_barrier()
; #define G_SCHED __builtin_amdgcn_sched_barrier(0)
;     ...
;             G_STAGE(G_SB(0, 1), b2 + chB, cB0, qB);
;             G_WAIT_V(6); G_BAR; G_MMA(1, 1, At, B1); G_BAR;
;             G_LDB(B0, 1, 0); G_SCHED; G_LDA(At, 1, 0); G_STAGE(G_SA(0, 1), a2 + chA, cA0, qA);
;             G_WAIT_L(8); G_BAR; G_WAIT_L(0); G_MMA(0, 0, At, B0); G_BAR; G_SCHED;
;             G_LDB(B1, 1, 1); G_STAGE(G_SB(1, 0), b3, cB0, qB);
;             G_BAR; G_WAIT_L(0); G_MMA(0, 1, At, B1); G_BAR;
;             G_LDA(At, 1, 1); G_STAGE(G_SA(1, 0), a3, cA0, qA);
;             G_BAR; G_WAIT_L(0); G_MMA(1, 0, At, B0); G_BAR; G_SCHED;
	s_add_i32 s4, s4, s26
	v_lshl_add_u64 v[136:137], v[164:165], 0, s[52:53]
	s_mov_b32 m0, s4
	s_nop 0
	global_load_lds_dwordx4 v[136:137], off
	v_lshl_add_u64 v[136:137], v[164:165], 0, s[54:55]
	s_add_i32 m0, s4, 0x2000
	s_nop 0
	global_load_lds_dwordx4 v[136:137], off
	s_waitcnt vmcnt(6)
	s_barrier
	s_setprio 3
	v_mfma_f32_16x16x32_bf16 v[60:63], v[208:211], v[156:159], v[60:63]
	v_mfma_f32_16x16x32_bf16 v[56:59], v[216:219], v[156:159], v[56:59]
	v_mfma_f32_16x16x32_bf16 v[44:47], v[208:211], v[174:177], v[44:47]
	v_mfma_f32_16x16x32_bf16 v[40:43], v[216:219], v[174:177], v[40:43]
	v_mfma_f32_16x16x32_bf16 v[28:31], v[208:211], v[182:185], v[28:31]
	v_mfma_f32_16x16x32_bf16 v[24:27], v[216:219], v[182:185], v[24:27]
	v_mfma_f32_16x16x32_bf16 v[12:15], v[208:211], v[200:203], v[12:15]
	v_mfma_f32_16x16x32_bf16 v[8:11], v[216:219], v[200:203], v[8:11]
	v_mfma_f32_16x16x32_bf16 v[60:63], v[212:215], v[160:163], v[60:63]
	v_mfma_f32_16x16x32_bf16 v[56:59], v[220:223], v[160:163], v[56:59]
	v_mfma_f32_16x16x32_bf16 v[44:47], v[212:215], v[178:181], v[44:47]
	v_mfma_f32_16x16x32_bf16 v[40:43], v[220:223], v[178:181], v[40:43]
	v_mfma_f32_16x16x32_bf16 v[28:31], v[212:215], v[196:199], v[28:31]
	v_mfma_f32_16x16x32_bf16 v[24:27], v[220:223], v[196:199], v[24:27]
	v_mfma_f32_16x16x32_bf16 v[12:15], v[212:215], v[204:207], v[12:15]
	v_mfma_f32_16x16x32_bf16 v[8:11], v[220:223], v[204:207], v[8:11]
	s_setprio 0
	s_add_i32 s4, 0, 0x18000
	v_add_u32_e32 v0, s4, v167
	s_barrier
	ds_read_b128 v[136:139], v0
	ds_read_b128 v[144:147], v0 offset:1024
	ds_read_b128 v[148:151], v0 offset:2048
	ds_read_b128 v[152:155], v0 offset:3072
	s_mov_b32 m0, s29
	v_lshl_add_u64 v[208:209], v[224:225], 0, s[52:53]
	ds_read_b128 v[156:159], v172 offset:32768
	ds_read_b128 v[160:163], v172 offset:33792
	ds_read_b128 v[174:177], v172 offset:34816
	ds_read_b128 v[178:181], v172 offset:35840
	ds_read_b128 v[182:185], v172 offset:36864
	ds_read_b128 v[196:199], v172 offset:37888
	ds_read_b128 v[200:203], v172 offset:38912
	ds_read_b128 v[204:207], v172 offset:39936
	global_load_lds_dwordx4 v[208:209], off
	v_lshl_add_u64 v[208:209], v[224:225], 0, s[54:55]
	s_mov_b32 m0, s30
	s_nop 0
	global_load_lds_dwordx4 v[208:209], off
	s_waitcnt lgkmcnt(8)
	s_barrier
	s_waitcnt lgkmcnt(0)
	s_setprio 3
	s_waitcnt lgkmcnt(0)
	v_mfma_f32_16x16x32_bf16 v[132:135], v[136:139], v[156:159], v[132:135]
	v_mfma_f32_16x16x32_bf16 v[128:131], v[148:151], v[156:159], v[128:131]
	v_mfma_f32_16x16x32_bf16 v[116:119], v[136:139], v[174:177], v[116:119]
	v_mfma_f32_16x16x32_bf16 v[112:115], v[148:151], v[174:177], v[112:115]
	v_mfma_f32_16x16x32_bf16 v[100:103], v[136:139], v[182:185], v[100:103]
	v_mfma_f32_16x16x32_bf16 v[96:99], v[148:151], v[182:185], v[96:99]
	v_mfma_f32_16x16x32_bf16 v[84:87], v[136:139], v[200:203], v[84:87]
	v_mfma_f32_16x16x32_bf16 v[80:83], v[148:151], v[200:203], v[80:83]
	v_mfma_f32_16x16x32_bf16 v[132:135], v[144:147], v[160:163], v[132:135]
	v_mfma_f32_16x16x32_bf16 v[128:131], v[152:155], v[160:163], v[128:131]
	v_mfma_f32_16x16x32_bf16 v[116:119], v[144:147], v[178:181], v[116:119]
	v_mfma_f32_16x16x32_bf16 v[112:115], v[152:155], v[178:181], v[112:115]
	v_mfma_f32_16x16x32_bf16 v[100:103], v[144:147], v[196:199], v[100:103]
	v_mfma_f32_16x16x32_bf16 v[96:99], v[152:155], v[196:199], v[96:99]
	v_mfma_f32_16x16x32_bf16 v[84:87], v[144:147], v[204:207], v[84:87]
	v_mfma_f32_16x16x32_bf16 v[80:83], v[152:155], v[204:207], v[80:83]
	s_setprio 0
	s_barrier
	s_add_i32 s5, 0, 0x1c000
	s_add_i32 s4, s4, s26
	v_add_u32_e32 v0, s5, v167
	v_lshl_add_u64 v[226:227], v[164:165], 0, s[46:47]
	s_mov_b32 m0, s4
	ds_read_b128 v[208:211], v0
	ds_read_b128 v[212:215], v0 offset:1024
	ds_read_b128 v[216:219], v0 offset:2048
	ds_read_b128 v[220:223], v0 offset:3072
	global_load_lds_dwordx4 v[226:227], off
	v_lshl_add_u64 v[226:227], v[164:165], 0, s[58:59]
	s_add_i32 m0, s4, 0x2000
	s_nop 0
	global_load_lds_dwordx4 v[226:227], off
	s_barrier
	s_waitcnt lgkmcnt(0)
	s_setprio 3
	s_waitcnt lgkmcnt(0)
	v_mfma_f32_16x16x32_bf16 v[124:127], v[208:211], v[156:159], v[124:127]
	v_mfma_f32_16x16x32_bf16 v[120:123], v[216:219], v[156:159], v[120:123]
	v_mfma_f32_16x16x32_bf16 v[108:111], v[208:211], v[174:177], v[108:111]
	v_mfma_f32_16x16x32_bf16 v[104:107], v[216:219], v[174:177], v[104:107]
	v_mfma_f32_16x16x32_bf16 v[92:95], v[208:211], v[182:185], v[92:95]
	v_mfma_f32_16x16x32_bf16 v[88:91], v[216:219], v[182:185], v[88:91]
	v_mfma_f32_16x16x32_bf16 v[76:79], v[208:211], v[200:203], v[76:79]
	v_mfma_f32_16x16x32_bf16 v[72:75], v[216:219], v[200:203], v[72:75]
	v_mfma_f32_16x16x32_bf16 v[124:127], v[212:215], v[160:163], v[124:127]
	v_mfma_f32_16x16x32_bf16 v[120:123], v[220:223], v[160:163], v[120:123]
	v_mfma_f32_16x16x32_bf16 v[108:111], v[212:215], v[178:181], v[108:111]
	v_mfma_f32_16x16x32_bf16 v[104:107], v[220:223], v[178:181], v[104:107]
	v_mfma_f32_16x16x32_bf16 v[92:95], v[212:215], v[196:199], v[92:95]
	v_mfma_f32_16x16x32_bf16 v[88:91], v[220:223], v[196:199], v[88:91]
	v_mfma_f32_16x16x32_bf16 v[76:79], v[212:215], v[204:207], v[76:79]
	v_mfma_f32_16x16x32_bf16 v[72:75], v[220:223], v[204:207], v[72:75]
	s_setprio 0
	s_mov_b32 m0, s31
	v_lshl_add_u64 v[226:227], v[224:225], 0, s[46:47]
	s_barrier
; __device__ __forceinline__ u32x4 pack8(const f32x4 a, const f32x4 b) { u32x4 w; w.x = cvt_pk_bf16(a[0], a[1]); w.y = cvt_pk_bf16(a[2], a[3]); w.z = cvt_pk_bf16(b[0], b[1]); w.w = cvt_pk_bf16(b[2], b[3]); return w; }
; #define G_STAGE(bufoff, gbase, o0, h64) do { \
;         __builtin_amdgcn_global_load_lds((const unsigned*)((const char*)(gbase) + (o0)), (LAS unsigned*)(lds + (bufoff) + ldsw), 16, 0, 0); \
;         __builtin_amdgcn_global_load_lds((const unsigned*)((const char*)(gbase) + (h64) + (o0)), (LAS unsigned*)(lds + (bufoff) + ldsw + 8192), 16, 0, 0); } while (0)
; #define G_LDA(dst, b, h) do { _Pragma("unroll") for (int m = 0; m < 4; ++m) _Pragma("unroll") for (int k = 0; k < 2; ++k) dst[m][k] = *(const LAS bf16x8*)(lds + G_SA(b, h) + aoff + m * 2048 + k * 1024); } while (0)
; #define G_BAR __builtin_amdgcn_s_barrier()
;     template <int KIND> __device__ __forceinline__ void run(f32x4 (&acc)[2][2][4][2], const Unit& u, int tid_in) const {
;     ...
;         if constexpr (KIND == K_WIN) { float rs[8]; get_rs(u, wr, fr, rs);
; #pragma unroll
;             for (int ai = 0; ai < 2; ++ai)
; #pragma unroll
;                 for (int m = 0; m < 4; ++m) { int row = rbase + ai * 128 + m * 16; asm volatile("" : "+v"(row)); const float r = rs[ai * 4 + m];
;                     if (u.pn >= 4 && u.pn < 8) {
;                         const f32x4 v0 = (acc[ai][0][m][0] * r) * (acc[ai][1][m][0] * r), v1 = (acc[ai][0][m][1] * r) * (acc[ai][1][m][1] * r);
;                         *(u32x4*)(zb + (size_t)row * ZW + 1024 + (u.pn - 4) * 128 + cl) = pack8(v0, v1); }
;                     else
; #pragma unroll
;                     for (int bj = 0; bj < 2; ++bj) { const u32x4 w = pack8(acc[ai][bj][m][0] * r, acc[ai][bj][m][1] * r);
;                         if (u.pn < 2) { const int col = u.pn * 256 + bj * 128 + cl; *(u32x4*)((bf16_t*)x + ((size_t)(col >> 4) * T_TOK + row) * 16 + (col & 15)) = w; }
;                         else if (u.pn < 10 || bj == 0) *(u32x4*)(zb + (size_t)row * ZW + u.pn * 256 + bj * 128 + cl) = w;
;     ...
;             G_LDA(At, 1, 1); G_STAGE(G_SA(1, 0), a3, cA0, qA);
;             G_BAR; G_WAIT_L(0); G_MMA(1, 0, At, B0); G_BAR; G_SCHED;
;             G_STAGE(G_SB(1, 1), b3 + chB, cB0, qB);
;             G_WAIT_V(6); G_BAR; G_MMA(1, 1, At, B1); G_BAR;
;         }
;         E.template run<cs.kind>(acc, cur, tid);
;         if (!has_next) break;
	ds_read_b128 v[156:159], v172 offset:49152
	ds_read_b128 v[160:163], v172 offset:50176
	ds_read_b128 v[174:177], v172 offset:51200
	ds_read_b128 v[178:181], v172 offset:52224
	ds_read_b128 v[182:185], v172 offset:53248
	ds_read_b128 v[196:199], v172 offset:54272
	ds_read_b128 v[200:203], v172 offset:55296
	ds_read_b128 v[204:207], v172 offset:56320
	global_load_lds_dwordx4 v[226:227], off
	v_lshl_add_u64 v[224:225], v[224:225], 0, s[58:59]
	s_mov_b32 m0, s34
	s_nop 0
	global_load_lds_dwordx4 v[224:225], off
	s_barrier
	s_waitcnt lgkmcnt(0)
	s_setprio 3
	s_waitcnt lgkmcnt(0)
	v_mfma_f32_16x16x32_bf16 v[68:71], v[136:139], v[156:159], v[68:71]
	v_mfma_f32_16x16x32_bf16 v[64:67], v[148:151], v[156:159], v[64:67]
	v_mfma_f32_16x16x32_bf16 v[52:55], v[136:139], v[174:177], v[52:55]
	v_mfma_f32_16x16x32_bf16 v[48:51], v[148:151], v[174:177], v[48:51]
	v_mfma_f32_16x16x32_bf16 v[36:39], v[136:139], v[182:185], v[36:39]
	v_mfma_f32_16x16x32_bf16 v[32:35], v[148:151], v[182:185], v[32:35]
	v_mfma_f32_16x16x32_bf16 v[20:23], v[136:139], v[200:203], v[20:23]
	v_mfma_f32_16x16x32_bf16 v[16:19], v[148:151], v[200:203], v[16:19]
	v_mfma_f32_16x16x32_bf16 v[68:71], v[144:147], v[160:163], v[68:71]
	v_mfma_f32_16x16x32_bf16 v[64:67], v[152:155], v[160:163], v[64:67]
	v_mfma_f32_16x16x32_bf16 v[52:55], v[144:147], v[178:181], v[52:55]
	v_mfma_f32_16x16x32_bf16 v[48:51], v[152:155], v[178:181], v[48:51]
	v_mfma_f32_16x16x32_bf16 v[36:39], v[144:147], v[196:199], v[36:39]
	v_mfma_f32_16x16x32_bf16 v[32:35], v[152:155], v[196:199], v[32:35]
	v_mfma_f32_16x16x32_bf16 v[20:23], v[144:147], v[204:207], v[20:23]
	v_mfma_f32_16x16x32_bf16 v[16:19], v[152:155], v[204:207], v[16:19]
	s_setprio 0
	s_barrier
	s_add_i32 s4, s5, s26
	v_lshl_add_u64 v[136:137], v[164:165], 0, s[62:63]
	s_mov_b32 m0, s4
	s_nop 0
	global_load_lds_dwordx4 v[136:137], off
	v_lshl_add_u64 v[136:137], v[164:165], 0, s[64:65]
	s_add_i32 m0, s4, 0x2000
	s_nop 0
	global_load_lds_dwordx4 v[136:137], off
	s_waitcnt vmcnt(6)
	s_barrier
	s_setprio 3
	v_mfma_f32_16x16x32_bf16 v[60:63], v[208:211], v[156:159], v[60:63]
	v_mfma_f32_16x16x32_bf16 v[56:59], v[216:219], v[156:159], v[56:59]
	v_mfma_f32_16x16x32_bf16 v[44:47], v[208:211], v[174:177], v[44:47]
	v_mfma_f32_16x16x32_bf16 v[40:43], v[216:219], v[174:177], v[40:43]
	v_mfma_f32_16x16x32_bf16 v[28:31], v[208:211], v[182:185], v[28:31]
	v_mfma_f32_16x16x32_bf16 v[24:27], v[216:219], v[182:185], v[24:27]
	v_mfma_f32_16x16x32_bf16 v[12:15], v[208:211], v[200:203], v[12:15]
	v_mfma_f32_16x16x32_bf16 v[8:11], v[216:219], v[200:203], v[8:11]
	v_mfma_f32_16x16x32_bf16 v[60:63], v[212:215], v[160:163], v[60:63]
	v_mfma_f32_16x16x32_bf16 v[56:59], v[220:223], v[160:163], v[56:59]
	v_mfma_f32_16x16x32_bf16 v[44:47], v[212:215], v[178:181], v[44:47]
	v_mfma_f32_16x16x32_bf16 v[40:43], v[220:223], v[178:181], v[40:43]
	v_mfma_f32_16x16x32_bf16 v[28:31], v[212:215], v[196:199], v[28:31]
	v_mfma_f32_16x16x32_bf16 v[24:27], v[220:223], v[196:199], v[24:27]
	v_mfma_f32_16x16x32_bf16 v[12:15], v[212:215], v[204:207], v[12:15]
	v_mfma_f32_16x16x32_bf16 v[8:11], v[220:223], v[204:207], v[8:11]
	s_setprio 0
	s_add_i32 s23, s23, 2
	s_add_u32 s2, s2, 0x100
	s_addc_u32 s3, s3, 0
	s_add_u32 s7, s7, 0x100
	s_addc_u32 s22, s22, 0
	s_cmp_gt_u32 s23, 13
	s_cbranch_scc0 .Ldb_WIN_cont
	v_readfirstlane_b32 s101, v186
	s_cmpk_gt_u32 s101, 0xff
	s_cbranch_scc1 .Ldb_WIN_exit
	s_barrier
	s_branch .Ldb_WIN_exit
.Ldb_WIN_cont:
	s_barrier
	s_branch .LBB0_212
.Ldb_WIN_exit:
	v_mov_b32_e32 v0, v166
	s_lshl_b32 s5, s6, 10
	v_readfirstlane_b32 s2, v0
	s_ashr_i32 s3, s2, 2
	s_lshr_b32 s4, s2, 1
	s_add_i32 s5, s5, 0
	s_and_b32 s2, s2, 0xffffff00
	v_and_b32_e32 v136, 15, v0
	s_add_i32 s5, s5, s2
	v_lshl_add_u32 v137, v136, 2, s5
	v_add_u32_e32 v137, 0x20010, v137
	ds_read2_b32 v[160:161], v137 offset1:16
	ds_read2_b32 v[154:155], v137 offset0:32 offset1:48
	ds_read2_b32 v[150:151], v137 offset0:128 offset1:144
	ds_read2_b32 v[146:147], v137 offset0:160 offset1:176
	s_andn2_b32 s3, s3, 63
	s_and_b32 s4, s4, 0x60
	v_lshrrev_b32_e32 v0, 1, v0
	v_and_or_b32 v173, v0, 24, s4
	v_or_b32_e32 v136, s3, v136
	s_and_b32 s4, s25, -4
	s_waitcnt lgkmcnt(0)
	v_mov_b32_e32 v156, v161
	v_lshl_add_u32 v145, s33, 8, v136
	s_cmp_lg_u32 s4, 4
	v_mov_b32_e32 v161, v160
	v_mov_b32_e32 v152, v155
	v_mov_b32_e32 v148, v151
	v_mov_b32_e32 v144, v147
	v_and_b32_e32 v174, 8, v0
	v_mov_b32_e32 v158, v145
	s_cselect_b64 s[2:3], -1, 0
	s_cmp_eq_u32 s4, 4
	s_mov_b64 s[6:7], -1
	v_pk_mul_f32 v[132:133], v[132:133], v[160:161]
	v_pk_mul_f32 v[128:129], v[128:129], v[160:161]
	s_cbranch_scc1 .LBB0_227
	v_mov_b64_e32 v[136:137], s[12:13]
	v_mad_i64_i32 v[162:163], s[6:7], v158, s76, v[136:137]
	s_cmp_gt_i32 s25, 1
	v_mov_b32_e32 v136, v160
	v_mov_b32_e32 v137, v160
	s_cselect_b64 s[6:7], -1, 0
	v_pk_mul_f32 v[138:139], v[134:135], v[136:137]
	s_lshl_b32 s74, s25, 8
	s_mov_b64 s[22:23], -1
	s_and_b64 vcc, exec, s[6:7]
	v_pk_mul_f32 v[164:165], v[130:131], v[136:137]
	v_cvt_pk_bf16_f32 v136, v132, v133
	v_cvt_pk_bf16_f32 v137, v138, v139
	v_cvt_pk_bf16_f32 v138, v128, v129
	s_nop 0
	v_cvt_pk_bf16_f32 v139, v164, v165
	s_cbranch_vccz .LBB0_216
	v_lshl_add_u64 v[164:165], s[74:75], 1, v[162:163]
	v_lshlrev_b32_e32 v0, 1, v173
	v_lshl_add_u64 v[164:165], v[164:165], 0, v[0:1]
	global_store_dwordx4 v[164:165], v[136:139], off
	s_mov_b64 s[22:23], 0

; #define G_STAGE(bufoff, gbase, o0, h64) do { \
;         __builtin_amdgcn_global_load_lds((const unsigned*)((const char*)(gbase) + (o0)), (LAS unsigned*)(lds + (bufoff) + ldsw), 16, 0, 0); \
;         __builtin_amdgcn_global_load_lds((const unsigned*)((const char*)(gbase) + (h64) + (o0)), (LAS unsigned*)(lds + (bufoff) + ldsw + 8192), 16, 0, 0); } while (0)
; #define G_LDA(dst, b, h) do { _Pragma("unroll") for (int m = 0; m < 4; ++m) _Pragma("unroll") for (int k = 0; k < 2; ++k) dst[m][k] = *(const LAS bf16x8*)(lds + G_SA(b, h) + aoff + m * 2048 + k * 1024); } while (0)
; #define G_LDB(dst, b, h) do { _Pragma("unroll") for (int n = 0; n < 2; ++n) _Pragma("unroll") for (int k = 0; k < 2; ++k) dst[n][k] = *(const LAS bf16x8*)(lds + G_SB(b, h) + boff + n * 2048 + k * 1024); } while (0)
; #define G_WAIT_L(n) asm volatile("s_waitcnt lgkmcnt(" #n ")" ::: "memory")
; #define G_BAR __builtin_amdgcn_s_barrier()
; #define G_SCHED __builtin_amdgcn_sched_barrier(0)
;     ...
;         for (int t = 0; t < nt; t += 2) {
;             const bool last = (t == nt - 2);
;             const char* a1 = cA + (size_t)(t + 1) * ckA;
;             const char* a2 = last ? nA : cA + (size_t)(t + 2) * ckA; const char* b2 = last ? nB : cB + (size_t)(t + 2) * kB;
;             const char* a3 = a2 + ckA; const char* b3 = b2 + kB;
;             G_LDB(B0, 0, 0); G_SCHED; G_LDA(At, 0, 0); G_STAGE(G_SA(1, 1), a1 + chA, cA0, qA);
;             G_WAIT_L(8); G_BAR; G_WAIT_L(0); G_MMA(0, 0, At, B0); G_BAR; G_SCHED;
;             G_LDB(B1, 0, 1); G_STAGE(G_SB(0, 0), b2, cB0, qB);
;             G_BAR; G_WAIT_L(0); G_MMA(0, 1, At, B1); G_BAR;
;             G_LDA(At, 0, 1); G_STAGE(G_SA(0, 0), a2, cA0, qA);
;             G_BAR; G_WAIT_L(0); G_MMA(1, 0, At, B0); G_BAR; G_SCHED;
.LBB0_450:
	s_add_u32 s4, s6, 0xfffe0080
	s_addc_u32 s5, s7, -1
	s_add_i32 s41, 0, 0x10000
	v_add_u32_e32 v0, s41, v145
	ds_read_b128 v[140:143], v0
	ds_read_b128 v[148:151], v0 offset:1024
	ds_read_b128 v[152:155], v0 offset:2048
	ds_read_b128 v[156:159], v0 offset:3072
	s_cmp_eq_u32 s21, 4
	s_cselect_b32 s23, s11, s5
	s_cselect_b32 s22, s10, s4
	s_cselect_b32 s43, s17, s20
	s_cselect_b32 s42, s16, s19
	v_lshl_add_u64 v[184:185], s[6:7], 0, v[138:139]
	s_add_i32 m0, s27, 0xc000
	ds_read_b128 v[160:163], v146
	ds_read_b128 v[164:167], v146 offset:1024
	ds_read_b128 v[172:175], v146 offset:2048
	ds_read_b128 v[176:179], v146 offset:3072
	ds_read_b128 v[180:183], v146 offset:4096
	ds_read_b128 v[196:199], v146 offset:5120
	ds_read_b128 v[200:203], v146 offset:6144
	ds_read_b128 v[204:207], v146 offset:7168
	global_load_lds_dwordx4 v[184:185], off
	v_lshl_add_u64 v[184:185], v[184:185], 0, s[52:53]
	s_add_i32 m0, s27, 0xe000
	s_nop 0
	global_load_lds_dwordx4 v[184:185], off
	s_waitcnt lgkmcnt(8)
	s_barrier
	s_waitcnt lgkmcnt(0)
	s_setprio 3
	s_waitcnt lgkmcnt(0)
	v_mfma_f32_16x16x32_bf16 v[132:135], v[140:143], v[160:163], v[132:135]
	v_mfma_f32_16x16x32_bf16 v[128:131], v[152:155], v[160:163], v[128:131]
	v_mfma_f32_16x16x32_bf16 v[116:119], v[140:143], v[172:175], v[116:119]
	v_mfma_f32_16x16x32_bf16 v[112:115], v[152:155], v[172:175], v[112:115]
	v_mfma_f32_16x16x32_bf16 v[100:103], v[140:143], v[180:183], v[100:103]
	v_mfma_f32_16x16x32_bf16 v[96:99], v[152:155], v[180:183], v[96:99]
	v_mfma_f32_16x16x32_bf16 v[84:87], v[140:143], v[200:203], v[84:87]
	v_mfma_f32_16x16x32_bf16 v[80:83], v[152:155], v[200:203], v[80:83]
	v_mfma_f32_16x16x32_bf16 v[132:135], v[148:151], v[164:167], v[132:135]
	v_mfma_f32_16x16x32_bf16 v[128:131], v[156:159], v[164:167], v[128:131]
	v_mfma_f32_16x16x32_bf16 v[116:119], v[148:151], v[176:179], v[116:119]
	v_mfma_f32_16x16x32_bf16 v[112:115], v[156:159], v[176:179], v[112:115]
	v_mfma_f32_16x16x32_bf16 v[100:103], v[148:151], v[196:199], v[100:103]
	v_mfma_f32_16x16x32_bf16 v[96:99], v[156:159], v[196:199], v[96:99]
	v_mfma_f32_16x16x32_bf16 v[84:87], v[148:151], v[204:207], v[84:87]
	v_mfma_f32_16x16x32_bf16 v[80:83], v[156:159], v[204:207], v[80:83]
	s_setprio 0
	s_barrier
	s_add_i32 s4, 0, 0x14000
	s_add_i32 s5, s41, s26
	v_add_u32_e32 v0, s4, v145
	v_lshl_add_u64 v[184:185], s[42:43], 0, v[136:137]
	s_mov_b32 m0, s5
	ds_read_b128 v[208:211], v0
	ds_read_b128 v[212:215], v0 offset:1024
	ds_read_b128 v[216:219], v0 offset:2048
	ds_read_b128 v[220:223], v0 offset:3072
	global_load_lds_dwordx4 v[184:185], off
	v_lshl_add_u64 v[224:225], v[184:185], 0, s[52:53]
	s_add_i32 m0, s5, 0x2000
	s_nop 0
	global_load_lds_dwordx4 v[224:225], off
	s_barrier
	s_waitcnt lgkmcnt(0)
	s_setprio 3
	s_waitcnt lgkmcnt(0)
	v_mfma_f32_16x16x32_bf16 v[124:127], v[208:211], v[160:163], v[124:127]
	v_mfma_f32_16x16x32_bf16 v[120:123], v[216:219], v[160:163], v[120:123]
	v_mfma_f32_16x16x32_bf16 v[108:111], v[208:211], v[172:175], v[108:111]
	v_mfma_f32_16x16x32_bf16 v[104:107], v[216:219], v[172:175], v[104:107]
	v_mfma_f32_16x16x32_bf16 v[92:95], v[208:211], v[180:183], v[92:95]
	v_mfma_f32_16x16x32_bf16 v[88:91], v[216:219], v[180:183], v[88:91]
	v_mfma_f32_16x16x32_bf16 v[76:79], v[208:211], v[200:203], v[76:79]
	v_mfma_f32_16x16x32_bf16 v[72:75], v[216:219], v[200:203], v[72:75]
	v_mfma_f32_16x16x32_bf16 v[124:127], v[212:215], v[164:167], v[124:127]
	v_mfma_f32_16x16x32_bf16 v[120:123], v[220:223], v[164:167], v[120:123]
	v_mfma_f32_16x16x32_bf16 v[108:111], v[212:215], v[176:179], v[108:111]
	v_mfma_f32_16x16x32_bf16 v[104:107], v[220:223], v[176:179], v[104:107]
	v_mfma_f32_16x16x32_bf16 v[92:95], v[212:215], v[196:199], v[92:95]
	v_mfma_f32_16x16x32_bf16 v[88:91], v[220:223], v[196:199], v[88:91]
	v_mfma_f32_16x16x32_bf16 v[76:79], v[212:215], v[204:207], v[76:79]
	v_mfma_f32_16x16x32_bf16 v[72:75], v[220:223], v[204:207], v[72:75]
	s_setprio 0
	s_mov_b32 m0, s27
	v_lshl_add_u64 v[224:225], s[22:23], 0, v[2:3]
	s_barrier
	ds_read_b128 v[160:163], v146 offset:16384
	ds_read_b128 v[164:167], v146 offset:17408
	ds_read_b128 v[172:175], v146 offset:18432
	ds_read_b128 v[176:179], v146 offset:19456
	ds_read_b128 v[180:183], v146 offset:20480
	ds_read_b128 v[196:199], v146 offset:21504
	ds_read_b128 v[200:203], v146 offset:22528
	ds_read_b128 v[204:207], v146 offset:23552
	global_load_lds_dwordx4 v[224:225], off
	v_lshl_add_u64 v[226:227], v[224:225], 0, s[52:53]
	s_mov_b32 m0, s28
	s_nop 0
	global_load_lds_dwordx4 v[226:227], off
	s_barrier
	s_waitcnt lgkmcnt(0)
	s_setprio 3
	s_waitcnt lgkmcnt(0)
	v_mfma_f32_16x16x32_bf16 v[68:71], v[140:143], v[160:163], v[68:71]
	v_mfma_f32_16x16x32_bf16 v[64:67], v[152:155], v[160:163], v[64:67]
	v_mfma_f32_16x16x32_bf16 v[52:55], v[140:143], v[172:175], v[52:55]
	v_mfma_f32_16x16x32_bf16 v[48:51], v[152:155], v[172:175], v[48:51]
	v_mfma_f32_16x16x32_bf16 v[36:39], v[140:143], v[180:183], v[36:39]
	v_mfma_f32_16x16x32_bf16 v[32:35], v[152:155], v[180:183], v[32:35]
	v_mfma_f32_16x16x32_bf16 v[20:23], v[140:143], v[200:203], v[20:23]
	v_mfma_f32_16x16x32_bf16 v[16:19], v[152:155], v[200:203], v[16:19]
	v_mfma_f32_16x16x32_bf16 v[68:71], v[148:151], v[164:167], v[68:71]
	v_mfma_f32_16x16x32_bf16 v[64:67], v[156:159], v[164:167], v[64:67]
	v_mfma_f32_16x16x32_bf16 v[52:55], v[148:151], v[176:179], v[52:55]
	v_mfma_f32_16x16x32_bf16 v[48:51], v[156:159], v[176:179], v[48:51]
	v_mfma_f32_16x16x32_bf16 v[36:39], v[148:151], v[196:199], v[36:39]
	v_mfma_f32_16x16x32_bf16 v[32:35], v[156:159], v[196:199], v[32:35]
	v_mfma_f32_16x16x32_bf16 v[20:23], v[148:151], v[204:207], v[20:23]
	v_mfma_f32_16x16x32_bf16 v[16:19], v[156:159], v[204:207], v[16:19]
	s_setprio 0
	s_barrier
; #define G_STAGE(bufoff, gbase, o0, h64) do { \
;         __builtin_amdgcn_global_load_lds((const unsigned*)((const char*)(gbase) + (o0)), (LAS unsigned*)(lds + (bufoff) + ldsw), 16, 0, 0); \
;         __builtin_amdgcn_global_load_lds((const unsigned*)((const char*)(gbase) + (h64) + (o0)), (LAS unsigned*)(lds + (bufoff) + ldsw + 8192), 16, 0, 0); } while (0)
; #define G_LDA(dst, b, h) do { _Pragma("unroll") for (int m = 0; m < 4; ++m) _Pragma("unroll") for (int k = 0; k < 2; ++k) dst[m][k] = *(const LAS bf16x8*)(lds + G_SA(b, h) + aoff + m * 2048 + k * 1024); } while (0)
; #define G_LDB(dst, b, h) do { _Pragma("unroll") for (int n = 0; n < 2; ++n) _Pragma("unroll") for (int k = 0; k < 2; ++k) dst[n][k] = *(const LAS bf16x8*)(lds + G_SB(b, h) + boff + n * 2048 + k * 1024); } while (0)
; #define G_WAIT_V(n) asm volatile("s_waitcnt vmcnt(" #n ")" ::: "memory")
; #define G_WAIT_L(n) asm volatile("s_waitcnt lgkmcnt(" #n ")" ::: "memory")
; #define G_BAR __builtin_amdgcn_s_barrier()
; #define G_SCHED __builtin_amdgcn_sched_barrier(0)
;     ...
;             G_STAGE(G_SB(0, 1), b2 + chB, cB0, qB);
;             G_WAIT_V(6); G_BAR; G_MMA(1, 1, At, B1); G_BAR;
;             G_LDB(B0, 1, 0); G_SCHED; G_LDA(At, 1, 0); G_STAGE(G_SA(0, 1), a2 + chA, cA0, qA);
;             G_WAIT_L(8); G_BAR; G_WAIT_L(0); G_MMA(0, 0, At, B0); G_BAR; G_SCHED;
;             G_LDB(B1, 1, 1); G_STAGE(G_SB(1, 0), b3, cB0, qB);
;             G_BAR; G_WAIT_L(0); G_MMA(0, 1, At, B1); G_BAR;
;             G_LDA(At, 1, 1); G_STAGE(G_SA(1, 0), a3, cA0, qA);
;             G_BAR; G_WAIT_L(0); G_MMA(1, 0, At, B0); G_BAR; G_SCHED;
;             G_STAGE(G_SB(1, 1), b3 + chB, cB0, qB);
	s_add_i32 s4, s4, s26
	v_lshl_add_u64 v[140:141], v[184:185], 0, s[0:1]
	s_mov_b32 m0, s4
	s_nop 0
	global_load_lds_dwordx4 v[140:141], off
	v_lshl_add_u64 v[140:141], v[184:185], 0, s[54:55]
	s_add_i32 m0, s4, 0x2000
	s_nop 0
	global_load_lds_dwordx4 v[140:141], off
	s_waitcnt vmcnt(6)
	s_barrier
	s_setprio 3
	v_mfma_f32_16x16x32_bf16 v[60:63], v[208:211], v[160:163], v[60:63]
	v_mfma_f32_16x16x32_bf16 v[56:59], v[216:219], v[160:163], v[56:59]
	v_mfma_f32_16x16x32_bf16 v[44:47], v[208:211], v[172:175], v[44:47]
	v_mfma_f32_16x16x32_bf16 v[40:43], v[216:219], v[172:175], v[40:43]
	v_mfma_f32_16x16x32_bf16 v[28:31], v[208:211], v[180:183], v[28:31]
	v_mfma_f32_16x16x32_bf16 v[24:27], v[216:219], v[180:183], v[24:27]
	v_mfma_f32_16x16x32_bf16 v[12:15], v[208:211], v[200:203], v[12:15]
	v_mfma_f32_16x16x32_bf16 v[8:11], v[216:219], v[200:203], v[8:11]
	v_mfma_f32_16x16x32_bf16 v[60:63], v[212:215], v[164:167], v[60:63]
	v_mfma_f32_16x16x32_bf16 v[56:59], v[220:223], v[164:167], v[56:59]
	v_mfma_f32_16x16x32_bf16 v[44:47], v[212:215], v[176:179], v[44:47]
	v_mfma_f32_16x16x32_bf16 v[40:43], v[220:223], v[176:179], v[40:43]
	v_mfma_f32_16x16x32_bf16 v[28:31], v[212:215], v[196:199], v[28:31]
	v_mfma_f32_16x16x32_bf16 v[24:27], v[220:223], v[196:199], v[24:27]
	v_mfma_f32_16x16x32_bf16 v[12:15], v[212:215], v[204:207], v[12:15]
	v_mfma_f32_16x16x32_bf16 v[8:11], v[220:223], v[204:207], v[8:11]
	s_setprio 0
	s_add_i32 s4, 0, 0x18000
	v_add_u32_e32 v0, s4, v145
	s_barrier
	ds_read_b128 v[140:143], v0
	ds_read_b128 v[148:151], v0 offset:1024
	ds_read_b128 v[152:155], v0 offset:2048
	ds_read_b128 v[156:159], v0 offset:3072
	s_mov_b32 m0, s29
	v_lshl_add_u64 v[208:209], v[224:225], 0, s[0:1]
	ds_read_b128 v[160:163], v146 offset:32768
	ds_read_b128 v[164:167], v146 offset:33792
	ds_read_b128 v[172:175], v146 offset:34816
	ds_read_b128 v[176:179], v146 offset:35840
	ds_read_b128 v[180:183], v146 offset:36864
	ds_read_b128 v[196:199], v146 offset:37888
	ds_read_b128 v[200:203], v146 offset:38912
	ds_read_b128 v[204:207], v146 offset:39936
	global_load_lds_dwordx4 v[208:209], off
	v_lshl_add_u64 v[208:209], v[224:225], 0, s[54:55]
	s_mov_b32 m0, s30
	s_nop 0
	global_load_lds_dwordx4 v[208:209], off
	s_waitcnt lgkmcnt(8)
	s_barrier
	s_waitcnt lgkmcnt(0)
	s_setprio 3
	s_waitcnt lgkmcnt(0)
	v_mfma_f32_16x16x32_bf16 v[132:135], v[140:143], v[160:163], v[132:135]
	v_mfma_f32_16x16x32_bf16 v[128:131], v[152:155], v[160:163], v[128:131]
	v_mfma_f32_16x16x32_bf16 v[116:119], v[140:143], v[172:175], v[116:119]
	v_mfma_f32_16x16x32_bf16 v[112:115], v[152:155], v[172:175], v[112:115]
	v_mfma_f32_16x16x32_bf16 v[100:103], v[140:143], v[180:183], v[100:103]
	v_mfma_f32_16x16x32_bf16 v[96:99], v[152:155], v[180:183], v[96:99]
	v_mfma_f32_16x16x32_bf16 v[84:87], v[140:143], v[200:203], v[84:87]
	v_mfma_f32_16x16x32_bf16 v[80:83], v[152:155], v[200:203], v[80:83]
	v_mfma_f32_16x16x32_bf16 v[132:135], v[148:151], v[164:167], v[132:135]
	v_mfma_f32_16x16x32_bf16 v[128:131], v[156:159], v[164:167], v[128:131]
	v_mfma_f32_16x16x32_bf16 v[116:119], v[148:151], v[176:179], v[116:119]
	v_mfma_f32_16x16x32_bf16 v[112:115], v[156:159], v[176:179], v[112:115]
	v_mfma_f32_16x16x32_bf16 v[100:103], v[148:151], v[196:199], v[100:103]
	v_mfma_f32_16x16x32_bf16 v[96:99], v[156:159], v[196:199], v[96:99]
	v_mfma_f32_16x16x32_bf16 v[84:87], v[148:151], v[204:207], v[84:87]
	v_mfma_f32_16x16x32_bf16 v[80:83], v[156:159], v[204:207], v[80:83]
	s_setprio 0
	s_barrier
	s_add_i32 s5, 0, 0x1c000
	s_add_i32 s4, s4, s26
	v_add_u32_e32 v0, s5, v145
	v_lshl_add_u64 v[226:227], v[184:185], 0, s[46:47]
	s_mov_b32 m0, s4
	ds_read_b128 v[208:211], v0
	ds_read_b128 v[212:215], v0 offset:1024
	ds_read_b128 v[216:219], v0 offset:2048
	ds_read_b128 v[220:223], v0 offset:3072
	global_load_lds_dwordx4 v[226:227], off
	v_lshl_add_u64 v[226:227], v[184:185], 0, s[58:59]
	s_add_i32 m0, s4, 0x2000
	s_nop 0
	global_load_lds_dwordx4 v[226:227], off
	s_barrier
; #define G_STAGE(bufoff, gbase, o0, h64) do { \
;         __builtin_amdgcn_global_load_lds((const unsigned*)((const char*)(gbase) + (o0)), (LAS unsigned*)(lds + (bufoff) + ldsw), 16, 0, 0); \
;         __builtin_amdgcn_global_load_lds((const unsigned*)((const char*)(gbase) + (h64) + (o0)), (LAS unsigned*)(lds + (bufoff) + ldsw + 8192), 16, 0, 0); } while (0)
; #define G_LDA(dst, b, h) do { _Pragma("unroll") for (int m = 0; m < 4; ++m) _Pragma("unroll") for (int k = 0; k < 2; ++k) dst[m][k] = *(const LAS bf16x8*)(lds + G_SA(b, h) + aoff + m * 2048 + k * 1024); } while (0)
; #define G_WAIT_V(n) asm volatile("s_waitcnt vmcnt(" #n ")" ::: "memory")
; #define G_WAIT_L(n) asm volatile("s_waitcnt lgkmcnt(" #n ")" ::: "memory")
; #define G_BAR __builtin_amdgcn_s_barrier()
; #define G_SCHED __builtin_amdgcn_sched_barrier(0)
;     ...
;             G_LDA(At, 1, 1); G_STAGE(G_SA(1, 0), a3, cA0, qA);
;             G_BAR; G_WAIT_L(0); G_MMA(1, 0, At, B0); G_BAR; G_SCHED;
;             G_STAGE(G_SB(1, 1), b3 + chB, cB0, qB);
;             G_WAIT_V(6); G_BAR; G_MMA(1, 1, At, B1); G_BAR;
;         }
;         E.template run<cs.kind>(acc, cur, tid);
;         if (!has_next) break;
	s_waitcnt lgkmcnt(0)
	s_setprio 3
	s_waitcnt lgkmcnt(0)
	v_mfma_f32_16x16x32_bf16 v[124:127], v[208:211], v[160:163], v[124:127]
	v_mfma_f32_16x16x32_bf16 v[120:123], v[216:219], v[160:163], v[120:123]
	v_mfma_f32_16x16x32_bf16 v[108:111], v[208:211], v[172:175], v[108:111]
	v_mfma_f32_16x16x32_bf16 v[104:107], v[216:219], v[172:175], v[104:107]
	v_mfma_f32_16x16x32_bf16 v[92:95], v[208:211], v[180:183], v[92:95]
	v_mfma_f32_16x16x32_bf16 v[88:91], v[216:219], v[180:183], v[88:91]
	v_mfma_f32_16x16x32_bf16 v[76:79], v[208:211], v[200:203], v[76:79]
	v_mfma_f32_16x16x32_bf16 v[72:75], v[216:219], v[200:203], v[72:75]
	v_mfma_f32_16x16x32_bf16 v[124:127], v[212:215], v[164:167], v[124:127]
	v_mfma_f32_16x16x32_bf16 v[120:123], v[220:223], v[164:167], v[120:123]
	v_mfma_f32_16x16x32_bf16 v[108:111], v[212:215], v[176:179], v[108:111]
	v_mfma_f32_16x16x32_bf16 v[104:107], v[220:223], v[176:179], v[104:107]
	v_mfma_f32_16x16x32_bf16 v[92:95], v[212:215], v[196:199], v[92:95]
	v_mfma_f32_16x16x32_bf16 v[88:91], v[220:223], v[196:199], v[88:91]
	v_mfma_f32_16x16x32_bf16 v[76:79], v[212:215], v[204:207], v[76:79]
	v_mfma_f32_16x16x32_bf16 v[72:75], v[220:223], v[204:207], v[72:75]
	s_setprio 0
	s_mov_b32 m0, s31
	v_lshl_add_u64 v[226:227], v[224:225], 0, s[46:47]
	s_barrier
	ds_read_b128 v[160:163], v146 offset:49152
	ds_read_b128 v[164:167], v146 offset:50176
	ds_read_b128 v[172:175], v146 offset:51200
	ds_read_b128 v[176:179], v146 offset:52224
	ds_read_b128 v[180:183], v146 offset:53248
	ds_read_b128 v[196:199], v146 offset:54272
	ds_read_b128 v[200:203], v146 offset:55296
	ds_read_b128 v[204:207], v146 offset:56320
	global_load_lds_dwordx4 v[226:227], off
	v_lshl_add_u64 v[224:225], v[224:225], 0, s[58:59]
	s_mov_b32 m0, s33
	s_nop 0
	global_load_lds_dwordx4 v[224:225], off
	s_barrier
	s_waitcnt lgkmcnt(0)
	s_setprio 3
	s_waitcnt lgkmcnt(0)
	v_mfma_f32_16x16x32_bf16 v[68:71], v[140:143], v[160:163], v[68:71]
	v_mfma_f32_16x16x32_bf16 v[64:67], v[152:155], v[160:163], v[64:67]
	v_mfma_f32_16x16x32_bf16 v[52:55], v[140:143], v[172:175], v[52:55]
	v_mfma_f32_16x16x32_bf16 v[48:51], v[152:155], v[172:175], v[48:51]
	v_mfma_f32_16x16x32_bf16 v[36:39], v[140:143], v[180:183], v[36:39]
	v_mfma_f32_16x16x32_bf16 v[32:35], v[152:155], v[180:183], v[32:35]
	v_mfma_f32_16x16x32_bf16 v[20:23], v[140:143], v[200:203], v[20:23]
	v_mfma_f32_16x16x32_bf16 v[16:19], v[152:155], v[200:203], v[16:19]
	v_mfma_f32_16x16x32_bf16 v[68:71], v[148:151], v[164:167], v[68:71]
	v_mfma_f32_16x16x32_bf16 v[64:67], v[156:159], v[164:167], v[64:67]
	v_mfma_f32_16x16x32_bf16 v[52:55], v[148:151], v[176:179], v[52:55]
	v_mfma_f32_16x16x32_bf16 v[48:51], v[156:159], v[176:179], v[48:51]
	v_mfma_f32_16x16x32_bf16 v[36:39], v[148:151], v[196:199], v[36:39]
	v_mfma_f32_16x16x32_bf16 v[32:35], v[156:159], v[196:199], v[32:35]
	v_mfma_f32_16x16x32_bf16 v[20:23], v[148:151], v[204:207], v[20:23]
	v_mfma_f32_16x16x32_bf16 v[16:19], v[156:159], v[204:207], v[16:19]
	s_setprio 0
	s_barrier
	s_add_i32 s4, s5, s26
	v_lshl_add_u64 v[140:141], v[184:185], 0, s[50:51]
	s_mov_b32 m0, s4
	s_nop 0
	global_load_lds_dwordx4 v[140:141], off
	v_lshl_add_u64 v[140:141], v[184:185], 0, s[62:63]
	s_add_i32 m0, s4, 0x2000
	s_nop 0
	global_load_lds_dwordx4 v[140:141], off
	s_waitcnt vmcnt(6)
	s_barrier
	s_setprio 3
	v_mfma_f32_16x16x32_bf16 v[60:63], v[208:211], v[160:163], v[60:63]
	v_mfma_f32_16x16x32_bf16 v[56:59], v[216:219], v[160:163], v[56:59]
	v_mfma_f32_16x16x32_bf16 v[44:47], v[208:211], v[172:175], v[44:47]
	v_mfma_f32_16x16x32_bf16 v[40:43], v[216:219], v[172:175], v[40:43]
	v_mfma_f32_16x16x32_bf16 v[28:31], v[208:211], v[180:183], v[28:31]
	v_mfma_f32_16x16x32_bf16 v[24:27], v[216:219], v[180:183], v[24:27]
	v_mfma_f32_16x16x32_bf16 v[12:15], v[208:211], v[200:203], v[12:15]
	v_mfma_f32_16x16x32_bf16 v[8:11], v[216:219], v[200:203], v[8:11]
	v_mfma_f32_16x16x32_bf16 v[60:63], v[212:215], v[164:167], v[60:63]
	v_mfma_f32_16x16x32_bf16 v[56:59], v[220:223], v[164:167], v[56:59]
	v_mfma_f32_16x16x32_bf16 v[44:47], v[212:215], v[176:179], v[44:47]
	v_mfma_f32_16x16x32_bf16 v[40:43], v[220:223], v[176:179], v[40:43]
	v_mfma_f32_16x16x32_bf16 v[28:31], v[212:215], v[196:199], v[28:31]
	v_mfma_f32_16x16x32_bf16 v[24:27], v[220:223], v[196:199], v[24:27]
	v_mfma_f32_16x16x32_bf16 v[12:15], v[212:215], v[204:207], v[12:15]
	v_mfma_f32_16x16x32_bf16 v[8:11], v[220:223], v[204:207], v[8:11]
	s_setprio 0
	s_add_i32 s21, s21, 2
	s_add_u32 s6, s6, 0x100
	s_addc_u32 s7, s7, 0
	s_add_u32 s19, s19, 0x100
	s_addc_u32 s20, s20, 0
	s_cmp_gt_u32 s21, 5
	s_cbranch_scc0 .Ldb_SSM1_cont
	v_readfirstlane_b32 s101, v186
	s_cmpk_gt_u32 s101, 0xff
	s_cbranch_scc1 .Ldb_SSM1_exit
	s_barrier
	s_branch .Ldb_SSM1_exit

; __device__ __forceinline__ u32x4 pack8(const f32x4 a, const f32x4 b) { u32x4 w; w.x = cvt_pk_bf16(a[0], a[1]); w.y = cvt_pk_bf16(a[2], a[3]); w.z = cvt_pk_bf16(b[0], b[1]); w.w = cvt_pk_bf16(b[2], b[3]); return w; }
;     template <int KIND> __device__ __forceinline__ void run(f32x4 (&acc)[2][2][4][2], const Unit& u, int tid_in) const {
;     ...
;         if constexpr (KIND == K_SSM1) { const int g = u.aux;
; #pragma unroll
;             for (int ai = 0; ai < 2; ++ai)
; #pragma unroll
;                 for (int m = 0; m < 4; ++m) { int R = rbase + ai * 128 + m * 16; asm volatile("" : "+v"(R));
;                     if (u.pn < 2) {
; #pragma unroll
;                         for (int bj = 0; bj < 2; ++bj) { const int t = 16 * u.pn + 8 * bj + 2 * wc + (fq >> 1), p0 = 8 * (fq & 1);
;                             *(u32x4*)(yi + ((size_t)g * T_TOK + (size_t)(R * LCH + t)) * 16 + p0) = pack8(acc[ai][bj][m][0], acc[ai][bj][m][1]); }
;                     } else { float* sp = (float*)(ws + OFF_S) + ((size_t)(R * 32 + g)) * 128 + cl; *(f32x4*)sp = acc[ai][0][m][0]; *(f32x4*)(sp + 4) = acc[ai][0][m][1]; } }
.Ldb_SSM1_exit:
	v_mov_b32_e32 v0, v144
	s_mov_b64 s[22:23], -1
	v_readfirstlane_b32 s4, v0
	s_bfe_u32 s19, s4, 0x20006
	s_ashr_i32 s4, s4, 2
	s_andn2_b32 s4, s4, 63
	v_and_or_b32 v141, v0, 15, s4
	v_lshl_add_u32 v147, s13, 8, v141
	s_ashr_i32 s13, s12, 31
	s_lshl_b64 s[6:7], s[12:13], 20
	s_add_u32 s6, s36, s6
	v_bfe_u32 v140, v0, 4, 2
	s_addc_u32 s7, s37, s7
	v_lshlrev_b32_e32 v140, 3, v140
	s_cmp_gt_i32 s25, 1
	v_lshl_or_b32 v140, s19, 5, v140
	v_mov_b32_e32 v141, v147
	s_cselect_b64 s[20:21], -1, 0
	s_and_b64 vcc, exec, s[20:21]
	v_lshlrev_b32_e32 v149, 5, v141
	v_lshlrev_b32_e32 v142, 2, v140
	s_cbranch_vccz .LBB0_453
	v_add_u32_e32 v140, s12, v149
	v_ashrrev_i32_e32 v141, 31, v140
	v_lshlrev_b64 v[140:141], 9, v[140:141]
	v_lshl_add_u64 v[140:141], s[2:3], 0, v[140:141]
	v_mov_b32_e32 v143, v1
	v_lshl_add_u64 v[140:141], v[140:141], 0, v[142:143]
	global_store_dwordx4 v[140:141], v[132:135], off
	global_store_dwordx4 v[140:141], v[128:131], off offset:16
	s_mov_b64 s[22:23], 0

;     ...
;         E.template run<cs.kind>(acc, cur, tid);
;         if (!has_next) break;
;         if (!(cs.kind == K_MG_B && cur.aux < 2))
; #pragma unroll
;         for (int a = 0; a < 2; ++a)
; #pragma unroll
;             for (int b = 0; b < 2; ++b)
; #pragma unroll
;                 for (int m = 0; m < 4; ++m)
; #pragma unroll
;                     for (int n = 0; n < 2; ++n) acc[a][b][m][n] = (f32x4){0.f, 0.f, 0.f, 0.f};
;         cur = nxt; cA = nA; cB = nB; ++ui;
.LBB0_1031:
	s_or_b64 exec, exec, s[2:3]
	s_cmpk_gt_u32 s101, 0xff
	s_cbranch_scc0 .Ldb_WOUT_nob
	s_barrier
.Ldb_WOUT_nob:
	s_and_b64 vcc, exec, s[12:13]
	s_mov_b32 s8, s40
	s_mov_b32 s9, s14
	s_mov_b64 s[6:7], s[18:19]
	s_mov_b64 s[2:3], s[16:17]
	s_cbranch_vccnz .LBB0_1054

; #define G_STAGE(bufoff, gbase, o0, h64) do { \
;         __builtin_amdgcn_global_load_lds((const unsigned*)((const char*)(gbase) + (o0)), (LAS unsigned*)(lds + (bufoff) + ldsw), 16, 0, 0); \
;         __builtin_amdgcn_global_load_lds((const unsigned*)((const char*)(gbase) + (h64) + (o0)), (LAS unsigned*)(lds + (bufoff) + ldsw + 8192), 16, 0, 0); } while (0)
; #define G_LDA(dst, b, h) do { _Pragma("unroll") for (int m = 0; m < 4; ++m) _Pragma("unroll") for (int k = 0; k < 2; ++k) dst[m][k] = *(const LAS bf16x8*)(lds + G_SA(b, h) + aoff + m * 2048 + k * 1024); } while (0)
; #define G_LDB(dst, b, h) do { _Pragma("unroll") for (int n = 0; n < 2; ++n) _Pragma("unroll") for (int k = 0; k < 2; ++k) dst[n][k] = *(const LAS bf16x8*)(lds + G_SB(b, h) + boff + n * 2048 + k * 1024); } while (0)
; #define G_WAIT_L(n) asm volatile("s_waitcnt lgkmcnt(" #n ")" ::: "memory")
; #define G_BAR __builtin_amdgcn_s_barrier()
; #define G_SCHED __builtin_amdgcn_sched_barrier(0)
;     ...
;         for (int t = 0; t < nt; t += 2) {
;             const bool last = (t == nt - 2);
;             const char* a1 = cA + (size_t)(t + 1) * ckA;
;             const char* a2 = last ? nA : cA + (size_t)(t + 2) * ckA; const char* b2 = last ? nB : cB + (size_t)(t + 2) * kB;
;             const char* a3 = a2 + ckA; const char* b3 = b2 + kB;
;             G_LDB(B0, 0, 0); G_SCHED; G_LDA(At, 0, 0); G_STAGE(G_SA(1, 1), a1 + chA, cA0, qA);
;             G_WAIT_L(8); G_BAR; G_WAIT_L(0); G_MMA(0, 0, At, B0); G_BAR; G_SCHED;
;             G_LDB(B1, 0, 1); G_STAGE(G_SB(0, 0), b2, cB0, qB);
;             G_BAR; G_WAIT_L(0); G_MMA(0, 1, At, B1); G_BAR;
;             G_LDA(At, 0, 1); G_STAGE(G_SA(0, 0), a2, cA0, qA);
;             G_BAR; G_WAIT_L(0); G_MMA(1, 0, At, B0); G_BAR; G_SCHED;
.LBB0_1037:
	s_add_u32 s4, s2, 0xfffc0080
	s_addc_u32 s5, s3, -1
	s_add_i32 s33, 0, 0x10000
	v_add_u32_e32 v0, s33, v181
	ds_read_b128 v[136:139], v0
	ds_read_b128 v[140:143], v0 offset:1024
	ds_read_b128 v[144:147], v0 offset:2048
	ds_read_b128 v[148:151], v0 offset:3072
	s_cmp_eq_u32 s15, 12
	s_cselect_b32 s5, s17, s5
	s_cselect_b32 s4, s16, s4
	s_cselect_b32 s21, s19, s7
	s_cselect_b32 s20, s18, s6
	v_lshl_add_u64 v[184:185], s[2:3], 0, v[166:167]
	s_add_i32 m0, s24, 0xc000
	ds_read_b128 v[152:155], v182
	ds_read_b128 v[156:159], v182 offset:1024
	ds_read_b128 v[160:163], v182 offset:2048
	ds_read_b128 v[172:175], v182 offset:3072
	ds_read_b128 v[176:179], v182 offset:4096
	ds_read_b128 v[196:199], v182 offset:5120
	ds_read_b128 v[200:203], v182 offset:6144
	ds_read_b128 v[204:207], v182 offset:7168
	global_load_lds_dwordx4 v[184:185], off
	v_lshl_add_u64 v[184:185], v[184:185], 0, s[0:1]
	s_add_i32 m0, s24, 0xe000
	s_nop 0
	global_load_lds_dwordx4 v[184:185], off
	s_waitcnt lgkmcnt(8)
	s_barrier
	s_waitcnt lgkmcnt(0)
	s_setprio 3
	s_waitcnt lgkmcnt(0)
	v_mfma_f32_16x16x32_bf16 v[132:135], v[136:139], v[152:155], v[132:135]
	v_mfma_f32_16x16x32_bf16 v[128:131], v[144:147], v[152:155], v[128:131]
	v_mfma_f32_16x16x32_bf16 v[116:119], v[136:139], v[160:163], v[116:119]
	v_mfma_f32_16x16x32_bf16 v[112:115], v[144:147], v[160:163], v[112:115]
	v_mfma_f32_16x16x32_bf16 v[100:103], v[136:139], v[176:179], v[100:103]
	v_mfma_f32_16x16x32_bf16 v[96:99], v[144:147], v[176:179], v[96:99]
	v_mfma_f32_16x16x32_bf16 v[84:87], v[136:139], v[200:203], v[84:87]
	v_mfma_f32_16x16x32_bf16 v[80:83], v[144:147], v[200:203], v[80:83]
	v_mfma_f32_16x16x32_bf16 v[132:135], v[140:143], v[156:159], v[132:135]
	v_mfma_f32_16x16x32_bf16 v[128:131], v[148:151], v[156:159], v[128:131]
	v_mfma_f32_16x16x32_bf16 v[116:119], v[140:143], v[172:175], v[116:119]
	v_mfma_f32_16x16x32_bf16 v[112:115], v[148:151], v[172:175], v[112:115]
	v_mfma_f32_16x16x32_bf16 v[100:103], v[140:143], v[196:199], v[100:103]
	v_mfma_f32_16x16x32_bf16 v[96:99], v[148:151], v[196:199], v[96:99]
	v_mfma_f32_16x16x32_bf16 v[84:87], v[140:143], v[204:207], v[84:87]
	v_mfma_f32_16x16x32_bf16 v[80:83], v[148:151], v[204:207], v[80:83]
	s_setprio 0
	s_barrier
	s_add_i32 s41, 0, 0x14000
	v_lshl_add_u64 v[184:185], s[20:21], 0, v[164:165]
	s_add_i32 s20, s33, s23
	v_add_u32_e32 v0, s41, v181
	s_mov_b32 m0, s20
	ds_read_b128 v[208:211], v0
	ds_read_b128 v[212:215], v0 offset:1024
	ds_read_b128 v[216:219], v0 offset:2048
	ds_read_b128 v[220:223], v0 offset:3072
	global_load_lds_dwordx4 v[184:185], off
	v_lshl_add_u64 v[224:225], v[184:185], 0, s[0:1]
	s_add_i32 m0, s20, 0x2000
	s_nop 0
	global_load_lds_dwordx4 v[224:225], off
	s_barrier
	s_waitcnt lgkmcnt(0)
	s_setprio 3
	s_waitcnt lgkmcnt(0)
	v_mfma_f32_16x16x32_bf16 v[124:127], v[208:211], v[152:155], v[124:127]
	v_mfma_f32_16x16x32_bf16 v[120:123], v[216:219], v[152:155], v[120:123]
	v_mfma_f32_16x16x32_bf16 v[108:111], v[208:211], v[160:163], v[108:111]
	v_mfma_f32_16x16x32_bf16 v[104:107], v[216:219], v[160:163], v[104:107]
	v_mfma_f32_16x16x32_bf16 v[92:95], v[208:211], v[176:179], v[92:95]
	v_mfma_f32_16x16x32_bf16 v[88:91], v[216:219], v[176:179], v[88:91]
	v_mfma_f32_16x16x32_bf16 v[76:79], v[208:211], v[200:203], v[76:79]
	v_mfma_f32_16x16x32_bf16 v[72:75], v[216:219], v[200:203], v[72:75]
	v_mfma_f32_16x16x32_bf16 v[124:127], v[212:215], v[156:159], v[124:127]
	v_mfma_f32_16x16x32_bf16 v[120:123], v[220:223], v[156:159], v[120:123]
	v_mfma_f32_16x16x32_bf16 v[108:111], v[212:215], v[172:175], v[108:111]
	v_mfma_f32_16x16x32_bf16 v[104:107], v[220:223], v[172:175], v[104:107]
	v_mfma_f32_16x16x32_bf16 v[92:95], v[212:215], v[196:199], v[92:95]
	v_mfma_f32_16x16x32_bf16 v[88:91], v[220:223], v[196:199], v[88:91]
	v_mfma_f32_16x16x32_bf16 v[76:79], v[212:215], v[204:207], v[76:79]
	v_mfma_f32_16x16x32_bf16 v[72:75], v[220:223], v[204:207], v[72:75]
	s_setprio 0
	s_mov_b32 m0, s24
	v_lshl_add_u64 v[224:225], s[4:5], 0, v[2:3]
	s_barrier
	ds_read_b128 v[152:155], v182 offset:16384
	ds_read_b128 v[156:159], v182 offset:17408
	ds_read_b128 v[160:163], v182 offset:18432
	ds_read_b128 v[172:175], v182 offset:19456
	ds_read_b128 v[176:179], v182 offset:20480
	ds_read_b128 v[196:199], v182 offset:21504
	ds_read_b128 v[200:203], v182 offset:22528
	ds_read_b128 v[204:207], v182 offset:23552
	global_load_lds_dwordx4 v[224:225], off
	v_lshl_add_u64 v[226:227], v[224:225], 0, s[0:1]
	s_mov_b32 m0, s25
	s_nop 0
	global_load_lds_dwordx4 v[226:227], off
	s_barrier
	s_waitcnt lgkmcnt(0)
	s_setprio 3
	s_waitcnt lgkmcnt(0)
	v_mfma_f32_16x16x32_bf16 v[68:71], v[136:139], v[152:155], v[68:71]
	v_mfma_f32_16x16x32_bf16 v[64:67], v[144:147], v[152:155], v[64:67]
	v_mfma_f32_16x16x32_bf16 v[52:55], v[136:139], v[160:163], v[52:55]
	v_mfma_f32_16x16x32_bf16 v[48:51], v[144:147], v[160:163], v[48:51]
	v_mfma_f32_16x16x32_bf16 v[36:39], v[136:139], v[176:179], v[36:39]
	v_mfma_f32_16x16x32_bf16 v[32:35], v[144:147], v[176:179], v[32:35]
	v_mfma_f32_16x16x32_bf16 v[20:23], v[136:139], v[200:203], v[20:23]
	v_mfma_f32_16x16x32_bf16 v[16:19], v[144:147], v[200:203], v[16:19]
	v_mfma_f32_16x16x32_bf16 v[68:71], v[140:143], v[156:159], v[68:71]
	v_mfma_f32_16x16x32_bf16 v[64:67], v[148:151], v[156:159], v[64:67]
	v_mfma_f32_16x16x32_bf16 v[52:55], v[140:143], v[172:175], v[52:55]
	v_mfma_f32_16x16x32_bf16 v[48:51], v[148:151], v[172:175], v[48:51]
	v_mfma_f32_16x16x32_bf16 v[36:39], v[140:143], v[196:199], v[36:39]
	v_mfma_f32_16x16x32_bf16 v[32:35], v[148:151], v[196:199], v[32:35]
	v_mfma_f32_16x16x32_bf16 v[20:23], v[140:143], v[204:207], v[20:23]
	v_mfma_f32_16x16x32_bf16 v[16:19], v[148:151], v[204:207], v[16:19]
	s_setprio 0
	s_barrier
; #define G_STAGE(bufoff, gbase, o0, h64) do { \
;         __builtin_amdgcn_global_load_lds((const unsigned*)((const char*)(gbase) + (o0)), (LAS unsigned*)(lds + (bufoff) + ldsw), 16, 0, 0); \
;         __builtin_amdgcn_global_load_lds((const unsigned*)((const char*)(gbase) + (h64) + (o0)), (LAS unsigned*)(lds + (bufoff) + ldsw + 8192), 16, 0, 0); } while (0)
; #define G_LDA(dst, b, h) do { _Pragma("unroll") for (int m = 0; m < 4; ++m) _Pragma("unroll") for (int k = 0; k < 2; ++k) dst[m][k] = *(const LAS bf16x8*)(lds + G_SA(b, h) + aoff + m * 2048 + k * 1024); } while (0)
; #define G_LDB(dst, b, h) do { _Pragma("unroll") for (int n = 0; n < 2; ++n) _Pragma("unroll") for (int k = 0; k < 2; ++k) dst[n][k] = *(const LAS bf16x8*)(lds + G_SB(b, h) + boff + n * 2048 + k * 1024); } while (0)
; #define G_WAIT_V(n) asm volatile("s_waitcnt vmcnt(" #n ")" ::: "memory")
; #define G_WAIT_L(n) asm volatile("s_waitcnt lgkmcnt(" #n ")" ::: "memory")
; #define G_BAR __builtin_amdgcn_s_barrier()
; #define G_SCHED __builtin_amdgcn_sched_barrier(0)
;     ...
;             G_STAGE(G_SB(0, 1), b2 + chB, cB0, qB);
;             G_WAIT_V(6); G_BAR; G_MMA(1, 1, At, B1); G_BAR;
;             G_LDB(B0, 1, 0); G_SCHED; G_LDA(At, 1, 0); G_STAGE(G_SA(0, 1), a2 + chA, cA0, qA);
;             G_WAIT_L(8); G_BAR; G_WAIT_L(0); G_MMA(0, 0, At, B0); G_BAR; G_SCHED;
;             G_LDB(B1, 1, 1); G_STAGE(G_SB(1, 0), b3, cB0, qB);
;             G_BAR; G_WAIT_L(0); G_MMA(0, 1, At, B1); G_BAR;
;             G_LDA(At, 1, 1); G_STAGE(G_SA(1, 0), a3, cA0, qA);
;             G_BAR; G_WAIT_L(0); G_MMA(1, 0, At, B0); G_BAR; G_SCHED;
;             G_STAGE(G_SB(1, 1), b3 + chB, cB0, qB);
	s_add_i32 s4, s41, s23
	v_lshl_add_u64 v[136:137], v[184:185], 0, s[42:43]
	s_mov_b32 m0, s4
	s_nop 0
	global_load_lds_dwordx4 v[136:137], off
	v_lshl_add_u64 v[136:137], v[184:185], 0, s[50:51]
	s_add_i32 m0, s4, 0x2000
	s_nop 0
	global_load_lds_dwordx4 v[136:137], off
	s_waitcnt vmcnt(6)
	s_barrier
	s_setprio 3
	v_mfma_f32_16x16x32_bf16 v[60:63], v[208:211], v[152:155], v[60:63]
	v_mfma_f32_16x16x32_bf16 v[56:59], v[216:219], v[152:155], v[56:59]
	v_mfma_f32_16x16x32_bf16 v[44:47], v[208:211], v[160:163], v[44:47]
	v_mfma_f32_16x16x32_bf16 v[40:43], v[216:219], v[160:163], v[40:43]
	v_mfma_f32_16x16x32_bf16 v[28:31], v[208:211], v[176:179], v[28:31]
	v_mfma_f32_16x16x32_bf16 v[24:27], v[216:219], v[176:179], v[24:27]
	v_mfma_f32_16x16x32_bf16 v[12:15], v[208:211], v[200:203], v[12:15]
	v_mfma_f32_16x16x32_bf16 v[8:11], v[216:219], v[200:203], v[8:11]
	v_mfma_f32_16x16x32_bf16 v[60:63], v[212:215], v[156:159], v[60:63]
	v_mfma_f32_16x16x32_bf16 v[56:59], v[220:223], v[156:159], v[56:59]
	v_mfma_f32_16x16x32_bf16 v[44:47], v[212:215], v[172:175], v[44:47]
	v_mfma_f32_16x16x32_bf16 v[40:43], v[220:223], v[172:175], v[40:43]
	v_mfma_f32_16x16x32_bf16 v[28:31], v[212:215], v[196:199], v[28:31]
	v_mfma_f32_16x16x32_bf16 v[24:27], v[220:223], v[196:199], v[24:27]
	v_mfma_f32_16x16x32_bf16 v[12:15], v[212:215], v[204:207], v[12:15]
	v_mfma_f32_16x16x32_bf16 v[8:11], v[220:223], v[204:207], v[8:11]
	s_setprio 0
	s_add_i32 s4, 0, 0x18000
	v_add_u32_e32 v0, s4, v181
	s_barrier
	ds_read_b128 v[136:139], v0
	ds_read_b128 v[140:143], v0 offset:1024
	ds_read_b128 v[144:147], v0 offset:2048
	ds_read_b128 v[148:151], v0 offset:3072
	s_mov_b32 m0, s26
	v_lshl_add_u64 v[208:209], v[224:225], 0, s[42:43]
	ds_read_b128 v[152:155], v182 offset:32768
	ds_read_b128 v[156:159], v182 offset:33792
	ds_read_b128 v[160:163], v182 offset:34816
	ds_read_b128 v[172:175], v182 offset:35840
	ds_read_b128 v[176:179], v182 offset:36864
	ds_read_b128 v[196:199], v182 offset:37888
	ds_read_b128 v[200:203], v182 offset:38912
	ds_read_b128 v[204:207], v182 offset:39936
	global_load_lds_dwordx4 v[208:209], off
	v_lshl_add_u64 v[208:209], v[224:225], 0, s[50:51]
	s_mov_b32 m0, s27
	s_nop 0
	global_load_lds_dwordx4 v[208:209], off
	s_waitcnt lgkmcnt(8)
	s_barrier
	s_waitcnt lgkmcnt(0)
	s_setprio 3
	s_waitcnt lgkmcnt(0)
	v_mfma_f32_16x16x32_bf16 v[132:135], v[136:139], v[152:155], v[132:135]
	v_mfma_f32_16x16x32_bf16 v[128:131], v[144:147], v[152:155], v[128:131]
	v_mfma_f32_16x16x32_bf16 v[116:119], v[136:139], v[160:163], v[116:119]
	v_mfma_f32_16x16x32_bf16 v[112:115], v[144:147], v[160:163], v[112:115]
	v_mfma_f32_16x16x32_bf16 v[100:103], v[136:139], v[176:179], v[100:103]
	v_mfma_f32_16x16x32_bf16 v[96:99], v[144:147], v[176:179], v[96:99]
	v_mfma_f32_16x16x32_bf16 v[84:87], v[136:139], v[200:203], v[84:87]
	v_mfma_f32_16x16x32_bf16 v[80:83], v[144:147], v[200:203], v[80:83]
	v_mfma_f32_16x16x32_bf16 v[132:135], v[140:143], v[156:159], v[132:135]
	v_mfma_f32_16x16x32_bf16 v[128:131], v[148:151], v[156:159], v[128:131]
	v_mfma_f32_16x16x32_bf16 v[116:119], v[140:143], v[172:175], v[116:119]
	v_mfma_f32_16x16x32_bf16 v[112:115], v[148:151], v[172:175], v[112:115]
	v_mfma_f32_16x16x32_bf16 v[100:103], v[140:143], v[196:199], v[100:103]
	v_mfma_f32_16x16x32_bf16 v[96:99], v[148:151], v[196:199], v[96:99]
	v_mfma_f32_16x16x32_bf16 v[84:87], v[140:143], v[204:207], v[84:87]
	v_mfma_f32_16x16x32_bf16 v[80:83], v[148:151], v[204:207], v[80:83]
	s_setprio 0
	s_barrier
	s_add_i32 s5, 0, 0x1c000
	s_add_i32 s4, s4, s23
	v_add_u32_e32 v0, s5, v181
	v_lshl_add_u64 v[226:227], v[184:185], 0, s[46:47]
	s_mov_b32 m0, s4
	ds_read_b128 v[208:211], v0
	ds_read_b128 v[212:215], v0 offset:1024
	ds_read_b128 v[216:219], v0 offset:2048
	ds_read_b128 v[220:223], v0 offset:3072
	global_load_lds_dwordx4 v[226:227], off
	v_lshl_add_u64 v[226:227], v[184:185], 0, s[52:53]
	s_add_i32 m0, s4, 0x2000
	s_nop 0
	global_load_lds_dwordx4 v[226:227], off
	s_barrier
; #define G_STAGE(bufoff, gbase, o0, h64) do { \
;         __builtin_amdgcn_global_load_lds((const unsigned*)((const char*)(gbase) + (o0)), (LAS unsigned*)(lds + (bufoff) + ldsw), 16, 0, 0); \
;         __builtin_amdgcn_global_load_lds((const unsigned*)((const char*)(gbase) + (h64) + (o0)), (LAS unsigned*)(lds + (bufoff) + ldsw + 8192), 16, 0, 0); } while (0)
; #define G_LDA(dst, b, h) do { _Pragma("unroll") for (int m = 0; m < 4; ++m) _Pragma("unroll") for (int k = 0; k < 2; ++k) dst[m][k] = *(const LAS bf16x8*)(lds + G_SA(b, h) + aoff + m * 2048 + k * 1024); } while (0)
; #define G_WAIT_V(n) asm volatile("s_waitcnt vmcnt(" #n ")" ::: "memory")
; #define G_WAIT_L(n) asm volatile("s_waitcnt lgkmcnt(" #n ")" ::: "memory")
; #define G_BAR __builtin_amdgcn_s_barrier()
; #define G_SCHED __builtin_amdgcn_sched_barrier(0)
;     ...
;             G_LDA(At, 1, 1); G_STAGE(G_SA(1, 0), a3, cA0, qA);
;             G_BAR; G_WAIT_L(0); G_MMA(1, 0, At, B0); G_BAR; G_SCHED;
;             G_STAGE(G_SB(1, 1), b3 + chB, cB0, qB);
;             G_WAIT_V(6); G_BAR; G_MMA(1, 1, At, B1); G_BAR;
;         }
;         E.template run<cs.kind>(acc, cur, tid);
;         if (!has_next) break;
	s_waitcnt lgkmcnt(0)
	s_setprio 3
	s_waitcnt lgkmcnt(0)
	v_mfma_f32_16x16x32_bf16 v[124:127], v[208:211], v[152:155], v[124:127]
	v_mfma_f32_16x16x32_bf16 v[120:123], v[216:219], v[152:155], v[120:123]
	v_mfma_f32_16x16x32_bf16 v[108:111], v[208:211], v[160:163], v[108:111]
	v_mfma_f32_16x16x32_bf16 v[104:107], v[216:219], v[160:163], v[104:107]
	v_mfma_f32_16x16x32_bf16 v[92:95], v[208:211], v[176:179], v[92:95]
	v_mfma_f32_16x16x32_bf16 v[88:91], v[216:219], v[176:179], v[88:91]
	v_mfma_f32_16x16x32_bf16 v[76:79], v[208:211], v[200:203], v[76:79]
	v_mfma_f32_16x16x32_bf16 v[72:75], v[216:219], v[200:203], v[72:75]
	v_mfma_f32_16x16x32_bf16 v[124:127], v[212:215], v[156:159], v[124:127]
	v_mfma_f32_16x16x32_bf16 v[120:123], v[220:223], v[156:159], v[120:123]
	v_mfma_f32_16x16x32_bf16 v[108:111], v[212:215], v[172:175], v[108:111]
	v_mfma_f32_16x16x32_bf16 v[104:107], v[220:223], v[172:175], v[104:107]
	v_mfma_f32_16x16x32_bf16 v[92:95], v[212:215], v[196:199], v[92:95]
	v_mfma_f32_16x16x32_bf16 v[88:91], v[220:223], v[196:199], v[88:91]
	v_mfma_f32_16x16x32_bf16 v[76:79], v[212:215], v[204:207], v[76:79]
	v_mfma_f32_16x16x32_bf16 v[72:75], v[220:223], v[204:207], v[72:75]
	s_setprio 0
	s_mov_b32 m0, s29
	v_lshl_add_u64 v[226:227], v[224:225], 0, s[46:47]
	s_barrier
	ds_read_b128 v[152:155], v182 offset:49152
	ds_read_b128 v[156:159], v182 offset:50176
	ds_read_b128 v[160:163], v182 offset:51200
	ds_read_b128 v[172:175], v182 offset:52224
	ds_read_b128 v[176:179], v182 offset:53248
	ds_read_b128 v[196:199], v182 offset:54272
	ds_read_b128 v[200:203], v182 offset:55296
	ds_read_b128 v[204:207], v182 offset:56320
	global_load_lds_dwordx4 v[226:227], off
	v_lshl_add_u64 v[224:225], v[224:225], 0, s[52:53]
	s_mov_b32 m0, s30
	s_nop 0
	global_load_lds_dwordx4 v[224:225], off
	s_barrier
	s_waitcnt lgkmcnt(0)
	s_setprio 3
	s_waitcnt lgkmcnt(0)
	v_mfma_f32_16x16x32_bf16 v[68:71], v[136:139], v[152:155], v[68:71]
	v_mfma_f32_16x16x32_bf16 v[64:67], v[144:147], v[152:155], v[64:67]
	v_mfma_f32_16x16x32_bf16 v[52:55], v[136:139], v[160:163], v[52:55]
	v_mfma_f32_16x16x32_bf16 v[48:51], v[144:147], v[160:163], v[48:51]
	v_mfma_f32_16x16x32_bf16 v[36:39], v[136:139], v[176:179], v[36:39]
	v_mfma_f32_16x16x32_bf16 v[32:35], v[144:147], v[176:179], v[32:35]
	v_mfma_f32_16x16x32_bf16 v[20:23], v[136:139], v[200:203], v[20:23]
	v_mfma_f32_16x16x32_bf16 v[16:19], v[144:147], v[200:203], v[16:19]
	v_mfma_f32_16x16x32_bf16 v[68:71], v[140:143], v[156:159], v[68:71]
	v_mfma_f32_16x16x32_bf16 v[64:67], v[148:151], v[156:159], v[64:67]
	v_mfma_f32_16x16x32_bf16 v[52:55], v[140:143], v[172:175], v[52:55]
	v_mfma_f32_16x16x32_bf16 v[48:51], v[148:151], v[172:175], v[48:51]
	v_mfma_f32_16x16x32_bf16 v[36:39], v[140:143], v[196:199], v[36:39]
	v_mfma_f32_16x16x32_bf16 v[32:35], v[148:151], v[196:199], v[32:35]
	v_mfma_f32_16x16x32_bf16 v[20:23], v[140:143], v[204:207], v[20:23]
	v_mfma_f32_16x16x32_bf16 v[16:19], v[148:151], v[204:207], v[16:19]
	s_setprio 0
	s_barrier
	s_add_i32 s4, s5, s23
	v_lshl_add_u64 v[136:137], v[184:185], 0, s[54:55]
	s_mov_b32 m0, s4
	s_nop 0
	global_load_lds_dwordx4 v[136:137], off
	v_lshl_add_u64 v[136:137], v[184:185], 0, s[58:59]
	s_add_i32 m0, s4, 0x2000
	s_nop 0
	global_load_lds_dwordx4 v[136:137], off
	s_waitcnt vmcnt(6)
	s_barrier
	s_setprio 3
	v_mfma_f32_16x16x32_bf16 v[60:63], v[208:211], v[152:155], v[60:63]
	v_mfma_f32_16x16x32_bf16 v[56:59], v[216:219], v[152:155], v[56:59]
	v_mfma_f32_16x16x32_bf16 v[44:47], v[208:211], v[160:163], v[44:47]
	v_mfma_f32_16x16x32_bf16 v[40:43], v[216:219], v[160:163], v[40:43]
	v_mfma_f32_16x16x32_bf16 v[28:31], v[208:211], v[176:179], v[28:31]
	v_mfma_f32_16x16x32_bf16 v[24:27], v[216:219], v[176:179], v[24:27]
	v_mfma_f32_16x16x32_bf16 v[12:15], v[208:211], v[200:203], v[12:15]
	v_mfma_f32_16x16x32_bf16 v[8:11], v[216:219], v[200:203], v[8:11]
	v_mfma_f32_16x16x32_bf16 v[60:63], v[212:215], v[156:159], v[60:63]
	v_mfma_f32_16x16x32_bf16 v[56:59], v[220:223], v[156:159], v[56:59]
	v_mfma_f32_16x16x32_bf16 v[44:47], v[212:215], v[172:175], v[44:47]
	v_mfma_f32_16x16x32_bf16 v[40:43], v[220:223], v[172:175], v[40:43]
	v_mfma_f32_16x16x32_bf16 v[28:31], v[212:215], v[196:199], v[28:31]
	v_mfma_f32_16x16x32_bf16 v[24:27], v[220:223], v[196:199], v[24:27]
	v_mfma_f32_16x16x32_bf16 v[12:15], v[212:215], v[204:207], v[12:15]
	v_mfma_f32_16x16x32_bf16 v[8:11], v[220:223], v[204:207], v[8:11]
	s_setprio 0
	s_add_i32 s15, s15, 2
	s_add_u32 s2, s2, 0x100
	s_addc_u32 s3, s3, 0
	s_add_u32 s6, s6, 0x100
	s_addc_u32 s7, s7, 0
	s_cmp_gt_u32 s15, 13
	s_cbranch_scc0 .Ldb_WOUT_cont
	v_readfirstlane_b32 s101, v186
	s_cmpk_gt_u32 s101, 0xff
	s_cbranch_scc1 .Ldb_WOUT_exit
	s_barrier
	s_branch .Ldb_WOUT_exit

; __device__ __forceinline__ u32x4 pack8(const f32x4 a, const f32x4 b) { u32x4 w; w.x = cvt_pk_bf16(a[0], a[1]); w.y = cvt_pk_bf16(a[2], a[3]); w.z = cvt_pk_bf16(b[0], b[1]); w.w = cvt_pk_bf16(b[2], b[3]); return w; }
; __device__ __forceinline__ void unpack8(const u32x4 w, f32x4& a, f32x4& b) { a[0] = bf_lo(w.x); a[1] = bf_hi(w.x); a[2] = bf_lo(w.y); a[3] = bf_hi(w.y); b[0] = bf_lo(w.z); b[1] = bf_hi(w.z); b[2] = bf_lo(w.w); b[3] = bf_hi(w.w); }
; #define MEMFENCE asm volatile("" ::: "memory")
; #define XLOAD(gi, bufi) do { _Pragma("unroll") for (int ml = 0; ml < 2; ++ml) { const int m_ = ((gi) & 1) * 2 + ml; int row_ = rbase + ((gi) >> 1) * 128 + m_ * 16; asm volatile("" : "+v"(row_)); \
;                 _Pragma("unroll") for (int bj = 0; bj < 2; ++bj) xv[bufi][ml][bj] = *(const u32x4*)(xsrc + (size_t)row_ * 1024 + u.pn * 256 + bj * 128 + cl); } } while (0)
;     template <int KIND> __device__ __forceinline__ void run(f32x4 (&acc)[2][2][4][2], const Unit& u, int tid_in) const {
;     ...
;         if constexpr (KIND == K_XADD) {
;             const bf16_t* xsrc = xb0; bf16_t* xbo = (u.aux ? mg : xb0); float* sso = (u.aux ? ssq2 : ssq1);
;             u32x4 xv[2][2][2];
;     ...
;             XLOAD(0, 0);
; #pragma unroll
;             for (int gi = 0; gi < 4; ++gi) { const int ai = gi >> 1, mh = gi & 1, bufi = gi & 1;
;                 if (gi < 3) XLOAD(gi + 1, (gi + 1) & 1);
; #pragma unroll
;                 for (int ml = 0; ml < 2; ++ml) { const int m = mh * 2 + ml; int row = rbase + ai * 128 + m * 16; asm volatile("" : "+v"(row)); float ss = 0.f;
; #pragma unroll
;                     for (int bj = 0; bj < 2; ++bj) { const size_t off = (size_t)row * 1024 + u.pn * 256 + bj * 128 + cl; f32x4 x0, x1; unpack8(xv[bufi][ml][bj], x0, x1);
;                         const f32x4 o0 = x0 + acc[ai][bj][m][0], o1 = x1 + acc[ai][bj][m][1];
;                         *(u32x4*)(xbo + off) = pack8(o0, o1);
;                         ss += (o0[0] * o0[0] + o0[1] * o0[1]) + (o0[2] * o0[2] + o0[3] * o0[3]) + (o1[0] * o1[0] + o1[1] * o1[1]) + (o1[2] * o1[2] + o1[3] * o1[3]); }
;                     ss += __shfl_xor(ss, 16); ss += __shfl_xor(ss, 32);
;                     if (fq == 0) sso[((size_t)u.pn * T_TOK + row) * 4 + wc] = ss; }
;                 MEMFENCE; }
.Ldb_WOUT_exit:
	v_mov_b32_e32 v0, v180
	s_lshl_b32 s3, s9, 8
	v_readfirstlane_b32 s2, v0
	s_bfe_u32 s15, s2, 0x20006
	s_ashr_i32 s2, s2, 2
	s_andn2_b32 s2, s2, 63
	s_add_i32 s2, s2, s3
	v_and_or_b32 v183, v0, 15, s2
	v_mov_b32_e32 v136, v183
	v_bfe_u32 v138, v0, 4, 2
	s_lshl_b32 s2, s8, 8
	v_ashrrev_i32_e32 v137, 31, v136
	v_lshlrev_b32_e32 v0, 3, v138
	v_lshlrev_b64 v[136:137], 11, v[136:137]
	s_ashr_i32 s3, s2, 31
	v_lshl_or_b32 v0, s15, 5, v0
	v_lshl_add_u64 v[136:137], s[10:11], 0, v[136:137]
	s_lshl_b64 s[20:21], s[2:3], 1
	v_lshl_add_u64 v[136:137], v[136:137], 0, s[20:21]
	v_lshlrev_b32_e32 v0, 1, v0
	v_lshl_add_u64 v[136:137], v[136:137], 0, v[0:1]
	global_load_dwordx4 v[196:199], v[136:137], off
	global_load_dwordx4 v[160:163], v[136:137], off offset:256
	v_or_b32_e32 v176, 16, v183
	v_mov_b32_e32 v136, v176
	v_or_b32_e32 v174, 32, v183
	v_ashrrev_i32_e32 v137, 31, v136
	v_lshlrev_b64 v[136:137], 11, v[136:137]
	v_lshl_add_u64 v[136:137], s[10:11], 0, v[136:137]
	v_lshl_add_u64 v[136:137], v[136:137], 0, s[20:21]
	v_lshl_add_u64 v[136:137], v[136:137], 0, v[0:1]
	global_load_dwordx4 v[156:159], v[136:137], off
	global_load_dwordx4 v[152:155], v[136:137], off offset:256
	v_mov_b32_e32 v136, v174
	v_or_b32_e32 v172, 48, v183
	v_ashrrev_i32_e32 v137, 31, v136
	v_lshlrev_b64 v[136:137], 11, v[136:137]
	v_lshl_add_u64 v[136:137], s[10:11], 0, v[136:137]
	v_lshl_add_u64 v[136:137], v[136:137], 0, s[20:21]
	v_lshl_add_u64 v[136:137], v[136:137], 0, v[0:1]
	global_load_dwordx4 v[148:151], v[136:137], off
	global_load_dwordx4 v[140:143], v[136:137], off offset:256
	v_mov_b32_e32 v136, v172
	v_cmp_eq_u32_e32 vcc, 0, v138
	v_ashrrev_i32_e32 v137, 31, v136
	v_lshlrev_b64 v[136:137], 11, v[136:137]
	v_lshl_add_u64 v[136:137], s[10:11], 0, v[136:137]
	v_lshl_add_u64 v[136:137], v[136:137], 0, s[20:21]
	v_lshl_add_u64 v[136:137], v[136:137], 0, v[0:1]
	global_load_dwordx4 v[144:147], v[136:137], off
	s_nop 0
	global_load_dwordx4 v[136:139], v[136:137], off offset:256
	v_mov_b32_e32 v178, v183
	s_waitcnt vmcnt(0)
	v_lshlrev_b32_e32 v200, 16, v196
	v_ashrrev_i32_e32 v179, 31, v178
	v_lshlrev_b64 v[184:185], 11, v[178:179]
	v_lshl_add_u64 v[184:185], s[10:11], 0, v[184:185]
	v_and_b32_e32 v201, 0xffff0000, v196
	v_lshlrev_b32_e32 v196, 16, v197
	v_and_b32_e32 v197, 0xffff0000, v197
	v_lshlrev_b32_e32 v202, 16, v198
	v_and_b32_e32 v203, 0xffff0000, v198
	v_lshlrev_b32_e32 v198, 16, v199
	v_and_b32_e32 v199, 0xffff0000, v199
	v_lshl_add_u64 v[184:185], v[184:185], 0, s[20:21]
	v_pk_add_f32 v[134:135], v[134:135], v[196:197]
	v_pk_add_f32 v[132:133], v[132:133], v[200:201]
	v_pk_add_f32 v[196:197], v[130:131], v[198:199]
	v_pk_add_f32 v[198:199], v[128:129], v[202:203]
	v_cvt_pk_bf16_f32 v128, v132, v133
	v_cvt_pk_bf16_f32 v129, v134, v135
	v_lshl_add_u64 v[184:185], v[184:185], 0, v[0:1]
	v_cvt_pk_bf16_f32 v130, v198, v199
	v_cvt_pk_bf16_f32 v131, v196, v197
	global_store_dwordx4 v[184:185], v[128:131], off
	s_nop 1
	v_mul_f32_e32 v128, v133, v133
	v_mul_f32_e32 v129, v135, v135
	v_fmac_f32_e32 v128, v132, v132
	v_fmac_f32_e32 v129, v134, v134
	v_add_f32_e32 v128, v128, v129
	v_mul_f32_e32 v129, v199, v199
	v_fmac_f32_e32 v129, v198, v198
	v_add_f32_e32 v128, v129, v128
	v_mul_f32_e32 v129, v197, v197
	v_fmac_f32_e32 v129, v196, v196
	v_add_f32_e32 v173, v129, v128
	v_lshlrev_b32_e32 v128, 16, v160
	v_and_b32_e32 v129, 0xffff0000, v160
	v_lshlrev_b32_e32 v130, 16, v161
	v_and_b32_e32 v131, 0xffff0000, v161
	v_lshlrev_b32_e32 v132, 16, v162
	v_and_b32_e32 v133, 0xffff0000, v162
	v_lshlrev_b32_e32 v134, 16, v163
	v_and_b32_e32 v135, 0xffff0000, v163
	v_pk_add_f32 v[126:127], v[126:127], v[130:131]
	v_pk_add_f32 v[124:125], v[124:125], v[128:129]
	v_pk_add_f32 v[130:131], v[120:121], v[132:133]
	v_cvt_pk_bf16_f32 v120, v124, v125
	v_cvt_pk_bf16_f32 v121, v126, v127
	v_pk_add_f32 v[128:129], v[122:123], v[134:135]
	v_cvt_pk_bf16_f32 v122, v130, v131
	s_nop 0
	v_cvt_pk_bf16_f32 v123, v128, v129
	global_store_dwordx4 v[184:185], v[120:123], off offset:256
	s_nop 1
	v_mul_f32_e32 v120, v125, v125
	v_mul_f32_e32 v121, v127, v127
	v_fmac_f32_e32 v120, v124, v124
	v_fmac_f32_e32 v121, v126, v126
	v_add_f32_e32 v120, v120, v121
	v_mul_f32_e32 v121, v131, v131
	v_fmac_f32_e32 v121, v130, v130
	v_add_f32_e32 v120, v121, v120
	v_mul_f32_e32 v121, v129, v129
	v_fmac_f32_e32 v121, v128, v128
	v_add_f32_e32 v120, v121, v120
	v_xor_b32_e32 v121, 16, v190
	v_cmp_lt_i32_e64 s[6:7], v121, v192
	v_add_f32_e32 v120, v173, v120
	s_nop 0
	v_cndmask_b32_e64 v121, v190, v121, s[6:7]
	v_lshlrev_b32_e32 v124, 2, v121
	ds_bpermute_b32 v121, v124, v120
	s_waitcnt lgkmcnt(0)
	v_add_f32_e32 v120, v120, v121
	v_xor_b32_e32 v121, 32, v190
	v_cmp_lt_i32_e64 s[6:7], v121, v192
	s_nop 1
	v_cndmask_b32_e64 v121, v190, v121, s[6:7]
	v_lshlrev_b32_e32 v125, 2, v121
	ds_bpermute_b32 v121, v125, v120
	s_and_saveexec_b64 s[6:7], vcc
	s_cbranch_execz .LBB0_1040
	s_ashr_i32 s9, s8, 31
	s_lshl_b64 s[4:5], s[8:9], 19
	s_add_u32 s4, s38, s4
	s_addc_u32 s5, s39, s5
	s_waitcnt lgkmcnt(0)
	v_add_f32_e32 v122, v120, v121
	v_lshl_add_u64 v[120:121], v[178:179], 4, s[4:5]
	s_lshl_b32 s74, s15, 2
	v_lshl_add_u64 v[120:121], v[120:121], 0, s[74:75]
	global_store_dword v[120:121], v122, off

; #define G_STAGE(bufoff, gbase, o0, h64) do { \
;         __builtin_amdgcn_global_load_lds((const unsigned*)((const char*)(gbase) + (o0)), (LAS unsigned*)(lds + (bufoff) + ldsw), 16, 0, 0); \
;         __builtin_amdgcn_global_load_lds((const unsigned*)((const char*)(gbase) + (h64) + (o0)), (LAS unsigned*)(lds + (bufoff) + ldsw + 8192), 16, 0, 0); } while (0)
; #define G_LDA(dst, b, h) do { _Pragma("unroll") for (int m = 0; m < 4; ++m) _Pragma("unroll") for (int k = 0; k < 2; ++k) dst[m][k] = *(const LAS bf16x8*)(lds + G_SA(b, h) + aoff + m * 2048 + k * 1024); } while (0)
; #define G_LDB(dst, b, h) do { _Pragma("unroll") for (int n = 0; n < 2; ++n) _Pragma("unroll") for (int k = 0; k < 2; ++k) dst[n][k] = *(const LAS bf16x8*)(lds + G_SB(b, h) + boff + n * 2048 + k * 1024); } while (0)
; #define G_WAIT_L(n) asm volatile("s_waitcnt lgkmcnt(" #n ")" ::: "memory")
; #define G_BAR __builtin_amdgcn_s_barrier()
; #define G_SCHED __builtin_amdgcn_sched_barrier(0)
;     ...
;         for (int t = 0; t < nt; t += 2) {
;             const bool last = (t == nt - 2);
;             const char* a1 = cA + (size_t)(t + 1) * ckA;
;             const char* a2 = last ? nA : cA + (size_t)(t + 2) * ckA; const char* b2 = last ? nB : cB + (size_t)(t + 2) * kB;
;             const char* a3 = a2 + ckA; const char* b3 = b2 + kB;
;             G_LDB(B0, 0, 0); G_SCHED; G_LDA(At, 0, 0); G_STAGE(G_SA(1, 1), a1 + chA, cA0, qA);
;             G_WAIT_L(8); G_BAR; G_WAIT_L(0); G_MMA(0, 0, At, B0); G_BAR; G_SCHED;
;             G_LDB(B1, 0, 1); G_STAGE(G_SB(0, 0), b2, cB0, qB);
;             G_BAR; G_WAIT_L(0); G_MMA(0, 1, At, B1); G_BAR;
;             G_LDA(At, 0, 1); G_STAGE(G_SA(0, 0), a2, cA0, qA);
;             G_BAR; G_WAIT_L(0); G_MMA(1, 0, At, B0); G_BAR; G_SCHED;
.LBB0_1120:
	s_add_u32 s4, s2, 0xfffc0080
	s_addc_u32 s5, s3, -1
	s_add_i32 s19, 0, 0x10000
	v_add_u32_e32 v0, s19, v149
	ds_read_b128 v[140:143], v0
	ds_read_b128 v[144:147], v0 offset:1024
	ds_read_b128 v[152:155], v0 offset:2048
	ds_read_b128 v[156:159], v0 offset:3072
	s_cmp_eq_u32 s18, 12
	s_cselect_b32 s5, s13, s5
	s_cselect_b32 s4, s12, s4
	s_cselect_b32 s41, s15, s17
	s_cselect_b32 s40, s14, s16
	v_lshl_add_u64 v[184:185], s[2:3], 0, v[138:139]
	s_add_i32 m0, s26, 0xc000
	ds_read_b128 v[160:163], v150
	ds_read_b128 v[164:167], v150 offset:1024
	ds_read_b128 v[172:175], v150 offset:2048
	ds_read_b128 v[176:179], v150 offset:3072
	ds_read_b128 v[180:183], v150 offset:4096
	ds_read_b128 v[196:199], v150 offset:5120
	ds_read_b128 v[200:203], v150 offset:6144
	ds_read_b128 v[204:207], v150 offset:7168
	global_load_lds_dwordx4 v[184:185], off
	v_lshl_add_u64 v[184:185], v[184:185], 0, s[0:1]
	s_add_i32 m0, s26, 0xe000
	s_nop 0
	global_load_lds_dwordx4 v[184:185], off
	s_waitcnt lgkmcnt(8)
	s_barrier
	s_waitcnt lgkmcnt(0)
	s_setprio 3
	s_waitcnt lgkmcnt(0)
	v_mfma_f32_16x16x32_bf16 v[132:135], v[140:143], v[160:163], v[132:135]
	v_mfma_f32_16x16x32_bf16 v[124:127], v[152:155], v[160:163], v[124:127]
	v_mfma_f32_16x16x32_bf16 v[116:119], v[140:143], v[172:175], v[116:119]
	v_mfma_f32_16x16x32_bf16 v[108:111], v[152:155], v[172:175], v[108:111]
	v_mfma_f32_16x16x32_bf16 v[100:103], v[140:143], v[180:183], v[100:103]
	v_mfma_f32_16x16x32_bf16 v[92:95], v[152:155], v[180:183], v[92:95]
	v_mfma_f32_16x16x32_bf16 v[84:87], v[140:143], v[200:203], v[84:87]
	v_mfma_f32_16x16x32_bf16 v[76:79], v[152:155], v[200:203], v[76:79]
	v_mfma_f32_16x16x32_bf16 v[132:135], v[144:147], v[164:167], v[132:135]
	v_mfma_f32_16x16x32_bf16 v[124:127], v[156:159], v[164:167], v[124:127]
	v_mfma_f32_16x16x32_bf16 v[116:119], v[144:147], v[176:179], v[116:119]
	v_mfma_f32_16x16x32_bf16 v[108:111], v[156:159], v[176:179], v[108:111]
	v_mfma_f32_16x16x32_bf16 v[100:103], v[144:147], v[196:199], v[100:103]
	v_mfma_f32_16x16x32_bf16 v[92:95], v[156:159], v[196:199], v[92:95]
	v_mfma_f32_16x16x32_bf16 v[84:87], v[144:147], v[204:207], v[84:87]
	v_mfma_f32_16x16x32_bf16 v[76:79], v[156:159], v[204:207], v[76:79]
	s_setprio 0
	s_barrier
	s_add_i32 s39, 0, 0x14000
	s_add_i32 s19, s19, s21
	v_add_u32_e32 v0, s39, v149
	v_lshl_add_u64 v[184:185], s[40:41], 0, v[2:3]
	s_mov_b32 m0, s19
	ds_read_b128 v[208:211], v0
	ds_read_b128 v[212:215], v0 offset:1024
	ds_read_b128 v[216:219], v0 offset:2048
	ds_read_b128 v[220:223], v0 offset:3072
	global_load_lds_dwordx4 v[184:185], off
	v_lshl_add_u64 v[224:225], v[184:185], 0, s[0:1]
	s_add_i32 m0, s19, 0x2000
	s_nop 0
	global_load_lds_dwordx4 v[224:225], off
	s_barrier
	s_waitcnt lgkmcnt(0)
	s_setprio 3
	s_waitcnt lgkmcnt(0)
	v_mfma_f32_16x16x32_bf16 v[128:131], v[208:211], v[160:163], v[128:131]
	v_mfma_f32_16x16x32_bf16 v[120:123], v[216:219], v[160:163], v[120:123]
	v_mfma_f32_16x16x32_bf16 v[112:115], v[208:211], v[172:175], v[112:115]
	v_mfma_f32_16x16x32_bf16 v[104:107], v[216:219], v[172:175], v[104:107]
	v_mfma_f32_16x16x32_bf16 v[96:99], v[208:211], v[180:183], v[96:99]
	v_mfma_f32_16x16x32_bf16 v[88:91], v[216:219], v[180:183], v[88:91]
	v_mfma_f32_16x16x32_bf16 v[80:83], v[208:211], v[200:203], v[80:83]
	v_mfma_f32_16x16x32_bf16 v[72:75], v[216:219], v[200:203], v[72:75]
	v_mfma_f32_16x16x32_bf16 v[128:131], v[212:215], v[164:167], v[128:131]
	v_mfma_f32_16x16x32_bf16 v[120:123], v[220:223], v[164:167], v[120:123]
	v_mfma_f32_16x16x32_bf16 v[112:115], v[212:215], v[176:179], v[112:115]
	v_mfma_f32_16x16x32_bf16 v[104:107], v[220:223], v[176:179], v[104:107]
	v_mfma_f32_16x16x32_bf16 v[96:99], v[212:215], v[196:199], v[96:99]
	v_mfma_f32_16x16x32_bf16 v[88:91], v[220:223], v[196:199], v[88:91]
	v_mfma_f32_16x16x32_bf16 v[80:83], v[212:215], v[204:207], v[80:83]
	v_mfma_f32_16x16x32_bf16 v[72:75], v[220:223], v[204:207], v[72:75]
	s_setprio 0
	s_mov_b32 m0, s26
	v_lshl_add_u64 v[224:225], s[4:5], 0, v[136:137]
	s_barrier
	ds_read_b128 v[160:163], v150 offset:16384
	ds_read_b128 v[164:167], v150 offset:17408
	ds_read_b128 v[172:175], v150 offset:18432
	ds_read_b128 v[176:179], v150 offset:19456
	ds_read_b128 v[180:183], v150 offset:20480
	ds_read_b128 v[196:199], v150 offset:21504
	ds_read_b128 v[200:203], v150 offset:22528
	ds_read_b128 v[204:207], v150 offset:23552
	global_load_lds_dwordx4 v[224:225], off
	v_lshl_add_u64 v[226:227], v[224:225], 0, s[0:1]
	s_mov_b32 m0, s27
	s_nop 0
	global_load_lds_dwordx4 v[226:227], off
	s_barrier
	s_waitcnt lgkmcnt(0)
	s_setprio 3
	s_waitcnt lgkmcnt(0)
	v_mfma_f32_16x16x32_bf16 v[68:71], v[140:143], v[160:163], v[68:71]
	v_mfma_f32_16x16x32_bf16 v[60:63], v[152:155], v[160:163], v[60:63]
	v_mfma_f32_16x16x32_bf16 v[52:55], v[140:143], v[172:175], v[52:55]
	v_mfma_f32_16x16x32_bf16 v[44:47], v[152:155], v[172:175], v[44:47]
	v_mfma_f32_16x16x32_bf16 v[36:39], v[140:143], v[180:183], v[36:39]
	v_mfma_f32_16x16x32_bf16 v[28:31], v[152:155], v[180:183], v[28:31]
	v_mfma_f32_16x16x32_bf16 v[20:23], v[140:143], v[200:203], v[20:23]
	v_mfma_f32_16x16x32_bf16 v[12:15], v[152:155], v[200:203], v[12:15]
	v_mfma_f32_16x16x32_bf16 v[68:71], v[144:147], v[164:167], v[68:71]
	v_mfma_f32_16x16x32_bf16 v[60:63], v[156:159], v[164:167], v[60:63]
	v_mfma_f32_16x16x32_bf16 v[52:55], v[144:147], v[176:179], v[52:55]
	v_mfma_f32_16x16x32_bf16 v[44:47], v[156:159], v[176:179], v[44:47]
	v_mfma_f32_16x16x32_bf16 v[36:39], v[144:147], v[196:199], v[36:39]
	v_mfma_f32_16x16x32_bf16 v[28:31], v[156:159], v[196:199], v[28:31]
	v_mfma_f32_16x16x32_bf16 v[20:23], v[144:147], v[204:207], v[20:23]
	v_mfma_f32_16x16x32_bf16 v[12:15], v[156:159], v[204:207], v[12:15]
	s_setprio 0
	s_barrier
; #define G_STAGE(bufoff, gbase, o0, h64) do { \
;         __builtin_amdgcn_global_load_lds((const unsigned*)((const char*)(gbase) + (o0)), (LAS unsigned*)(lds + (bufoff) + ldsw), 16, 0, 0); \
;         __builtin_amdgcn_global_load_lds((const unsigned*)((const char*)(gbase) + (h64) + (o0)), (LAS unsigned*)(lds + (bufoff) + ldsw + 8192), 16, 0, 0); } while (0)
; #define G_LDA(dst, b, h) do { _Pragma("unroll") for (int m = 0; m < 4; ++m) _Pragma("unroll") for (int k = 0; k < 2; ++k) dst[m][k] = *(const LAS bf16x8*)(lds + G_SA(b, h) + aoff + m * 2048 + k * 1024); } while (0)
; #define G_LDB(dst, b, h) do { _Pragma("unroll") for (int n = 0; n < 2; ++n) _Pragma("unroll") for (int k = 0; k < 2; ++k) dst[n][k] = *(const LAS bf16x8*)(lds + G_SB(b, h) + boff + n * 2048 + k * 1024); } while (0)
; #define G_WAIT_V(n) asm volatile("s_waitcnt vmcnt(" #n ")" ::: "memory")
; #define G_WAIT_L(n) asm volatile("s_waitcnt lgkmcnt(" #n ")" ::: "memory")
; #define G_BAR __builtin_amdgcn_s_barrier()
; #define G_SCHED __builtin_amdgcn_sched_barrier(0)
;     ...
;             G_STAGE(G_SB(0, 1), b2 + chB, cB0, qB);
;             G_WAIT_V(6); G_BAR; G_MMA(1, 1, At, B1); G_BAR;
;             G_LDB(B0, 1, 0); G_SCHED; G_LDA(At, 1, 0); G_STAGE(G_SA(0, 1), a2 + chA, cA0, qA);
;             G_WAIT_L(8); G_BAR; G_WAIT_L(0); G_MMA(0, 0, At, B0); G_BAR; G_SCHED;
;             G_LDB(B1, 1, 1); G_STAGE(G_SB(1, 0), b3, cB0, qB);
;             G_BAR; G_WAIT_L(0); G_MMA(0, 1, At, B1); G_BAR;
;             G_LDA(At, 1, 1); G_STAGE(G_SA(1, 0), a3, cA0, qA);
;             G_BAR; G_WAIT_L(0); G_MMA(1, 0, At, B0); G_BAR; G_SCHED;
;             G_STAGE(G_SB(1, 1), b3 + chB, cB0, qB);
	s_add_i32 s4, s39, s21
	v_lshl_add_u64 v[140:141], v[184:185], 0, s[42:43]
	s_mov_b32 m0, s4
	s_nop 0
	global_load_lds_dwordx4 v[140:141], off
	v_lshl_add_u64 v[140:141], v[184:185], 0, s[50:51]
	s_add_i32 m0, s4, 0x2000
	s_nop 0
	global_load_lds_dwordx4 v[140:141], off
	s_waitcnt vmcnt(6)
	s_barrier
	s_setprio 3
	v_mfma_f32_16x16x32_bf16 v[64:67], v[208:211], v[160:163], v[64:67]
	v_mfma_f32_16x16x32_bf16 v[56:59], v[216:219], v[160:163], v[56:59]
	v_mfma_f32_16x16x32_bf16 v[48:51], v[208:211], v[172:175], v[48:51]
	v_mfma_f32_16x16x32_bf16 v[40:43], v[216:219], v[172:175], v[40:43]
	v_mfma_f32_16x16x32_bf16 v[32:35], v[208:211], v[180:183], v[32:35]
	v_mfma_f32_16x16x32_bf16 v[24:27], v[216:219], v[180:183], v[24:27]
	v_mfma_f32_16x16x32_bf16 v[16:19], v[208:211], v[200:203], v[16:19]
	v_mfma_f32_16x16x32_bf16 v[8:11], v[216:219], v[200:203], v[8:11]
	v_mfma_f32_16x16x32_bf16 v[64:67], v[212:215], v[164:167], v[64:67]
	v_mfma_f32_16x16x32_bf16 v[56:59], v[220:223], v[164:167], v[56:59]
	v_mfma_f32_16x16x32_bf16 v[48:51], v[212:215], v[176:179], v[48:51]
	v_mfma_f32_16x16x32_bf16 v[40:43], v[220:223], v[176:179], v[40:43]
	v_mfma_f32_16x16x32_bf16 v[32:35], v[212:215], v[196:199], v[32:35]
	v_mfma_f32_16x16x32_bf16 v[24:27], v[220:223], v[196:199], v[24:27]
	v_mfma_f32_16x16x32_bf16 v[16:19], v[212:215], v[204:207], v[16:19]
	v_mfma_f32_16x16x32_bf16 v[8:11], v[220:223], v[204:207], v[8:11]
	s_setprio 0
	s_add_i32 s4, 0, 0x18000
	v_add_u32_e32 v0, s4, v149
	s_barrier
	ds_read_b128 v[140:143], v0
	ds_read_b128 v[144:147], v0 offset:1024
	ds_read_b128 v[152:155], v0 offset:2048
	ds_read_b128 v[156:159], v0 offset:3072
	s_mov_b32 m0, s29
	v_lshl_add_u64 v[208:209], v[224:225], 0, s[42:43]
	ds_read_b128 v[160:163], v150 offset:32768
	ds_read_b128 v[164:167], v150 offset:33792
	ds_read_b128 v[172:175], v150 offset:34816
	ds_read_b128 v[176:179], v150 offset:35840
	ds_read_b128 v[180:183], v150 offset:36864
	ds_read_b128 v[196:199], v150 offset:37888
	ds_read_b128 v[200:203], v150 offset:38912
	ds_read_b128 v[204:207], v150 offset:39936
	global_load_lds_dwordx4 v[208:209], off
	v_lshl_add_u64 v[208:209], v[224:225], 0, s[50:51]
	s_mov_b32 m0, s30
	s_nop 0
	global_load_lds_dwordx4 v[208:209], off
	s_waitcnt lgkmcnt(8)
	s_barrier
	s_waitcnt lgkmcnt(0)
	s_setprio 3
	s_waitcnt lgkmcnt(0)
	v_mfma_f32_16x16x32_bf16 v[132:135], v[140:143], v[160:163], v[132:135]
	v_mfma_f32_16x16x32_bf16 v[124:127], v[152:155], v[160:163], v[124:127]
	v_mfma_f32_16x16x32_bf16 v[116:119], v[140:143], v[172:175], v[116:119]
	v_mfma_f32_16x16x32_bf16 v[108:111], v[152:155], v[172:175], v[108:111]
	v_mfma_f32_16x16x32_bf16 v[100:103], v[140:143], v[180:183], v[100:103]
	v_mfma_f32_16x16x32_bf16 v[92:95], v[152:155], v[180:183], v[92:95]
	v_mfma_f32_16x16x32_bf16 v[84:87], v[140:143], v[200:203], v[84:87]
	v_mfma_f32_16x16x32_bf16 v[76:79], v[152:155], v[200:203], v[76:79]
	v_mfma_f32_16x16x32_bf16 v[132:135], v[144:147], v[164:167], v[132:135]
	v_mfma_f32_16x16x32_bf16 v[124:127], v[156:159], v[164:167], v[124:127]
	v_mfma_f32_16x16x32_bf16 v[116:119], v[144:147], v[176:179], v[116:119]
	v_mfma_f32_16x16x32_bf16 v[108:111], v[156:159], v[176:179], v[108:111]
	v_mfma_f32_16x16x32_bf16 v[100:103], v[144:147], v[196:199], v[100:103]
	v_mfma_f32_16x16x32_bf16 v[92:95], v[156:159], v[196:199], v[92:95]
	v_mfma_f32_16x16x32_bf16 v[84:87], v[144:147], v[204:207], v[84:87]
	v_mfma_f32_16x16x32_bf16 v[76:79], v[156:159], v[204:207], v[76:79]
	s_setprio 0
	s_barrier
	s_add_i32 s5, 0, 0x1c000
	s_add_i32 s4, s4, s21
	v_add_u32_e32 v0, s5, v149
	v_lshl_add_u64 v[226:227], v[184:185], 0, s[46:47]
	s_mov_b32 m0, s4
	ds_read_b128 v[208:211], v0
	ds_read_b128 v[212:215], v0 offset:1024
	ds_read_b128 v[216:219], v0 offset:2048
	ds_read_b128 v[220:223], v0 offset:3072
	global_load_lds_dwordx4 v[226:227], off
	v_lshl_add_u64 v[226:227], v[184:185], 0, s[52:53]
	s_add_i32 m0, s4, 0x2000
	s_nop 0
	global_load_lds_dwordx4 v[226:227], off
	s_barrier
; #define G_STAGE(bufoff, gbase, o0, h64) do { \
;         __builtin_amdgcn_global_load_lds((const unsigned*)((const char*)(gbase) + (o0)), (LAS unsigned*)(lds + (bufoff) + ldsw), 16, 0, 0); \
;         __builtin_amdgcn_global_load_lds((const unsigned*)((const char*)(gbase) + (h64) + (o0)), (LAS unsigned*)(lds + (bufoff) + ldsw + 8192), 16, 0, 0); } while (0)
; #define G_LDA(dst, b, h) do { _Pragma("unroll") for (int m = 0; m < 4; ++m) _Pragma("unroll") for (int k = 0; k < 2; ++k) dst[m][k] = *(const LAS bf16x8*)(lds + G_SA(b, h) + aoff + m * 2048 + k * 1024); } while (0)
; #define G_WAIT_V(n) asm volatile("s_waitcnt vmcnt(" #n ")" ::: "memory")
; #define G_WAIT_L(n) asm volatile("s_waitcnt lgkmcnt(" #n ")" ::: "memory")
; #define G_BAR __builtin_amdgcn_s_barrier()
; #define G_SCHED __builtin_amdgcn_sched_barrier(0)
;     ...
;             G_LDA(At, 1, 1); G_STAGE(G_SA(1, 0), a3, cA0, qA);
;             G_BAR; G_WAIT_L(0); G_MMA(1, 0, At, B0); G_BAR; G_SCHED;
;             G_STAGE(G_SB(1, 1), b3 + chB, cB0, qB);
;             G_WAIT_V(6); G_BAR; G_MMA(1, 1, At, B1); G_BAR;
;         }
;         E.template run<cs.kind>(acc, cur, tid);
;         if (!has_next) break;
	s_waitcnt lgkmcnt(0)
	s_setprio 3
	s_waitcnt lgkmcnt(0)
	v_mfma_f32_16x16x32_bf16 v[128:131], v[208:211], v[160:163], v[128:131]
	v_mfma_f32_16x16x32_bf16 v[120:123], v[216:219], v[160:163], v[120:123]
	v_mfma_f32_16x16x32_bf16 v[112:115], v[208:211], v[172:175], v[112:115]
	v_mfma_f32_16x16x32_bf16 v[104:107], v[216:219], v[172:175], v[104:107]
	v_mfma_f32_16x16x32_bf16 v[96:99], v[208:211], v[180:183], v[96:99]
	v_mfma_f32_16x16x32_bf16 v[88:91], v[216:219], v[180:183], v[88:91]
	v_mfma_f32_16x16x32_bf16 v[80:83], v[208:211], v[200:203], v[80:83]
	v_mfma_f32_16x16x32_bf16 v[72:75], v[216:219], v[200:203], v[72:75]
	v_mfma_f32_16x16x32_bf16 v[128:131], v[212:215], v[164:167], v[128:131]
	v_mfma_f32_16x16x32_bf16 v[120:123], v[220:223], v[164:167], v[120:123]
	v_mfma_f32_16x16x32_bf16 v[112:115], v[212:215], v[176:179], v[112:115]
	v_mfma_f32_16x16x32_bf16 v[104:107], v[220:223], v[176:179], v[104:107]
	v_mfma_f32_16x16x32_bf16 v[96:99], v[212:215], v[196:199], v[96:99]
	v_mfma_f32_16x16x32_bf16 v[88:91], v[220:223], v[196:199], v[88:91]
	v_mfma_f32_16x16x32_bf16 v[80:83], v[212:215], v[204:207], v[80:83]
	v_mfma_f32_16x16x32_bf16 v[72:75], v[220:223], v[204:207], v[72:75]
	s_setprio 0
	s_mov_b32 m0, s31
	v_lshl_add_u64 v[226:227], v[224:225], 0, s[46:47]
	s_barrier
	ds_read_b128 v[160:163], v150 offset:49152
	ds_read_b128 v[164:167], v150 offset:50176
	ds_read_b128 v[172:175], v150 offset:51200
	ds_read_b128 v[176:179], v150 offset:52224
	ds_read_b128 v[180:183], v150 offset:53248
	ds_read_b128 v[196:199], v150 offset:54272
	ds_read_b128 v[200:203], v150 offset:55296
	ds_read_b128 v[204:207], v150 offset:56320
	global_load_lds_dwordx4 v[226:227], off
	v_lshl_add_u64 v[224:225], v[224:225], 0, s[52:53]
	s_mov_b32 m0, s34
	s_nop 0
	global_load_lds_dwordx4 v[224:225], off
	s_barrier
	s_waitcnt lgkmcnt(0)
	s_setprio 3
	s_waitcnt lgkmcnt(0)
	v_mfma_f32_16x16x32_bf16 v[68:71], v[140:143], v[160:163], v[68:71]
	v_mfma_f32_16x16x32_bf16 v[60:63], v[152:155], v[160:163], v[60:63]
	v_mfma_f32_16x16x32_bf16 v[52:55], v[140:143], v[172:175], v[52:55]
	v_mfma_f32_16x16x32_bf16 v[44:47], v[152:155], v[172:175], v[44:47]
	v_mfma_f32_16x16x32_bf16 v[36:39], v[140:143], v[180:183], v[36:39]
	v_mfma_f32_16x16x32_bf16 v[28:31], v[152:155], v[180:183], v[28:31]
	v_mfma_f32_16x16x32_bf16 v[20:23], v[140:143], v[200:203], v[20:23]
	v_mfma_f32_16x16x32_bf16 v[12:15], v[152:155], v[200:203], v[12:15]
	v_mfma_f32_16x16x32_bf16 v[68:71], v[144:147], v[164:167], v[68:71]
	v_mfma_f32_16x16x32_bf16 v[60:63], v[156:159], v[164:167], v[60:63]
	v_mfma_f32_16x16x32_bf16 v[52:55], v[144:147], v[176:179], v[52:55]
	v_mfma_f32_16x16x32_bf16 v[44:47], v[156:159], v[176:179], v[44:47]
	v_mfma_f32_16x16x32_bf16 v[36:39], v[144:147], v[196:199], v[36:39]
	v_mfma_f32_16x16x32_bf16 v[28:31], v[156:159], v[196:199], v[28:31]
	v_mfma_f32_16x16x32_bf16 v[20:23], v[144:147], v[204:207], v[20:23]
	v_mfma_f32_16x16x32_bf16 v[12:15], v[156:159], v[204:207], v[12:15]
	s_setprio 0
	s_barrier
	s_add_i32 s4, s5, s21
	v_lshl_add_u64 v[140:141], v[184:185], 0, s[54:55]
	s_mov_b32 m0, s4
	s_nop 0
	global_load_lds_dwordx4 v[140:141], off
	v_lshl_add_u64 v[140:141], v[184:185], 0, s[58:59]
	s_add_i32 m0, s4, 0x2000
	s_nop 0
	global_load_lds_dwordx4 v[140:141], off
	s_waitcnt vmcnt(6)
	s_barrier
	s_setprio 3
	v_mfma_f32_16x16x32_bf16 v[64:67], v[208:211], v[160:163], v[64:67]
	v_mfma_f32_16x16x32_bf16 v[56:59], v[216:219], v[160:163], v[56:59]
	v_mfma_f32_16x16x32_bf16 v[48:51], v[208:211], v[172:175], v[48:51]
	v_mfma_f32_16x16x32_bf16 v[40:43], v[216:219], v[172:175], v[40:43]
	v_mfma_f32_16x16x32_bf16 v[32:35], v[208:211], v[180:183], v[32:35]
	v_mfma_f32_16x16x32_bf16 v[24:27], v[216:219], v[180:183], v[24:27]
	v_mfma_f32_16x16x32_bf16 v[16:19], v[208:211], v[200:203], v[16:19]
	v_mfma_f32_16x16x32_bf16 v[8:11], v[216:219], v[200:203], v[8:11]
	v_mfma_f32_16x16x32_bf16 v[64:67], v[212:215], v[164:167], v[64:67]
	v_mfma_f32_16x16x32_bf16 v[56:59], v[220:223], v[164:167], v[56:59]
	v_mfma_f32_16x16x32_bf16 v[48:51], v[212:215], v[176:179], v[48:51]
	v_mfma_f32_16x16x32_bf16 v[40:43], v[220:223], v[176:179], v[40:43]
	v_mfma_f32_16x16x32_bf16 v[32:35], v[212:215], v[196:199], v[32:35]
	v_mfma_f32_16x16x32_bf16 v[24:27], v[220:223], v[196:199], v[24:27]
	v_mfma_f32_16x16x32_bf16 v[16:19], v[212:215], v[204:207], v[16:19]
	v_mfma_f32_16x16x32_bf16 v[8:11], v[220:223], v[204:207], v[8:11]
	s_setprio 0
	s_add_i32 s18, s18, 2
	s_add_u32 s2, s2, 0x100
	s_addc_u32 s3, s3, 0
	s_add_u32 s16, s16, 0x100
	s_addc_u32 s17, s17, 0
	s_cmp_gt_u32 s18, 13
	s_cbranch_scc0 .Ldb_FFI_cont
	v_readfirstlane_b32 s101, v186
	s_cmpk_gt_u32 s101, 0xff
	s_cbranch_scc1 .Ldb_FFI_exit
	s_barrier
	s_branch .Ldb_FFI_exit

; __device__ __forceinline__ float sigmoidf_(float v) { return __builtin_amdgcn_rcpf(1.0f + __expf(-v)); }
; __device__ __forceinline__ u32x4 pack8(const f32x4 a, const f32x4 b) { u32x4 w; w.x = cvt_pk_bf16(a[0], a[1]); w.y = cvt_pk_bf16(a[2], a[3]); w.z = cvt_pk_bf16(b[0], b[1]); w.w = cvt_pk_bf16(b[2], b[3]); return w; }
; #define MEMFENCE asm volatile("" ::: "memory")
;     template <int KIND> __device__ __forceinline__ void run(f32x4 (&acc)[2][2][4][2], const Unit& u, int tid_in) const {
;     ...
;         if constexpr (KIND == K_FFI) { bf16_t* act = zb; float rs[8]; get_rs(u, wr, fr, rs);
; #pragma unroll
;             for (int ai = 0; ai < 2; ++ai)
; #pragma unroll
;                 for (int m = 0; m < 4; ++m) { int row = rbase + ai * 128 + m * 16; asm volatile("" : "+v"(row)); const float r = rs[ai * 4 + m]; f32x4 o[2];
; #pragma unroll
;                     for (int n = 0; n < 2; ++n) { const f32x4 g = acc[ai][0][m][n] * r, v = acc[ai][1][m][n] * r;
; #pragma unroll
;                         for (int j = 0; j < 4; ++j) o[n][j] = g[j] * sigmoidf_(g[j]) * v[j]; }
;                     *(u32x4*)(act + (size_t)row * ZW + u.pn * 128 + cl) = pack8(o[0], o[1]); MEMFENCE; }
.Ldb_FFI_exit:
	v_readfirstlane_b32 s2, v148
	s_lshr_b32 s4, s2, 1
	s_and_b32 s4, s4, 0x60
	v_lshrrev_b32_e32 v0, 1, v148
	v_and_or_b32 v0, v0, 24, s4
	v_and_b32_e32 v140, 15, v148
	s_lshl_b32 s4, s38, 10
	s_and_b32 s3, s2, 0xffffff00
	s_add_i32 s4, s4, s3
	v_lshl_add_u32 v141, v140, 2, s4
	v_add_u32_e32 v141, 0x20010, v141
	ds_read_b32 v240, v141
	ds_read_b32 v242, v141 offset:64
	ds_read_b32 v244, v141 offset:128
	ds_read_b32 v246, v141 offset:192
	ds_read_b32 v248, v141 offset:512
	ds_read_b32 v250, v141 offset:576
	ds_read_b32 v252, v141 offset:640
	ds_read_b32 v254, v141 offset:704
	s_ashr_i32 s3, s2, 2
	s_andn2_b32 s3, s3, 63
	v_or_b32_e32 v140, s3, v140
	v_lshl_add_u32 v140, s37, 8, v140
	v_mul_lo_u32 v140, v140, s76
	s_lshl_b32 s3, s33, 8
	v_lshlrev_b32_e32 v0, 1, v0
	v_add3_u32 v140, v140, v0, s3
	s_mov_b64 s[4:5], s[6:7]
	s_mov_b32 s2, 0xbfb8aa3b
	s_mov_b32 s100, 1.0
	s_waitcnt lgkmcnt(0)
	v_pk_mul_f32 v[132:133], v[132:133], v[240:241] op_sel_hi:[1,0]
	v_pk_mul_f32 v[128:129], v[128:129], v[240:241] op_sel_hi:[1,0]
	v_pk_mul_f32 v[216:217], v[132:133], s[2:3] op_sel_hi:[1,0]
	v_pk_mul_f32 v[134:135], v[134:135], v[240:241] op_sel_hi:[1,0]
	v_pk_mul_f32 v[130:131], v[130:131], v[240:241] op_sel_hi:[1,0]
	v_pk_mul_f32 v[218:219], v[134:135], s[2:3] op_sel_hi:[1,0]
	v_pk_mul_f32 v[124:125], v[124:125], v[240:241] op_sel_hi:[1,0]
	v_pk_mul_f32 v[120:121], v[120:121], v[240:241] op_sel_hi:[1,0]
	v_pk_mul_f32 v[220:221], v[124:125], s[2:3] op_sel_hi:[1,0]
	v_pk_mul_f32 v[126:127], v[126:127], v[240:241] op_sel_hi:[1,0]
	v_pk_mul_f32 v[122:123], v[122:123], v[240:241] op_sel_hi:[1,0]
	v_pk_mul_f32 v[222:223], v[126:127], s[2:3] op_sel_hi:[1,0]
	v_exp_f32_e32 v216, v216
	v_exp_f32_e32 v217, v217
	v_exp_f32_e32 v218, v218
	v_exp_f32_e32 v219, v219
	v_exp_f32_e32 v220, v220
	v_exp_f32_e32 v221, v221
	v_exp_f32_e32 v222, v222
	v_exp_f32_e32 v223, v223
	v_pk_add_f32 v[216:217], v[216:217], s[100:101] op_sel_hi:[1,0]
	v_pk_add_f32 v[218:219], v[218:219], s[100:101] op_sel_hi:[1,0]
	v_pk_add_f32 v[220:221], v[220:221], s[100:101] op_sel_hi:[1,0]
	v_pk_add_f32 v[222:223], v[222:223], s[100:101] op_sel_hi:[1,0]
	v_rcp_f32_e32 v216, v216
	v_rcp_f32_e32 v217, v217
	v_rcp_f32_e32 v218, v218
	v_rcp_f32_e32 v219, v219
	v_rcp_f32_e32 v220, v220
	v_rcp_f32_e32 v221, v221
	v_rcp_f32_e32 v222, v222
	v_rcp_f32_e32 v223, v223
	v_pk_mul_f32 v[132:133], v[132:133], v[216:217]
	v_pk_mul_f32 v[134:135], v[134:135], v[218:219]
	v_pk_mul_f32 v[124:125], v[124:125], v[220:221]
	v_pk_mul_f32 v[126:127], v[126:127], v[222:223]
	v_pk_mul_f32 v[132:133], v[132:133], v[128:129]
	v_pk_mul_f32 v[134:135], v[134:135], v[130:131]
	v_pk_mul_f32 v[124:125], v[124:125], v[120:121]
	v_pk_mul_f32 v[126:127], v[126:127], v[122:123]
	v_cvt_pk_bf16_f32 v236, v132, v133
	v_cvt_pk_bf16_f32 v237, v134, v135
	v_cvt_pk_bf16_f32 v238, v124, v125
	v_cvt_pk_bf16_f32 v239, v126, v127
	global_store_dwordx4 v140, v[236:239], s[4:5]
	s_add_u32 s4, s4, 0x16000
	s_addc_u32 s5, s5, 0
	v_pk_mul_f32 v[116:117], v[116:117], v[242:243] op_sel_hi:[1,0]
	v_pk_mul_f32 v[112:113], v[112:113], v[242:243] op_sel_hi:[1,0]
	v_pk_mul_f32 v[216:217], v[116:117], s[2:3] op_sel_hi:[1,0]
	v_pk_mul_f32 v[118:119], v[118:119], v[242:243] op_sel_hi:[1,0]
	v_pk_mul_f32 v[114:115], v[114:115], v[242:243] op_sel_hi:[1,0]
	v_pk_mul_f32 v[218:219], v[118:119], s[2:3] op_sel_hi:[1,0]
	v_pk_mul_f32 v[108:109], v[108:109], v[242:243] op_sel_hi:[1,0]
	v_pk_mul_f32 v[104:105], v[104:105], v[242:243] op_sel_hi:[1,0]
	v_pk_mul_f32 v[220:221], v[108:109], s[2:3] op_sel_hi:[1,0]
	v_pk_mul_f32 v[110:111], v[110:111], v[242:243] op_sel_hi:[1,0]
	v_pk_mul_f32 v[106:107], v[106:107], v[242:243] op_sel_hi:[1,0]
	v_pk_mul_f32 v[222:223], v[110:111], s[2:3] op_sel_hi:[1,0]
	v_exp_f32_e32 v216, v216
	v_exp_f32_e32 v217, v217
	v_exp_f32_e32 v218, v218
	v_exp_f32_e32 v219, v219
	v_exp_f32_e32 v220, v220
	v_exp_f32_e32 v221, v221
	v_exp_f32_e32 v222, v222
	v_exp_f32_e32 v223, v223
	v_pk_add_f32 v[216:217], v[216:217], s[100:101] op_sel_hi:[1,0]
	v_pk_add_f32 v[218:219], v[218:219], s[100:101] op_sel_hi:[1,0]
	v_pk_add_f32 v[220:221], v[220:221], s[100:101] op_sel_hi:[1,0]
	v_pk_add_f32 v[222:223], v[222:223], s[100:101] op_sel_hi:[1,0]
	v_rcp_f32_e32 v216, v216
	v_rcp_f32_e32 v217, v217
	v_rcp_f32_e32 v218, v218
	v_rcp_f32_e32 v219, v219
	v_rcp_f32_e32 v220, v220
	v_rcp_f32_e32 v221, v221
	v_rcp_f32_e32 v222, v222
	v_rcp_f32_e32 v223, v223
	v_pk_mul_f32 v[116:117], v[116:117], v[216:217]
	v_pk_mul_f32 v[118:119], v[118:119], v[218:219]
	v_pk_mul_f32 v[108:109], v[108:109], v[220:221]
	v_pk_mul_f32 v[110:111], v[110:111], v[222:223]
	v_pk_mul_f32 v[116:117], v[116:117], v[112:113]
	v_pk_mul_f32 v[118:119], v[118:119], v[114:115]
	v_pk_mul_f32 v[108:109], v[108:109], v[104:105]
	v_pk_mul_f32 v[110:111], v[110:111], v[106:107]
	v_cvt_pk_bf16_f32 v236, v116, v117
	v_cvt_pk_bf16_f32 v237, v118, v119
	v_cvt_pk_bf16_f32 v238, v108, v109
	v_cvt_pk_bf16_f32 v239, v110, v111
	global_store_dwordx4 v140, v[236:239], s[4:5]
	s_add_u32 s4, s4, 0x16000
	s_addc_u32 s5, s5, 0
	v_pk_mul_f32 v[100:101], v[100:101], v[244:245] op_sel_hi:[1,0]
	v_pk_mul_f32 v[96:97], v[96:97], v[244:245] op_sel_hi:[1,0]
	v_pk_mul_f32 v[216:217], v[100:101], s[2:3] op_sel_hi:[1,0]
	v_pk_mul_f32 v[102:103], v[102:103], v[244:245] op_sel_hi:[1,0]
	v_pk_mul_f32 v[98:99], v[98:99], v[244:245] op_sel_hi:[1,0]
	v_pk_mul_f32 v[218:219], v[102:103], s[2:3] op_sel_hi:[1,0]
	v_pk_mul_f32 v[92:93], v[92:93], v[244:245] op_sel_hi:[1,0]
	v_pk_mul_f32 v[88:89], v[88:89], v[244:245] op_sel_hi:[1,0]
	v_pk_mul_f32 v[220:221], v[92:93], s[2:3] op_sel_hi:[1,0]
; __device__ __forceinline__ float sigmoidf_(float v) { return __builtin_amdgcn_rcpf(1.0f + __expf(-v)); }
; __device__ __forceinline__ u32x4 pack8(const f32x4 a, const f32x4 b) { u32x4 w; w.x = cvt_pk_bf16(a[0], a[1]); w.y = cvt_pk_bf16(a[2], a[3]); w.z = cvt_pk_bf16(b[0], b[1]); w.w = cvt_pk_bf16(b[2], b[3]); return w; }
; #define MEMFENCE asm volatile("" ::: "memory")
;     template <int KIND> __device__ __forceinline__ void run(f32x4 (&acc)[2][2][4][2], const Unit& u, int tid_in) const {
;     ...
;                 for (int m = 0; m < 4; ++m) { int row = rbase + ai * 128 + m * 16; asm volatile("" : "+v"(row)); const float r = rs[ai * 4 + m]; f32x4 o[2];
; #pragma unroll
;                     for (int n = 0; n < 2; ++n) { const f32x4 g = acc[ai][0][m][n] * r, v = acc[ai][1][m][n] * r;
; #pragma unroll
;                         for (int j = 0; j < 4; ++j) o[n][j] = g[j] * sigmoidf_(g[j]) * v[j]; }
;                     *(u32x4*)(act + (size_t)row * ZW + u.pn * 128 + cl) = pack8(o[0], o[1]); MEMFENCE; }
	v_pk_mul_f32 v[94:95], v[94:95], v[244:245] op_sel_hi:[1,0]
	v_pk_mul_f32 v[90:91], v[90:91], v[244:245] op_sel_hi:[1,0]
	v_pk_mul_f32 v[222:223], v[94:95], s[2:3] op_sel_hi:[1,0]
	v_exp_f32_e32 v216, v216
	v_exp_f32_e32 v217, v217
	v_exp_f32_e32 v218, v218
	v_exp_f32_e32 v219, v219
	v_exp_f32_e32 v220, v220
	v_exp_f32_e32 v221, v221
	v_exp_f32_e32 v222, v222
	v_exp_f32_e32 v223, v223
	v_pk_add_f32 v[216:217], v[216:217], s[100:101] op_sel_hi:[1,0]
	v_pk_add_f32 v[218:219], v[218:219], s[100:101] op_sel_hi:[1,0]
	v_pk_add_f32 v[220:221], v[220:221], s[100:101] op_sel_hi:[1,0]
	v_pk_add_f32 v[222:223], v[222:223], s[100:101] op_sel_hi:[1,0]
	v_rcp_f32_e32 v216, v216
	v_rcp_f32_e32 v217, v217
	v_rcp_f32_e32 v218, v218
	v_rcp_f32_e32 v219, v219
	v_rcp_f32_e32 v220, v220
	v_rcp_f32_e32 v221, v221
	v_rcp_f32_e32 v222, v222
	v_rcp_f32_e32 v223, v223
	v_pk_mul_f32 v[100:101], v[100:101], v[216:217]
	v_pk_mul_f32 v[102:103], v[102:103], v[218:219]
	v_pk_mul_f32 v[92:93], v[92:93], v[220:221]
	v_pk_mul_f32 v[94:95], v[94:95], v[222:223]
	v_pk_mul_f32 v[100:101], v[100:101], v[96:97]
	v_pk_mul_f32 v[102:103], v[102:103], v[98:99]
	v_pk_mul_f32 v[92:93], v[92:93], v[88:89]
	v_pk_mul_f32 v[94:95], v[94:95], v[90:91]
	v_cvt_pk_bf16_f32 v236, v100, v101
	v_cvt_pk_bf16_f32 v237, v102, v103
	v_cvt_pk_bf16_f32 v238, v92, v93
	v_cvt_pk_bf16_f32 v239, v94, v95
	global_store_dwordx4 v140, v[236:239], s[4:5]
	s_add_u32 s4, s4, 0x16000
	s_addc_u32 s5, s5, 0
	v_pk_mul_f32 v[84:85], v[84:85], v[246:247] op_sel_hi:[1,0]
	v_pk_mul_f32 v[80:81], v[80:81], v[246:247] op_sel_hi:[1,0]
	v_pk_mul_f32 v[216:217], v[84:85], s[2:3] op_sel_hi:[1,0]
	v_pk_mul_f32 v[86:87], v[86:87], v[246:247] op_sel_hi:[1,0]
	v_pk_mul_f32 v[82:83], v[82:83], v[246:247] op_sel_hi:[1,0]
	v_pk_mul_f32 v[218:219], v[86:87], s[2:3] op_sel_hi:[1,0]
	v_pk_mul_f32 v[76:77], v[76:77], v[246:247] op_sel_hi:[1,0]
	v_pk_mul_f32 v[72:73], v[72:73], v[246:247] op_sel_hi:[1,0]
	v_pk_mul_f32 v[220:221], v[76:77], s[2:3] op_sel_hi:[1,0]
	v_pk_mul_f32 v[78:79], v[78:79], v[246:247] op_sel_hi:[1,0]
	v_pk_mul_f32 v[74:75], v[74:75], v[246:247] op_sel_hi:[1,0]
	v_pk_mul_f32 v[222:223], v[78:79], s[2:3] op_sel_hi:[1,0]
	v_exp_f32_e32 v216, v216
	v_exp_f32_e32 v217, v217
	v_exp_f32_e32 v218, v218
	v_exp_f32_e32 v219, v219
	v_exp_f32_e32 v220, v220
	v_exp_f32_e32 v221, v221
	v_exp_f32_e32 v222, v222
	v_exp_f32_e32 v223, v223
	v_pk_add_f32 v[216:217], v[216:217], s[100:101] op_sel_hi:[1,0]
	v_pk_add_f32 v[218:219], v[218:219], s[100:101] op_sel_hi:[1,0]
	v_pk_add_f32 v[220:221], v[220:221], s[100:101] op_sel_hi:[1,0]
	v_pk_add_f32 v[222:223], v[222:223], s[100:101] op_sel_hi:[1,0]
	v_rcp_f32_e32 v216, v216
	v_rcp_f32_e32 v217, v217
	v_rcp_f32_e32 v218, v218
	v_rcp_f32_e32 v219, v219
	v_rcp_f32_e32 v220, v220
	v_rcp_f32_e32 v221, v221
	v_rcp_f32_e32 v222, v222
	v_rcp_f32_e32 v223, v223
	v_pk_mul_f32 v[84:85], v[84:85], v[216:217]
	v_pk_mul_f32 v[86:87], v[86:87], v[218:219]
	v_pk_mul_f32 v[76:77], v[76:77], v[220:221]
	v_pk_mul_f32 v[78:79], v[78:79], v[222:223]
	v_pk_mul_f32 v[84:85], v[84:85], v[80:81]
	v_pk_mul_f32 v[86:87], v[86:87], v[82:83]
	v_pk_mul_f32 v[76:77], v[76:77], v[72:73]
	v_pk_mul_f32 v[78:79], v[78:79], v[74:75]
	v_cvt_pk_bf16_f32 v236, v84, v85
	v_cvt_pk_bf16_f32 v237, v86, v87
	v_cvt_pk_bf16_f32 v238, v76, v77
	v_cvt_pk_bf16_f32 v239, v78, v79
	global_store_dwordx4 v140, v[236:239], s[4:5]
	s_add_u32 s4, s4, 0x6e000
	s_addc_u32 s5, s5, 0
	v_pk_mul_f32 v[68:69], v[68:69], v[248:249] op_sel_hi:[1,0]
	v_pk_mul_f32 v[64:65], v[64:65], v[248:249] op_sel_hi:[1,0]
	v_pk_mul_f32 v[216:217], v[68:69], s[2:3] op_sel_hi:[1,0]
	v_pk_mul_f32 v[70:71], v[70:71], v[248:249] op_sel_hi:[1,0]
	v_pk_mul_f32 v[66:67], v[66:67], v[248:249] op_sel_hi:[1,0]
	v_pk_mul_f32 v[218:219], v[70:71], s[2:3] op_sel_hi:[1,0]
	v_pk_mul_f32 v[60:61], v[60:61], v[248:249] op_sel_hi:[1,0]
	v_pk_mul_f32 v[56:57], v[56:57], v[248:249] op_sel_hi:[1,0]
	v_pk_mul_f32 v[220:221], v[60:61], s[2:3] op_sel_hi:[1,0]
	v_pk_mul_f32 v[62:63], v[62:63], v[248:249] op_sel_hi:[1,0]
	v_pk_mul_f32 v[58:59], v[58:59], v[248:249] op_sel_hi:[1,0]
	v_pk_mul_f32 v[222:223], v[62:63], s[2:3] op_sel_hi:[1,0]
	v_exp_f32_e32 v216, v216
	v_exp_f32_e32 v217, v217
	v_exp_f32_e32 v218, v218
	v_exp_f32_e32 v219, v219
	v_exp_f32_e32 v220, v220
	v_exp_f32_e32 v221, v221
	v_exp_f32_e32 v222, v222
	v_exp_f32_e32 v223, v223
	v_pk_add_f32 v[216:217], v[216:217], s[100:101] op_sel_hi:[1,0]
	v_pk_add_f32 v[218:219], v[218:219], s[100:101] op_sel_hi:[1,0]
	v_pk_add_f32 v[220:221], v[220:221], s[100:101] op_sel_hi:[1,0]
	v_pk_add_f32 v[222:223], v[222:223], s[100:101] op_sel_hi:[1,0]
	v_rcp_f32_e32 v216, v216
	v_rcp_f32_e32 v217, v217
	v_rcp_f32_e32 v218, v218
	v_rcp_f32_e32 v219, v219
	v_rcp_f32_e32 v220, v220
	v_rcp_f32_e32 v221, v221
	v_rcp_f32_e32 v222, v222
	v_rcp_f32_e32 v223, v223
	v_pk_mul_f32 v[68:69], v[68:69], v[216:217]
	v_pk_mul_f32 v[70:71], v[70:71], v[218:219]
	v_pk_mul_f32 v[60:61], v[60:61], v[220:221]
	v_pk_mul_f32 v[62:63], v[62:63], v[222:223]
	v_pk_mul_f32 v[68:69], v[68:69], v[64:65]
	v_pk_mul_f32 v[70:71], v[70:71], v[66:67]
	v_pk_mul_f32 v[60:61], v[60:61], v[56:57]
	v_pk_mul_f32 v[62:63], v[62:63], v[58:59]
	v_cvt_pk_bf16_f32 v236, v68, v69
	v_cvt_pk_bf16_f32 v237, v70, v71
	v_cvt_pk_bf16_f32 v238, v60, v61
	v_cvt_pk_bf16_f32 v239, v62, v63
	global_store_dwordx4 v140, v[236:239], s[4:5]
	s_add_u32 s4, s4, 0x16000
	s_addc_u32 s5, s5, 0
	v_pk_mul_f32 v[52:53], v[52:53], v[250:251] op_sel_hi:[1,0]
	v_pk_mul_f32 v[48:49], v[48:49], v[250:251] op_sel_hi:[1,0]
	v_pk_mul_f32 v[216:217], v[52:53], s[2:3] op_sel_hi:[1,0]
; __device__ __forceinline__ float sigmoidf_(float v) { return __builtin_amdgcn_rcpf(1.0f + __expf(-v)); }
; __device__ __forceinline__ u32x4 pack8(const f32x4 a, const f32x4 b) { u32x4 w; w.x = cvt_pk_bf16(a[0], a[1]); w.y = cvt_pk_bf16(a[2], a[3]); w.z = cvt_pk_bf16(b[0], b[1]); w.w = cvt_pk_bf16(b[2], b[3]); return w; }
; #define MEMFENCE asm volatile("" ::: "memory")
;     template <int KIND> __device__ __forceinline__ void run(f32x4 (&acc)[2][2][4][2], const Unit& u, int tid_in) const {
;     ...
;                 for (int m = 0; m < 4; ++m) { int row = rbase + ai * 128 + m * 16; asm volatile("" : "+v"(row)); const float r = rs[ai * 4 + m]; f32x4 o[2];
; #pragma unroll
;                     for (int n = 0; n < 2; ++n) { const f32x4 g = acc[ai][0][m][n] * r, v = acc[ai][1][m][n] * r;
; #pragma unroll
;                         for (int j = 0; j < 4; ++j) o[n][j] = g[j] * sigmoidf_(g[j]) * v[j]; }
;                     *(u32x4*)(act + (size_t)row * ZW + u.pn * 128 + cl) = pack8(o[0], o[1]); MEMFENCE; }
;         }
;     }
;     ...
;         if (!has_next) break;
;         if (!(cs.kind == K_MG_B && cur.aux < 2))
; #pragma unroll
;         for (int a = 0; a < 2; ++a)
; #pragma unroll
;             for (int b = 0; b < 2; ++b)
; #pragma unroll
;                 for (int m = 0; m < 4; ++m)
; #pragma unroll
;                     for (int n = 0; n < 2; ++n) acc[a][b][m][n] = (f32x4){0.f, 0.f, 0.f, 0.f};
;         cur = nxt; cA = nA; cB = nB; ++ui;
	v_pk_mul_f32 v[54:55], v[54:55], v[250:251] op_sel_hi:[1,0]
	v_pk_mul_f32 v[50:51], v[50:51], v[250:251] op_sel_hi:[1,0]
	v_pk_mul_f32 v[218:219], v[54:55], s[2:3] op_sel_hi:[1,0]
	v_pk_mul_f32 v[44:45], v[44:45], v[250:251] op_sel_hi:[1,0]
	v_pk_mul_f32 v[40:41], v[40:41], v[250:251] op_sel_hi:[1,0]
	v_pk_mul_f32 v[220:221], v[44:45], s[2:3] op_sel_hi:[1,0]
	v_pk_mul_f32 v[46:47], v[46:47], v[250:251] op_sel_hi:[1,0]
	v_pk_mul_f32 v[42:43], v[42:43], v[250:251] op_sel_hi:[1,0]
	v_pk_mul_f32 v[222:223], v[46:47], s[2:3] op_sel_hi:[1,0]
	v_exp_f32_e32 v216, v216
	v_exp_f32_e32 v217, v217
	v_exp_f32_e32 v218, v218
	v_exp_f32_e32 v219, v219
	v_exp_f32_e32 v220, v220
	v_exp_f32_e32 v221, v221
	v_exp_f32_e32 v222, v222
	v_exp_f32_e32 v223, v223
	v_pk_add_f32 v[216:217], v[216:217], s[100:101] op_sel_hi:[1,0]
	v_pk_add_f32 v[218:219], v[218:219], s[100:101] op_sel_hi:[1,0]
	v_pk_add_f32 v[220:221], v[220:221], s[100:101] op_sel_hi:[1,0]
	v_pk_add_f32 v[222:223], v[222:223], s[100:101] op_sel_hi:[1,0]
	v_rcp_f32_e32 v216, v216
	v_rcp_f32_e32 v217, v217
	v_rcp_f32_e32 v218, v218
	v_rcp_f32_e32 v219, v219
	v_rcp_f32_e32 v220, v220
	v_rcp_f32_e32 v221, v221
	v_rcp_f32_e32 v222, v222
	v_rcp_f32_e32 v223, v223
	v_pk_mul_f32 v[52:53], v[52:53], v[216:217]
	v_pk_mul_f32 v[54:55], v[54:55], v[218:219]
	v_pk_mul_f32 v[44:45], v[44:45], v[220:221]
	v_pk_mul_f32 v[46:47], v[46:47], v[222:223]
	v_pk_mul_f32 v[52:53], v[52:53], v[48:49]
	v_pk_mul_f32 v[54:55], v[54:55], v[50:51]
	v_pk_mul_f32 v[44:45], v[44:45], v[40:41]
	v_pk_mul_f32 v[46:47], v[46:47], v[42:43]
	v_cvt_pk_bf16_f32 v236, v52, v53
	v_cvt_pk_bf16_f32 v237, v54, v55
	v_cvt_pk_bf16_f32 v238, v44, v45
	v_cvt_pk_bf16_f32 v239, v46, v47
	global_store_dwordx4 v140, v[236:239], s[4:5]
	s_add_u32 s4, s4, 0x16000
	s_addc_u32 s5, s5, 0
	v_pk_mul_f32 v[36:37], v[36:37], v[252:253] op_sel_hi:[1,0]
	v_pk_mul_f32 v[32:33], v[32:33], v[252:253] op_sel_hi:[1,0]
	v_pk_mul_f32 v[216:217], v[36:37], s[2:3] op_sel_hi:[1,0]
	v_pk_mul_f32 v[38:39], v[38:39], v[252:253] op_sel_hi:[1,0]
	v_pk_mul_f32 v[34:35], v[34:35], v[252:253] op_sel_hi:[1,0]
	v_pk_mul_f32 v[218:219], v[38:39], s[2:3] op_sel_hi:[1,0]
	v_pk_mul_f32 v[28:29], v[28:29], v[252:253] op_sel_hi:[1,0]
	v_pk_mul_f32 v[24:25], v[24:25], v[252:253] op_sel_hi:[1,0]
	v_pk_mul_f32 v[220:221], v[28:29], s[2:3] op_sel_hi:[1,0]
	v_pk_mul_f32 v[30:31], v[30:31], v[252:253] op_sel_hi:[1,0]
	v_pk_mul_f32 v[26:27], v[26:27], v[252:253] op_sel_hi:[1,0]
	v_pk_mul_f32 v[222:223], v[30:31], s[2:3] op_sel_hi:[1,0]
	v_exp_f32_e32 v216, v216
	v_exp_f32_e32 v217, v217
	v_exp_f32_e32 v218, v218
	v_exp_f32_e32 v219, v219
	v_exp_f32_e32 v220, v220
	v_exp_f32_e32 v221, v221
	v_exp_f32_e32 v222, v222
	v_exp_f32_e32 v223, v223
	v_pk_add_f32 v[216:217], v[216:217], s[100:101] op_sel_hi:[1,0]
	v_pk_add_f32 v[218:219], v[218:219], s[100:101] op_sel_hi:[1,0]
	v_pk_add_f32 v[220:221], v[220:221], s[100:101] op_sel_hi:[1,0]
	v_pk_add_f32 v[222:223], v[222:223], s[100:101] op_sel_hi:[1,0]
	v_rcp_f32_e32 v216, v216
	v_rcp_f32_e32 v217, v217
	v_rcp_f32_e32 v218, v218
	v_rcp_f32_e32 v219, v219
	v_rcp_f32_e32 v220, v220
	v_rcp_f32_e32 v221, v221
	v_rcp_f32_e32 v222, v222
	v_rcp_f32_e32 v223, v223
	v_pk_mul_f32 v[36:37], v[36:37], v[216:217]
	v_pk_mul_f32 v[38:39], v[38:39], v[218:219]
	v_pk_mul_f32 v[28:29], v[28:29], v[220:221]
	v_pk_mul_f32 v[30:31], v[30:31], v[222:223]
	v_pk_mul_f32 v[36:37], v[36:37], v[32:33]
	v_pk_mul_f32 v[38:39], v[38:39], v[34:35]
	v_pk_mul_f32 v[28:29], v[28:29], v[24:25]
	v_pk_mul_f32 v[30:31], v[30:31], v[26:27]
	v_cvt_pk_bf16_f32 v236, v36, v37
	v_cvt_pk_bf16_f32 v237, v38, v39
	v_cvt_pk_bf16_f32 v238, v28, v29
	v_cvt_pk_bf16_f32 v239, v30, v31
	global_store_dwordx4 v140, v[236:239], s[4:5]
	s_add_u32 s4, s4, 0x16000
	s_addc_u32 s5, s5, 0
	v_pk_mul_f32 v[20:21], v[20:21], v[254:255] op_sel_hi:[1,0]
	v_pk_mul_f32 v[16:17], v[16:17], v[254:255] op_sel_hi:[1,0]
	v_pk_mul_f32 v[216:217], v[20:21], s[2:3] op_sel_hi:[1,0]
	v_pk_mul_f32 v[22:23], v[22:23], v[254:255] op_sel_hi:[1,0]
	v_pk_mul_f32 v[18:19], v[18:19], v[254:255] op_sel_hi:[1,0]
	v_pk_mul_f32 v[218:219], v[22:23], s[2:3] op_sel_hi:[1,0]
	v_pk_mul_f32 v[12:13], v[12:13], v[254:255] op_sel_hi:[1,0]
	v_pk_mul_f32 v[8:9], v[8:9], v[254:255] op_sel_hi:[1,0]
	v_pk_mul_f32 v[220:221], v[12:13], s[2:3] op_sel_hi:[1,0]
	v_pk_mul_f32 v[14:15], v[14:15], v[254:255] op_sel_hi:[1,0]
	v_pk_mul_f32 v[10:11], v[10:11], v[254:255] op_sel_hi:[1,0]
	v_pk_mul_f32 v[222:223], v[14:15], s[2:3] op_sel_hi:[1,0]
	v_exp_f32_e32 v216, v216
	v_exp_f32_e32 v217, v217
	v_exp_f32_e32 v218, v218
	v_exp_f32_e32 v219, v219
	v_exp_f32_e32 v220, v220
	v_exp_f32_e32 v221, v221
	v_exp_f32_e32 v222, v222
	v_exp_f32_e32 v223, v223
	v_pk_add_f32 v[216:217], v[216:217], s[100:101] op_sel_hi:[1,0]
	v_pk_add_f32 v[218:219], v[218:219], s[100:101] op_sel_hi:[1,0]
	v_pk_add_f32 v[220:221], v[220:221], s[100:101] op_sel_hi:[1,0]
	v_pk_add_f32 v[222:223], v[222:223], s[100:101] op_sel_hi:[1,0]
	v_rcp_f32_e32 v216, v216
	v_rcp_f32_e32 v217, v217
	v_rcp_f32_e32 v218, v218
	v_rcp_f32_e32 v219, v219
	v_rcp_f32_e32 v220, v220
	v_rcp_f32_e32 v221, v221
	v_rcp_f32_e32 v222, v222
	v_rcp_f32_e32 v223, v223
	v_pk_mul_f32 v[20:21], v[20:21], v[216:217]
	v_pk_mul_f32 v[22:23], v[22:23], v[218:219]
	v_pk_mul_f32 v[12:13], v[12:13], v[220:221]
	v_pk_mul_f32 v[14:15], v[14:15], v[222:223]
	v_pk_mul_f32 v[20:21], v[20:21], v[16:17]
	v_pk_mul_f32 v[22:23], v[22:23], v[18:19]
	v_pk_mul_f32 v[12:13], v[12:13], v[8:9]
	v_pk_mul_f32 v[14:15], v[14:15], v[10:11]
	v_cvt_pk_bf16_f32 v236, v20, v21
	v_cvt_pk_bf16_f32 v237, v22, v23
	v_cvt_pk_bf16_f32 v238, v12, v13
	v_cvt_pk_bf16_f32 v239, v14, v15
	global_store_dwordx4 v140, v[236:239], s[4:5]
	s_mov_b32 s38, s11
	s_mov_b32 s37, s10
	s_mov_b64 s[18:19], s[14:15]
	s_mov_b64 s[16:17], s[12:13]
	s_mov_b32 s33, s36
	s_and_b64 vcc, exec, s[8:9]
	s_cmpk_gt_u32 s101, 0xff
	s_cbranch_scc0 .Ldb_FFI_nob
	s_barrier
.Ldb_FFI_nob:
	s_cbranch_vccz .LBB0_1115
	s_waitcnt vmcnt(0)
	s_cmpk_gt_u32 s20, 0xff
	s_cbranch_scc1 .LBB0_1124
	s_barrier

;     ...
;         if (!has_next) break;
;         if (!(cs.kind == K_MG_B && cur.aux < 2))
; #pragma unroll
;         for (int a = 0; a < 2; ++a)
; #pragma unroll
;             for (int b = 0; b < 2; ++b)
; #pragma unroll
;                 for (int m = 0; m < 4; ++m)
; #pragma unroll
;                     for (int n = 0; n < 2; ++n) acc[a][b][m][n] = (f32x4){0.f, 0.f, 0.f, 0.f};
;         cur = nxt; cA = nA; cB = nB; ++ui;
.Ldb_FFO_nob:
	s_and_b64 vcc, exec, s[14:15]
	s_mov_b32 s11, s50
	s_mov_b32 s10, s42
	s_mov_b32 s20, s43
	s_mov_b64 s[6:7], s[18:19]
	s_mov_b64 s[2:3], s[16:17]
	s_cbranch_vccnz .LBB0_1202

; #define G_STAGE(bufoff, gbase, o0, h64) do { \
;         __builtin_amdgcn_global_load_lds((const unsigned*)((const char*)(gbase) + (o0)), (LAS unsigned*)(lds + (bufoff) + ldsw), 16, 0, 0); \
;         __builtin_amdgcn_global_load_lds((const unsigned*)((const char*)(gbase) + (h64) + (o0)), (LAS unsigned*)(lds + (bufoff) + ldsw + 8192), 16, 0, 0); } while (0)
; #define G_LDA(dst, b, h) do { _Pragma("unroll") for (int m = 0; m < 4; ++m) _Pragma("unroll") for (int k = 0; k < 2; ++k) dst[m][k] = *(const LAS bf16x8*)(lds + G_SA(b, h) + aoff + m * 2048 + k * 1024); } while (0)
; #define G_LDB(dst, b, h) do { _Pragma("unroll") for (int n = 0; n < 2; ++n) _Pragma("unroll") for (int k = 0; k < 2; ++k) dst[n][k] = *(const LAS bf16x8*)(lds + G_SB(b, h) + boff + n * 2048 + k * 1024); } while (0)
; #define G_WAIT_L(n) asm volatile("s_waitcnt lgkmcnt(" #n ")" ::: "memory")
; #define G_BAR __builtin_amdgcn_s_barrier()
; #define G_SCHED __builtin_amdgcn_sched_barrier(0)
;     ...
;         for (int t = 0; t < nt; t += 2) {
;             const bool last = (t == nt - 2);
;             const char* a1 = cA + (size_t)(t + 1) * ckA;
;             const char* a2 = last ? nA : cA + (size_t)(t + 2) * ckA; const char* b2 = last ? nB : cB + (size_t)(t + 2) * kB;
;             const char* a3 = a2 + ckA; const char* b3 = b2 + kB;
;             G_LDB(B0, 0, 0); G_SCHED; G_LDA(At, 0, 0); G_STAGE(G_SA(1, 1), a1 + chA, cA0, qA);
;             G_WAIT_L(8); G_BAR; G_WAIT_L(0); G_MMA(0, 0, At, B0); G_BAR; G_SCHED;
;             G_LDB(B1, 0, 1); G_STAGE(G_SB(0, 0), b2, cB0, qB);
;             G_BAR; G_WAIT_L(0); G_MMA(0, 1, At, B1); G_BAR;
;             G_LDA(At, 0, 1); G_STAGE(G_SA(0, 0), a2, cA0, qA);
;             G_BAR; G_WAIT_L(0); G_MMA(1, 0, At, B0); G_BAR; G_SCHED;
.LBB0_1185:
	s_add_u32 s4, s2, 0xfff50080
	s_addc_u32 s5, s3, -1
	s_add_i32 s33, 0, 0x10000
	v_add_u32_e32 v0, s33, v185
	ds_read_b128 v[136:139], v0
	ds_read_b128 v[140:143], v0 offset:1024
	ds_read_b128 v[144:147], v0 offset:2048
	ds_read_b128 v[148:151], v0 offset:3072
	s_cmp_eq_u32 s21, 40
	s_cselect_b32 s5, s17, s5
	s_cselect_b32 s4, s16, s4
	s_cselect_b32 s23, s19, s7
	s_cselect_b32 s22, s18, s6
	v_lshl_add_u64 v[204:205], s[2:3], 0, v[174:175]
	s_add_i32 m0, s26, 0xc000
	ds_read_b128 v[152:155], v195
	ds_read_b128 v[156:159], v195 offset:1024
	ds_read_b128 v[160:163], v195 offset:2048
	ds_read_b128 v[164:167], v195 offset:3072
	ds_read_b128 v[176:179], v195 offset:4096
	ds_read_b128 v[180:183], v195 offset:5120
	ds_read_b128 v[196:199], v195 offset:6144
	ds_read_b128 v[200:203], v195 offset:7168
	global_load_lds_dwordx4 v[204:205], off
	v_lshl_add_u64 v[204:205], v[204:205], 0, s[86:87]
	s_add_i32 m0, s26, 0xe000
	s_nop 0
	global_load_lds_dwordx4 v[204:205], off
	s_waitcnt lgkmcnt(8)
	s_barrier
	s_waitcnt lgkmcnt(0)
	s_setprio 3
	s_waitcnt lgkmcnt(0)
	v_mfma_f32_16x16x32_bf16 v[132:135], v[136:139], v[152:155], v[132:135]
	v_mfma_f32_16x16x32_bf16 v[128:131], v[144:147], v[152:155], v[128:131]
	v_mfma_f32_16x16x32_bf16 v[116:119], v[136:139], v[160:163], v[116:119]
	v_mfma_f32_16x16x32_bf16 v[112:115], v[144:147], v[160:163], v[112:115]
	v_mfma_f32_16x16x32_bf16 v[100:103], v[136:139], v[176:179], v[100:103]
	v_mfma_f32_16x16x32_bf16 v[96:99], v[144:147], v[176:179], v[96:99]
	v_mfma_f32_16x16x32_bf16 v[84:87], v[136:139], v[196:199], v[84:87]
	v_mfma_f32_16x16x32_bf16 v[80:83], v[144:147], v[196:199], v[80:83]
	v_mfma_f32_16x16x32_bf16 v[132:135], v[140:143], v[156:159], v[132:135]
	v_mfma_f32_16x16x32_bf16 v[128:131], v[148:151], v[156:159], v[128:131]
	v_mfma_f32_16x16x32_bf16 v[116:119], v[140:143], v[164:167], v[116:119]
	v_mfma_f32_16x16x32_bf16 v[112:115], v[148:151], v[164:167], v[112:115]
	v_mfma_f32_16x16x32_bf16 v[100:103], v[140:143], v[180:183], v[100:103]
	v_mfma_f32_16x16x32_bf16 v[96:99], v[148:151], v[180:183], v[96:99]
	v_mfma_f32_16x16x32_bf16 v[84:87], v[140:143], v[200:203], v[84:87]
	v_mfma_f32_16x16x32_bf16 v[80:83], v[148:151], v[200:203], v[80:83]
	s_setprio 0
	s_barrier
	s_add_i32 s44, 0, 0x14000
	v_lshl_add_u64 v[220:221], s[22:23], 0, v[172:173]
	s_add_i32 s22, s33, s25
	v_add_u32_e32 v0, s44, v185
	s_mov_b32 m0, s22
	ds_read_b128 v[204:207], v0
	ds_read_b128 v[208:211], v0 offset:1024
	ds_read_b128 v[212:215], v0 offset:2048
	ds_read_b128 v[216:219], v0 offset:3072
	global_load_lds_dwordx4 v[220:221], off
	v_lshl_add_u64 v[222:223], v[220:221], 0, s[86:87]
	s_add_i32 m0, s22, 0x2000
	s_nop 0
	global_load_lds_dwordx4 v[222:223], off
	s_barrier
	s_waitcnt lgkmcnt(0)
	s_setprio 3
	s_waitcnt lgkmcnt(0)
	v_mfma_f32_16x16x32_bf16 v[124:127], v[204:207], v[152:155], v[124:127]
	v_mfma_f32_16x16x32_bf16 v[120:123], v[212:215], v[152:155], v[120:123]
	v_mfma_f32_16x16x32_bf16 v[108:111], v[204:207], v[160:163], v[108:111]
	v_mfma_f32_16x16x32_bf16 v[104:107], v[212:215], v[160:163], v[104:107]
	v_mfma_f32_16x16x32_bf16 v[92:95], v[204:207], v[176:179], v[92:95]
	v_mfma_f32_16x16x32_bf16 v[88:91], v[212:215], v[176:179], v[88:91]
	v_mfma_f32_16x16x32_bf16 v[76:79], v[204:207], v[196:199], v[76:79]
	v_mfma_f32_16x16x32_bf16 v[72:75], v[212:215], v[196:199], v[72:75]
	v_mfma_f32_16x16x32_bf16 v[124:127], v[208:211], v[156:159], v[124:127]
	v_mfma_f32_16x16x32_bf16 v[120:123], v[216:219], v[156:159], v[120:123]
	v_mfma_f32_16x16x32_bf16 v[108:111], v[208:211], v[164:167], v[108:111]
	v_mfma_f32_16x16x32_bf16 v[104:107], v[216:219], v[164:167], v[104:107]
	v_mfma_f32_16x16x32_bf16 v[92:95], v[208:211], v[180:183], v[92:95]
	v_mfma_f32_16x16x32_bf16 v[88:91], v[216:219], v[180:183], v[88:91]
	v_mfma_f32_16x16x32_bf16 v[76:79], v[208:211], v[200:203], v[76:79]
	v_mfma_f32_16x16x32_bf16 v[72:75], v[216:219], v[200:203], v[72:75]
	s_setprio 0
	s_mov_b32 m0, s26
	v_lshl_add_u64 v[222:223], s[4:5], 0, v[2:3]
	s_barrier
	ds_read_b128 v[152:155], v195 offset:16384
	ds_read_b128 v[156:159], v195 offset:17408
	ds_read_b128 v[160:163], v195 offset:18432
	ds_read_b128 v[164:167], v195 offset:19456
	ds_read_b128 v[176:179], v195 offset:20480
	ds_read_b128 v[180:183], v195 offset:21504
	ds_read_b128 v[196:199], v195 offset:22528
	ds_read_b128 v[200:203], v195 offset:23552
	global_load_lds_dwordx4 v[222:223], off
	v_lshl_add_u64 v[224:225], v[222:223], 0, s[86:87]
	s_mov_b32 m0, s27
	s_nop 0
	global_load_lds_dwordx4 v[224:225], off
	s_barrier
	s_waitcnt lgkmcnt(0)
	s_setprio 3
	s_waitcnt lgkmcnt(0)
	v_mfma_f32_16x16x32_bf16 v[68:71], v[136:139], v[152:155], v[68:71]
	v_mfma_f32_16x16x32_bf16 v[64:67], v[144:147], v[152:155], v[64:67]
	v_mfma_f32_16x16x32_bf16 v[52:55], v[136:139], v[160:163], v[52:55]
	v_mfma_f32_16x16x32_bf16 v[48:51], v[144:147], v[160:163], v[48:51]
	v_mfma_f32_16x16x32_bf16 v[36:39], v[136:139], v[176:179], v[36:39]
	v_mfma_f32_16x16x32_bf16 v[32:35], v[144:147], v[176:179], v[32:35]
	v_mfma_f32_16x16x32_bf16 v[20:23], v[136:139], v[196:199], v[20:23]
	v_mfma_f32_16x16x32_bf16 v[16:19], v[144:147], v[196:199], v[16:19]
	v_mfma_f32_16x16x32_bf16 v[68:71], v[140:143], v[156:159], v[68:71]
	v_mfma_f32_16x16x32_bf16 v[64:67], v[148:151], v[156:159], v[64:67]
	v_mfma_f32_16x16x32_bf16 v[52:55], v[140:143], v[164:167], v[52:55]
	v_mfma_f32_16x16x32_bf16 v[48:51], v[148:151], v[164:167], v[48:51]
	v_mfma_f32_16x16x32_bf16 v[36:39], v[140:143], v[180:183], v[36:39]
	v_mfma_f32_16x16x32_bf16 v[32:35], v[148:151], v[180:183], v[32:35]
	v_mfma_f32_16x16x32_bf16 v[20:23], v[140:143], v[200:203], v[20:23]
	v_mfma_f32_16x16x32_bf16 v[16:19], v[148:151], v[200:203], v[16:19]
	s_setprio 0
	s_barrier
; #define G_STAGE(bufoff, gbase, o0, h64) do { \
;         __builtin_amdgcn_global_load_lds((const unsigned*)((const char*)(gbase) + (o0)), (LAS unsigned*)(lds + (bufoff) + ldsw), 16, 0, 0); \
;         __builtin_amdgcn_global_load_lds((const unsigned*)((const char*)(gbase) + (h64) + (o0)), (LAS unsigned*)(lds + (bufoff) + ldsw + 8192), 16, 0, 0); } while (0)
; #define G_LDA(dst, b, h) do { _Pragma("unroll") for (int m = 0; m < 4; ++m) _Pragma("unroll") for (int k = 0; k < 2; ++k) dst[m][k] = *(const LAS bf16x8*)(lds + G_SA(b, h) + aoff + m * 2048 + k * 1024); } while (0)
; #define G_LDB(dst, b, h) do { _Pragma("unroll") for (int n = 0; n < 2; ++n) _Pragma("unroll") for (int k = 0; k < 2; ++k) dst[n][k] = *(const LAS bf16x8*)(lds + G_SB(b, h) + boff + n * 2048 + k * 1024); } while (0)
; #define G_WAIT_V(n) asm volatile("s_waitcnt vmcnt(" #n ")" ::: "memory")
; #define G_WAIT_L(n) asm volatile("s_waitcnt lgkmcnt(" #n ")" ::: "memory")
; #define G_BAR __builtin_amdgcn_s_barrier()
; #define G_SCHED __builtin_amdgcn_sched_barrier(0)
;     ...
;             G_STAGE(G_SB(0, 1), b2 + chB, cB0, qB);
;             G_WAIT_V(6); G_BAR; G_MMA(1, 1, At, B1); G_BAR;
;             G_LDB(B0, 1, 0); G_SCHED; G_LDA(At, 1, 0); G_STAGE(G_SA(0, 1), a2 + chA, cA0, qA);
;             G_WAIT_L(8); G_BAR; G_WAIT_L(0); G_MMA(0, 0, At, B0); G_BAR; G_SCHED;
;             G_LDB(B1, 1, 1); G_STAGE(G_SB(1, 0), b3, cB0, qB);
;             G_BAR; G_WAIT_L(0); G_MMA(0, 1, At, B1); G_BAR;
;             G_LDA(At, 1, 1); G_STAGE(G_SA(1, 0), a3, cA0, qA);
;             G_BAR; G_WAIT_L(0); G_MMA(1, 0, At, B0); G_BAR; G_SCHED;
;             G_STAGE(G_SB(1, 1), b3 + chB, cB0, qB);
	s_add_i32 s4, s44, s25
	v_lshl_add_u64 v[136:137], v[220:221], 0, s[88:89]
	s_mov_b32 m0, s4
	s_nop 0
	global_load_lds_dwordx4 v[136:137], off
	v_lshl_add_u64 v[136:137], v[220:221], 0, s[64:65]
	s_add_i32 m0, s4, 0x2000
	s_nop 0
	global_load_lds_dwordx4 v[136:137], off
	s_waitcnt vmcnt(6)
	s_barrier
	s_setprio 3
	v_mfma_f32_16x16x32_bf16 v[60:63], v[204:207], v[152:155], v[60:63]
	v_mfma_f32_16x16x32_bf16 v[56:59], v[212:215], v[152:155], v[56:59]
	v_mfma_f32_16x16x32_bf16 v[44:47], v[204:207], v[160:163], v[44:47]
	v_mfma_f32_16x16x32_bf16 v[40:43], v[212:215], v[160:163], v[40:43]
	v_mfma_f32_16x16x32_bf16 v[28:31], v[204:207], v[176:179], v[28:31]
	v_mfma_f32_16x16x32_bf16 v[24:27], v[212:215], v[176:179], v[24:27]
	v_mfma_f32_16x16x32_bf16 v[12:15], v[204:207], v[196:199], v[12:15]
	v_mfma_f32_16x16x32_bf16 v[8:11], v[212:215], v[196:199], v[8:11]
	v_mfma_f32_16x16x32_bf16 v[60:63], v[208:211], v[156:159], v[60:63]
	v_mfma_f32_16x16x32_bf16 v[56:59], v[216:219], v[156:159], v[56:59]
	v_mfma_f32_16x16x32_bf16 v[44:47], v[208:211], v[164:167], v[44:47]
	v_mfma_f32_16x16x32_bf16 v[40:43], v[216:219], v[164:167], v[40:43]
	v_mfma_f32_16x16x32_bf16 v[28:31], v[208:211], v[180:183], v[28:31]
	v_mfma_f32_16x16x32_bf16 v[24:27], v[216:219], v[180:183], v[24:27]
	v_mfma_f32_16x16x32_bf16 v[12:15], v[208:211], v[200:203], v[12:15]
	v_mfma_f32_16x16x32_bf16 v[8:11], v[216:219], v[200:203], v[8:11]
	s_setprio 0
	s_add_i32 s4, 0, 0x18000
	v_add_u32_e32 v0, s4, v185
	s_barrier
	ds_read_b128 v[136:139], v0
	ds_read_b128 v[140:143], v0 offset:1024
	ds_read_b128 v[144:147], v0 offset:2048
	ds_read_b128 v[148:151], v0 offset:3072
	s_mov_b32 m0, s29
	v_lshl_add_u64 v[204:205], v[222:223], 0, s[88:89]
	ds_read_b128 v[152:155], v195 offset:32768
	ds_read_b128 v[156:159], v195 offset:33792
	ds_read_b128 v[160:163], v195 offset:34816
	ds_read_b128 v[164:167], v195 offset:35840
	ds_read_b128 v[176:179], v195 offset:36864
	ds_read_b128 v[180:183], v195 offset:37888
	ds_read_b128 v[196:199], v195 offset:38912
	ds_read_b128 v[200:203], v195 offset:39936
	global_load_lds_dwordx4 v[204:205], off
	v_lshl_add_u64 v[204:205], v[222:223], 0, s[64:65]
	s_mov_b32 m0, s30
	s_nop 0
	global_load_lds_dwordx4 v[204:205], off
	s_waitcnt lgkmcnt(8)
	s_barrier
	s_waitcnt lgkmcnt(0)
	s_setprio 3
	s_waitcnt lgkmcnt(0)
	v_mfma_f32_16x16x32_bf16 v[132:135], v[136:139], v[152:155], v[132:135]
	v_mfma_f32_16x16x32_bf16 v[128:131], v[144:147], v[152:155], v[128:131]
	v_mfma_f32_16x16x32_bf16 v[116:119], v[136:139], v[160:163], v[116:119]
	v_mfma_f32_16x16x32_bf16 v[112:115], v[144:147], v[160:163], v[112:115]
	v_mfma_f32_16x16x32_bf16 v[100:103], v[136:139], v[176:179], v[100:103]
	v_mfma_f32_16x16x32_bf16 v[96:99], v[144:147], v[176:179], v[96:99]
	v_mfma_f32_16x16x32_bf16 v[84:87], v[136:139], v[196:199], v[84:87]
	v_mfma_f32_16x16x32_bf16 v[80:83], v[144:147], v[196:199], v[80:83]
	v_mfma_f32_16x16x32_bf16 v[132:135], v[140:143], v[156:159], v[132:135]
	v_mfma_f32_16x16x32_bf16 v[128:131], v[148:151], v[156:159], v[128:131]
	v_mfma_f32_16x16x32_bf16 v[116:119], v[140:143], v[164:167], v[116:119]
	v_mfma_f32_16x16x32_bf16 v[112:115], v[148:151], v[164:167], v[112:115]
	v_mfma_f32_16x16x32_bf16 v[100:103], v[140:143], v[180:183], v[100:103]
	v_mfma_f32_16x16x32_bf16 v[96:99], v[148:151], v[180:183], v[96:99]
	v_mfma_f32_16x16x32_bf16 v[84:87], v[140:143], v[200:203], v[84:87]
	v_mfma_f32_16x16x32_bf16 v[80:83], v[148:151], v[200:203], v[80:83]
	s_setprio 0
	s_barrier
	s_add_i32 s5, 0, 0x1c000
	s_add_i32 s4, s4, s25
	v_add_u32_e32 v0, s5, v185
	v_lshl_add_u64 v[224:225], v[220:221], 0, s[46:47]
	s_mov_b32 m0, s4
	ds_read_b128 v[204:207], v0
	ds_read_b128 v[208:211], v0 offset:1024
	ds_read_b128 v[212:215], v0 offset:2048
	ds_read_b128 v[216:219], v0 offset:3072
	global_load_lds_dwordx4 v[224:225], off
	v_lshl_add_u64 v[224:225], v[220:221], 0, s[66:67]
	s_add_i32 m0, s4, 0x2000
	s_nop 0
	global_load_lds_dwordx4 v[224:225], off
	s_barrier
; #define G_STAGE(bufoff, gbase, o0, h64) do { \
;         __builtin_amdgcn_global_load_lds((const unsigned*)((const char*)(gbase) + (o0)), (LAS unsigned*)(lds + (bufoff) + ldsw), 16, 0, 0); \
;         __builtin_amdgcn_global_load_lds((const unsigned*)((const char*)(gbase) + (h64) + (o0)), (LAS unsigned*)(lds + (bufoff) + ldsw + 8192), 16, 0, 0); } while (0)
; #define G_LDA(dst, b, h) do { _Pragma("unroll") for (int m = 0; m < 4; ++m) _Pragma("unroll") for (int k = 0; k < 2; ++k) dst[m][k] = *(const LAS bf16x8*)(lds + G_SA(b, h) + aoff + m * 2048 + k * 1024); } while (0)
; #define G_WAIT_V(n) asm volatile("s_waitcnt vmcnt(" #n ")" ::: "memory")
; #define G_WAIT_L(n) asm volatile("s_waitcnt lgkmcnt(" #n ")" ::: "memory")
; #define G_BAR __builtin_amdgcn_s_barrier()
; #define G_SCHED __builtin_amdgcn_sched_barrier(0)
;     ...
;             G_LDA(At, 1, 1); G_STAGE(G_SA(1, 0), a3, cA0, qA);
;             G_BAR; G_WAIT_L(0); G_MMA(1, 0, At, B0); G_BAR; G_SCHED;
;             G_STAGE(G_SB(1, 1), b3 + chB, cB0, qB);
;             G_WAIT_V(6); G_BAR; G_MMA(1, 1, At, B1); G_BAR;
;         }
;         E.template run<cs.kind>(acc, cur, tid);
;         if (!has_next) break;
	s_waitcnt lgkmcnt(0)
	s_setprio 3
	s_waitcnt lgkmcnt(0)
	v_mfma_f32_16x16x32_bf16 v[124:127], v[204:207], v[152:155], v[124:127]
	v_mfma_f32_16x16x32_bf16 v[120:123], v[212:215], v[152:155], v[120:123]
	v_mfma_f32_16x16x32_bf16 v[108:111], v[204:207], v[160:163], v[108:111]
	v_mfma_f32_16x16x32_bf16 v[104:107], v[212:215], v[160:163], v[104:107]
	v_mfma_f32_16x16x32_bf16 v[92:95], v[204:207], v[176:179], v[92:95]
	v_mfma_f32_16x16x32_bf16 v[88:91], v[212:215], v[176:179], v[88:91]
	v_mfma_f32_16x16x32_bf16 v[76:79], v[204:207], v[196:199], v[76:79]
	v_mfma_f32_16x16x32_bf16 v[72:75], v[212:215], v[196:199], v[72:75]
	v_mfma_f32_16x16x32_bf16 v[124:127], v[208:211], v[156:159], v[124:127]
	v_mfma_f32_16x16x32_bf16 v[120:123], v[216:219], v[156:159], v[120:123]
	v_mfma_f32_16x16x32_bf16 v[108:111], v[208:211], v[164:167], v[108:111]
	v_mfma_f32_16x16x32_bf16 v[104:107], v[216:219], v[164:167], v[104:107]
	v_mfma_f32_16x16x32_bf16 v[92:95], v[208:211], v[180:183], v[92:95]
	v_mfma_f32_16x16x32_bf16 v[88:91], v[216:219], v[180:183], v[88:91]
	v_mfma_f32_16x16x32_bf16 v[76:79], v[208:211], v[200:203], v[76:79]
	v_mfma_f32_16x16x32_bf16 v[72:75], v[216:219], v[200:203], v[72:75]
	s_setprio 0
	s_mov_b32 m0, s31
	v_lshl_add_u64 v[224:225], v[222:223], 0, s[46:47]
	s_barrier
	ds_read_b128 v[152:155], v195 offset:49152
	ds_read_b128 v[156:159], v195 offset:50176
	ds_read_b128 v[160:163], v195 offset:51200
	ds_read_b128 v[164:167], v195 offset:52224
	ds_read_b128 v[176:179], v195 offset:53248
	ds_read_b128 v[180:183], v195 offset:54272
	ds_read_b128 v[196:199], v195 offset:55296
	ds_read_b128 v[200:203], v195 offset:56320
	global_load_lds_dwordx4 v[224:225], off
	v_lshl_add_u64 v[222:223], v[222:223], 0, s[66:67]
	s_mov_b32 m0, s34
	s_nop 0
	global_load_lds_dwordx4 v[222:223], off
	s_barrier
	s_waitcnt lgkmcnt(0)
	s_setprio 3
	s_waitcnt lgkmcnt(0)
	v_mfma_f32_16x16x32_bf16 v[68:71], v[136:139], v[152:155], v[68:71]
	v_mfma_f32_16x16x32_bf16 v[64:67], v[144:147], v[152:155], v[64:67]
	v_mfma_f32_16x16x32_bf16 v[52:55], v[136:139], v[160:163], v[52:55]
	v_mfma_f32_16x16x32_bf16 v[48:51], v[144:147], v[160:163], v[48:51]
	v_mfma_f32_16x16x32_bf16 v[36:39], v[136:139], v[176:179], v[36:39]
	v_mfma_f32_16x16x32_bf16 v[32:35], v[144:147], v[176:179], v[32:35]
	v_mfma_f32_16x16x32_bf16 v[20:23], v[136:139], v[196:199], v[20:23]
	v_mfma_f32_16x16x32_bf16 v[16:19], v[144:147], v[196:199], v[16:19]
	v_mfma_f32_16x16x32_bf16 v[68:71], v[140:143], v[156:159], v[68:71]
	v_mfma_f32_16x16x32_bf16 v[64:67], v[148:151], v[156:159], v[64:67]
	v_mfma_f32_16x16x32_bf16 v[52:55], v[140:143], v[164:167], v[52:55]
	v_mfma_f32_16x16x32_bf16 v[48:51], v[148:151], v[164:167], v[48:51]
	v_mfma_f32_16x16x32_bf16 v[36:39], v[140:143], v[180:183], v[36:39]
	v_mfma_f32_16x16x32_bf16 v[32:35], v[148:151], v[180:183], v[32:35]
	v_mfma_f32_16x16x32_bf16 v[20:23], v[140:143], v[200:203], v[20:23]
	v_mfma_f32_16x16x32_bf16 v[16:19], v[148:151], v[200:203], v[16:19]
	s_setprio 0
	s_barrier
	s_add_i32 s4, s5, s25
	v_lshl_add_u64 v[136:137], v[220:221], 0, s[52:53]
	s_mov_b32 m0, s4
	s_nop 0
	global_load_lds_dwordx4 v[136:137], off
	v_lshl_add_u64 v[136:137], v[220:221], 0, s[54:55]
	s_add_i32 m0, s4, 0x2000
	s_nop 0
	global_load_lds_dwordx4 v[136:137], off
	s_waitcnt vmcnt(6)
	s_barrier
	s_setprio 3
	v_mfma_f32_16x16x32_bf16 v[60:63], v[204:207], v[152:155], v[60:63]
	v_mfma_f32_16x16x32_bf16 v[56:59], v[212:215], v[152:155], v[56:59]
	v_mfma_f32_16x16x32_bf16 v[44:47], v[204:207], v[160:163], v[44:47]
	v_mfma_f32_16x16x32_bf16 v[40:43], v[212:215], v[160:163], v[40:43]
	v_mfma_f32_16x16x32_bf16 v[28:31], v[204:207], v[176:179], v[28:31]
	v_mfma_f32_16x16x32_bf16 v[24:27], v[212:215], v[176:179], v[24:27]
	v_mfma_f32_16x16x32_bf16 v[12:15], v[204:207], v[196:199], v[12:15]
	v_mfma_f32_16x16x32_bf16 v[8:11], v[212:215], v[196:199], v[8:11]
	v_mfma_f32_16x16x32_bf16 v[60:63], v[208:211], v[156:159], v[60:63]
	v_mfma_f32_16x16x32_bf16 v[56:59], v[216:219], v[156:159], v[56:59]
	v_mfma_f32_16x16x32_bf16 v[44:47], v[208:211], v[164:167], v[44:47]
	v_mfma_f32_16x16x32_bf16 v[40:43], v[216:219], v[164:167], v[40:43]
	v_mfma_f32_16x16x32_bf16 v[28:31], v[208:211], v[180:183], v[28:31]
	v_mfma_f32_16x16x32_bf16 v[24:27], v[216:219], v[180:183], v[24:27]
	v_mfma_f32_16x16x32_bf16 v[12:15], v[208:211], v[200:203], v[12:15]
	v_mfma_f32_16x16x32_bf16 v[8:11], v[216:219], v[200:203], v[8:11]
	s_setprio 0
	s_add_i32 s21, s21, 2
	s_add_u32 s2, s2, 0x100
	s_addc_u32 s3, s3, 0
	s_add_u32 s6, s6, 0x100
	s_addc_u32 s7, s7, 0
	s_cmp_gt_u32 s21, 41
	s_cbranch_scc0 .Ldb_FFO_cont
	v_readfirstlane_b32 s101, v186
	s_cmpk_gt_u32 s101, 0xff
	s_cbranch_scc1 .Ldb_FFO_exit
	s_barrier
	s_branch .Ldb_FFO_exit

; __device__ __forceinline__ u32x4 pack8(const f32x4 a, const f32x4 b) { u32x4 w; w.x = cvt_pk_bf16(a[0], a[1]); w.y = cvt_pk_bf16(a[2], a[3]); w.z = cvt_pk_bf16(b[0], b[1]); w.w = cvt_pk_bf16(b[2], b[3]); return w; }
; __device__ __forceinline__ void unpack8(const u32x4 w, f32x4& a, f32x4& b) { a[0] = bf_lo(w.x); a[1] = bf_hi(w.x); a[2] = bf_lo(w.y); a[3] = bf_hi(w.y); b[0] = bf_lo(w.z); b[1] = bf_hi(w.z); b[2] = bf_lo(w.w); b[3] = bf_hi(w.w); }
; #define MEMFENCE asm volatile("" ::: "memory")
; #define XLOAD(gi, bufi) do { _Pragma("unroll") for (int ml = 0; ml < 2; ++ml) { const int m_ = ((gi) & 1) * 2 + ml; int row_ = rbase + ((gi) >> 1) * 128 + m_ * 16; asm volatile("" : "+v"(row_)); \
;                 _Pragma("unroll") for (int bj = 0; bj < 2; ++bj) xv[bufi][ml][bj] = *(const u32x4*)(xsrc + (size_t)row_ * 1024 + u.pn * 256 + bj * 128 + cl); } } while (0)
;     template <int KIND> __device__ __forceinline__ void run(f32x4 (&acc)[2][2][4][2], const Unit& u, int tid_in) const {
;     ...
;         if constexpr (KIND == K_XADD) {
;             const bf16_t* xsrc = xb0; bf16_t* xbo = (u.aux ? mg : xb0); float* sso = (u.aux ? ssq2 : ssq1);
;             u32x4 xv[2][2][2];
;     ...
;             XLOAD(0, 0);
; #pragma unroll
;             for (int gi = 0; gi < 4; ++gi) { const int ai = gi >> 1, mh = gi & 1, bufi = gi & 1;
;                 if (gi < 3) XLOAD(gi + 1, (gi + 1) & 1);
; #pragma unroll
;                 for (int ml = 0; ml < 2; ++ml) { const int m = mh * 2 + ml; int row = rbase + ai * 128 + m * 16; asm volatile("" : "+v"(row)); float ss = 0.f;
; #pragma unroll
;                     for (int bj = 0; bj < 2; ++bj) { const size_t off = (size_t)row * 1024 + u.pn * 256 + bj * 128 + cl; f32x4 x0, x1; unpack8(xv[bufi][ml][bj], x0, x1);
;                         const f32x4 o0 = x0 + acc[ai][bj][m][0], o1 = x1 + acc[ai][bj][m][1];
;                         *(u32x4*)(xbo + off) = pack8(o0, o1);
;                         ss += (o0[0] * o0[0] + o0[1] * o0[1]) + (o0[2] * o0[2] + o0[3] * o0[3]) + (o1[0] * o1[0] + o1[1] * o1[1]) + (o1[2] * o1[2] + o1[3] * o1[3]); }
;                     ss += __shfl_xor(ss, 16); ss += __shfl_xor(ss, 32);
;                     if (fq == 0) sso[((size_t)u.pn * T_TOK + row) * 4 + wc] = ss; }
;                 MEMFENCE; }
.Ldb_FFO_exit:
	v_mov_b32_e32 v0, v184
	s_lshl_b32 s3, s20, 8
	v_readfirstlane_b32 s2, v0
	s_bfe_u32 s33, s2, 0x20006
	s_ashr_i32 s2, s2, 2
	s_andn2_b32 s2, s2, 63
	s_add_i32 s2, s2, s3
	v_and_or_b32 v196, v0, 15, s2
	v_mov_b32_e32 v136, v196
	v_bfe_u32 v138, v0, 4, 2
	s_lshl_b32 s2, s10, 8
	v_lshlrev_b32_e32 v0, 3, v138
	v_ashrrev_i32_e32 v137, 31, v136
	s_ashr_i32 s3, s2, 31
	v_lshlrev_b64 v[136:137], 11, v[136:137]
	v_lshl_or_b32 v0, s33, 5, v0
	s_lshl_b64 s[22:23], s[2:3], 1
	v_lshl_add_u64 v[136:137], s[12:13], 0, v[136:137]
	v_lshl_add_u64 v[136:137], v[136:137], 0, s[22:23]
	v_lshlrev_b32_e32 v0, 1, v0
	v_lshl_add_u64 v[136:137], v[136:137], 0, v[0:1]
	global_load_dwordx4 v[164:167], v[136:137], off
	global_load_dwordx4 v[160:163], v[136:137], off offset:256
	v_or_b32_e32 v180, 16, v196
	v_mov_b32_e32 v136, v180
	v_or_b32_e32 v178, 32, v196
	v_ashrrev_i32_e32 v137, 31, v136
	v_lshlrev_b64 v[136:137], 11, v[136:137]
	v_lshl_add_u64 v[136:137], s[12:13], 0, v[136:137]
	v_lshl_add_u64 v[136:137], v[136:137], 0, s[22:23]
	v_lshl_add_u64 v[136:137], v[136:137], 0, v[0:1]
	global_load_dwordx4 v[156:159], v[136:137], off
	global_load_dwordx4 v[152:155], v[136:137], off offset:256
	v_mov_b32_e32 v136, v178
	v_or_b32_e32 v176, 48, v196
	v_ashrrev_i32_e32 v137, 31, v136
	v_lshlrev_b64 v[136:137], 11, v[136:137]
	v_lshl_add_u64 v[136:137], s[12:13], 0, v[136:137]
	v_lshl_add_u64 v[136:137], v[136:137], 0, s[22:23]
	v_lshl_add_u64 v[136:137], v[136:137], 0, v[0:1]
	global_load_dwordx4 v[148:151], v[136:137], off
	global_load_dwordx4 v[140:143], v[136:137], off offset:256
	v_mov_b32_e32 v136, v176
	v_cmp_eq_u32_e32 vcc, 0, v138
	v_ashrrev_i32_e32 v137, 31, v136
	v_lshlrev_b64 v[136:137], 11, v[136:137]
	v_lshl_add_u64 v[136:137], s[12:13], 0, v[136:137]
	v_lshl_add_u64 v[136:137], v[136:137], 0, s[22:23]
	v_lshl_add_u64 v[136:137], v[136:137], 0, v[0:1]
	global_load_dwordx4 v[144:147], v[136:137], off
	s_nop 0
	global_load_dwordx4 v[136:139], v[136:137], off offset:256
	v_mov_b32_e32 v182, v196
	s_cmp_eq_u32 s11, 0
	s_cselect_b32 s21, s13, s41
	v_ashrrev_i32_e32 v183, 31, v182
	s_cselect_b32 s20, s12, s40
	v_lshlrev_b64 v[198:199], 11, v[182:183]
	v_lshl_add_u64 v[198:199], s[20:21], 0, v[198:199]
	v_lshl_add_u64 v[198:199], v[198:199], 0, s[22:23]
	v_lshl_add_u64 v[198:199], v[198:199], 0, v[0:1]
	s_mov_b32 s4, 0xaa00000
	s_cselect_b32 s4, s4, 0xac00000
	s_add_u32 s51, s8, s4
	s_addc_u32 s52, s9, 0
	s_waitcnt vmcnt(0)
	v_lshlrev_b32_e32 v200, 16, v164
	v_and_b32_e32 v201, 0xffff0000, v164
	v_lshlrev_b32_e32 v164, 16, v165
	v_and_b32_e32 v165, 0xffff0000, v165
	v_lshlrev_b32_e32 v202, 16, v166
	v_and_b32_e32 v203, 0xffff0000, v166
	v_lshlrev_b32_e32 v166, 16, v167
	v_and_b32_e32 v167, 0xffff0000, v167
	v_pk_add_f32 v[134:135], v[134:135], v[164:165]
	v_pk_add_f32 v[132:133], v[132:133], v[200:201]
	v_pk_add_f32 v[164:165], v[130:131], v[166:167]
	v_pk_add_f32 v[166:167], v[128:129], v[202:203]
	v_cvt_pk_bf16_f32 v128, v132, v133
	v_cvt_pk_bf16_f32 v129, v134, v135
	s_nop 0
	v_cvt_pk_bf16_f32 v130, v166, v167
	v_cvt_pk_bf16_f32 v131, v164, v165
	global_store_dwordx4 v[198:199], v[128:131], off
	s_nop 1
	v_mul_f32_e32 v128, v133, v133
	v_mul_f32_e32 v129, v135, v135
	v_fmac_f32_e32 v128, v132, v132
	v_fmac_f32_e32 v129, v134, v134
	v_add_f32_e32 v128, v128, v129
	v_mul_f32_e32 v129, v167, v167
	v_fmac_f32_e32 v129, v166, v166
	v_add_f32_e32 v128, v129, v128
	v_mul_f32_e32 v129, v165, v165
	v_fmac_f32_e32 v129, v164, v164
	v_add_f32_e32 v164, v129, v128
	v_lshlrev_b32_e32 v128, 16, v160
	v_and_b32_e32 v129, 0xffff0000, v160
	v_lshlrev_b32_e32 v130, 16, v161
	v_and_b32_e32 v131, 0xffff0000, v161
	v_lshlrev_b32_e32 v132, 16, v162
	v_and_b32_e32 v133, 0xffff0000, v162
	v_lshlrev_b32_e32 v134, 16, v163
	v_and_b32_e32 v135, 0xffff0000, v163
	v_pk_add_f32 v[126:127], v[126:127], v[130:131]
	v_pk_add_f32 v[124:125], v[124:125], v[128:129]
	v_pk_add_f32 v[130:131], v[120:121], v[132:133]
	v_cvt_pk_bf16_f32 v120, v124, v125
	v_cvt_pk_bf16_f32 v121, v126, v127
	v_pk_add_f32 v[128:129], v[122:123], v[134:135]
	v_cvt_pk_bf16_f32 v122, v130, v131
	s_nop 0
	v_cvt_pk_bf16_f32 v123, v128, v129
	global_store_dwordx4 v[198:199], v[120:123], off offset:256
	s_nop 1
	v_mul_f32_e32 v120, v125, v125
	v_mul_f32_e32 v121, v127, v127
	v_fmac_f32_e32 v120, v124, v124
	v_fmac_f32_e32 v121, v126, v126
	v_add_f32_e32 v120, v120, v121
	v_mul_f32_e32 v121, v131, v131
	v_fmac_f32_e32 v121, v130, v130
	v_add_f32_e32 v120, v121, v120
	v_mul_f32_e32 v121, v129, v129
	v_fmac_f32_e32 v121, v128, v128
	v_add_f32_e32 v120, v121, v120
	v_xor_b32_e32 v121, 16, v190
	v_cmp_lt_i32_e64 s[6:7], v121, v192
	v_add_f32_e32 v120, v164, v120
	s_nop 0
	v_cndmask_b32_e64 v121, v190, v121, s[6:7]
	v_lshlrev_b32_e32 v124, 2, v121
	ds_bpermute_b32 v121, v124, v120
	s_waitcnt lgkmcnt(0)
	v_add_f32_e32 v120, v120, v121
	v_xor_b32_e32 v121, 32, v190
	v_cmp_lt_i32_e64 s[6:7], v121, v192
	s_nop 1
	v_cndmask_b32_e64 v121, v190, v121, s[6:7]
	v_lshlrev_b32_e32 v125, 2, v121
	ds_bpermute_b32 v121, v125, v120
	s_and_saveexec_b64 s[6:7], vcc
	s_cbranch_execz .LBB0_1188
	s_ashr_i32 s11, s10, 31
	s_lshl_b64 s[4:5], s[10:11], 19
	s_add_u32 s4, s51, s4
	s_addc_u32 s5, s52, s5
	s_waitcnt lgkmcnt(0)
	v_add_f32_e32 v122, v120, v121
	v_lshl_add_u64 v[120:121], v[182:183], 4, s[4:5]
	s_lshl_b32 s74, s33, 2
	v_lshl_add_u64 v[120:121], v[120:121], 0, s[74:75]
	global_store_dword v[120:121], v122, off

;     ...
;         if (!has_next) break;
;         if (!(cs.kind == K_MG_B && cur.aux < 2))
; #pragma unroll
;         for (int a = 0; a < 2; ++a)
; #pragma unroll
;             for (int b = 0; b < 2; ++b)
; #pragma unroll
;                 for (int m = 0; m < 4; ++m)
; #pragma unroll
;                     for (int n = 0; n < 2; ++n) acc[a][b][m][n] = (f32x4){0.f, 0.f, 0.f, 0.f};
;         cur = nxt; cA = nA; cB = nB; ++ui;
.Ldb_PLE1_nob:
	s_and_b64 vcc, exec, s[14:15]
	s_mov_b32 s33, s17
	s_mov_b32 s6, s52
	s_mov_b32 s7, s16
	s_mov_b64 s[22:23], s[20:21]
	s_mov_b64 s[24:25], s[18:19]
	s_cbranch_vccnz .LBB0_1300

; #define G_STAGE(bufoff, gbase, o0, h64) do { \
;         __builtin_amdgcn_global_load_lds((const unsigned*)((const char*)(gbase) + (o0)), (LAS unsigned*)(lds + (bufoff) + ldsw), 16, 0, 0); \
;         __builtin_amdgcn_global_load_lds((const unsigned*)((const char*)(gbase) + (h64) + (o0)), (LAS unsigned*)(lds + (bufoff) + ldsw + 8192), 16, 0, 0); } while (0)
; #define G_LDA(dst, b, h) do { _Pragma("unroll") for (int m = 0; m < 4; ++m) _Pragma("unroll") for (int k = 0; k < 2; ++k) dst[m][k] = *(const LAS bf16x8*)(lds + G_SA(b, h) + aoff + m * 2048 + k * 1024); } while (0)
; #define G_LDB(dst, b, h) do { _Pragma("unroll") for (int n = 0; n < 2; ++n) _Pragma("unroll") for (int k = 0; k < 2; ++k) dst[n][k] = *(const LAS bf16x8*)(lds + G_SB(b, h) + boff + n * 2048 + k * 1024); } while (0)
; #define G_WAIT_L(n) asm volatile("s_waitcnt lgkmcnt(" #n ")" ::: "memory")
; #define G_BAR __builtin_amdgcn_s_barrier()
; #define G_SCHED __builtin_amdgcn_sched_barrier(0)
;     ...
;         for (int t = 0; t < nt; t += 2) {
;             const bool last = (t == nt - 2);
;             const char* a1 = cA + (size_t)(t + 1) * ckA;
;             const char* a2 = last ? nA : cA + (size_t)(t + 2) * ckA; const char* b2 = last ? nB : cB + (size_t)(t + 2) * kB;
;             const char* a3 = a2 + ckA; const char* b3 = b2 + kB;
;             G_LDB(B0, 0, 0); G_SCHED; G_LDA(At, 0, 0); G_STAGE(G_SA(1, 1), a1 + chA, cA0, qA);
;             G_WAIT_L(8); G_BAR; G_WAIT_L(0); G_MMA(0, 0, At, B0); G_BAR; G_SCHED;
;             G_LDB(B1, 0, 1); G_STAGE(G_SB(0, 0), b2, cB0, qB);
;             G_BAR; G_WAIT_L(0); G_MMA(0, 1, At, B1); G_BAR;
;             G_LDA(At, 0, 1); G_STAGE(G_SA(0, 0), a2, cA0, qA);
;             G_BAR; G_WAIT_L(0); G_MMA(1, 0, At, B0); G_BAR; G_SCHED;
.LBB0_1283:
	s_add_u32 s4, s2, 0xfffc0080
	s_addc_u32 s5, s3, -1
	s_add_i32 s25, 0, 0x10000
	v_add_u32_e32 v0, s25, v181
	ds_read_b128 v[136:139], v0
	ds_read_b128 v[140:143], v0 offset:1024
	ds_read_b128 v[144:147], v0 offset:2048
	ds_read_b128 v[148:151], v0 offset:3072
	s_cmp_eq_u32 s24, 12
	s_cselect_b32 s5, s19, s5
	s_cselect_b32 s4, s18, s4
	s_cselect_b32 s41, s21, s23
	s_cselect_b32 s40, s20, s22
	v_lshl_add_u64 v[184:185], s[2:3], 0, v[158:159]
	s_add_i32 m0, s29, 0xc000
	ds_read_b128 v[152:155], v182
	ds_read_b128 v[160:163], v182 offset:1024
	ds_read_b128 v[164:167], v182 offset:2048
	ds_read_b128 v[172:175], v182 offset:3072
	ds_read_b128 v[176:179], v182 offset:4096
	ds_read_b128 v[196:199], v182 offset:5120
	ds_read_b128 v[200:203], v182 offset:6144
	ds_read_b128 v[204:207], v182 offset:7168
	global_load_lds_dwordx4 v[184:185], off
	v_lshl_add_u64 v[184:185], v[184:185], 0, s[0:1]
	s_add_i32 m0, s29, 0xe000
	s_nop 0
	global_load_lds_dwordx4 v[184:185], off
	s_waitcnt lgkmcnt(8)
	s_barrier
	s_waitcnt lgkmcnt(0)
	s_setprio 3
	s_waitcnt lgkmcnt(0)
	v_mfma_f32_16x16x32_bf16 v[132:135], v[136:139], v[152:155], v[132:135]
	v_mfma_f32_16x16x32_bf16 v[128:131], v[144:147], v[152:155], v[128:131]
	v_mfma_f32_16x16x32_bf16 v[116:119], v[136:139], v[164:167], v[116:119]
	v_mfma_f32_16x16x32_bf16 v[112:115], v[144:147], v[164:167], v[112:115]
	v_mfma_f32_16x16x32_bf16 v[100:103], v[136:139], v[176:179], v[100:103]
	v_mfma_f32_16x16x32_bf16 v[96:99], v[144:147], v[176:179], v[96:99]
	v_mfma_f32_16x16x32_bf16 v[84:87], v[136:139], v[200:203], v[84:87]
	v_mfma_f32_16x16x32_bf16 v[80:83], v[144:147], v[200:203], v[80:83]
	v_mfma_f32_16x16x32_bf16 v[132:135], v[140:143], v[160:163], v[132:135]
	v_mfma_f32_16x16x32_bf16 v[128:131], v[148:151], v[160:163], v[128:131]
	v_mfma_f32_16x16x32_bf16 v[116:119], v[140:143], v[172:175], v[116:119]
	v_mfma_f32_16x16x32_bf16 v[112:115], v[148:151], v[172:175], v[112:115]
	v_mfma_f32_16x16x32_bf16 v[100:103], v[140:143], v[196:199], v[100:103]
	v_mfma_f32_16x16x32_bf16 v[96:99], v[148:151], v[196:199], v[96:99]
	v_mfma_f32_16x16x32_bf16 v[84:87], v[140:143], v[204:207], v[84:87]
	v_mfma_f32_16x16x32_bf16 v[80:83], v[148:151], v[204:207], v[80:83]
	s_setprio 0
	s_barrier
	s_add_i32 s44, 0, 0x14000
	s_add_i32 s25, s25, s27
	v_add_u32_e32 v0, s44, v181
	v_lshl_add_u64 v[184:185], s[40:41], 0, v[156:157]
	s_mov_b32 m0, s25
	ds_read_b128 v[208:211], v0
	ds_read_b128 v[212:215], v0 offset:1024
	ds_read_b128 v[216:219], v0 offset:2048
	ds_read_b128 v[220:223], v0 offset:3072
	global_load_lds_dwordx4 v[184:185], off
	v_lshl_add_u64 v[224:225], v[184:185], 0, s[0:1]
	s_add_i32 m0, s25, 0x2000
	s_nop 0
	global_load_lds_dwordx4 v[224:225], off
	s_barrier
	s_waitcnt lgkmcnt(0)
	s_setprio 3
	s_waitcnt lgkmcnt(0)
	v_mfma_f32_16x16x32_bf16 v[124:127], v[208:211], v[152:155], v[124:127]
	v_mfma_f32_16x16x32_bf16 v[120:123], v[216:219], v[152:155], v[120:123]
	v_mfma_f32_16x16x32_bf16 v[108:111], v[208:211], v[164:167], v[108:111]
	v_mfma_f32_16x16x32_bf16 v[104:107], v[216:219], v[164:167], v[104:107]
	v_mfma_f32_16x16x32_bf16 v[92:95], v[208:211], v[176:179], v[92:95]
	v_mfma_f32_16x16x32_bf16 v[88:91], v[216:219], v[176:179], v[88:91]
	v_mfma_f32_16x16x32_bf16 v[76:79], v[208:211], v[200:203], v[76:79]
	v_mfma_f32_16x16x32_bf16 v[72:75], v[216:219], v[200:203], v[72:75]
	v_mfma_f32_16x16x32_bf16 v[124:127], v[212:215], v[160:163], v[124:127]
	v_mfma_f32_16x16x32_bf16 v[120:123], v[220:223], v[160:163], v[120:123]
	v_mfma_f32_16x16x32_bf16 v[108:111], v[212:215], v[172:175], v[108:111]
	v_mfma_f32_16x16x32_bf16 v[104:107], v[220:223], v[172:175], v[104:107]
	v_mfma_f32_16x16x32_bf16 v[92:95], v[212:215], v[196:199], v[92:95]
	v_mfma_f32_16x16x32_bf16 v[88:91], v[220:223], v[196:199], v[88:91]
	v_mfma_f32_16x16x32_bf16 v[76:79], v[212:215], v[204:207], v[76:79]
	v_mfma_f32_16x16x32_bf16 v[72:75], v[220:223], v[204:207], v[72:75]
	s_setprio 0
	s_mov_b32 m0, s29
	v_lshl_add_u64 v[224:225], s[4:5], 0, v[2:3]
	s_barrier
	ds_read_b128 v[152:155], v182 offset:16384
	ds_read_b128 v[160:163], v182 offset:17408
	ds_read_b128 v[164:167], v182 offset:18432
	ds_read_b128 v[172:175], v182 offset:19456
	ds_read_b128 v[176:179], v182 offset:20480
	ds_read_b128 v[196:199], v182 offset:21504
	ds_read_b128 v[200:203], v182 offset:22528
	ds_read_b128 v[204:207], v182 offset:23552
	global_load_lds_dwordx4 v[224:225], off
	v_lshl_add_u64 v[226:227], v[224:225], 0, s[0:1]
	s_mov_b32 m0, s30
	s_nop 0
	global_load_lds_dwordx4 v[226:227], off
	s_barrier
	s_waitcnt lgkmcnt(0)
	s_setprio 3
	s_waitcnt lgkmcnt(0)
	v_mfma_f32_16x16x32_bf16 v[68:71], v[136:139], v[152:155], v[68:71]
	v_mfma_f32_16x16x32_bf16 v[64:67], v[144:147], v[152:155], v[64:67]
	v_mfma_f32_16x16x32_bf16 v[52:55], v[136:139], v[164:167], v[52:55]
	v_mfma_f32_16x16x32_bf16 v[48:51], v[144:147], v[164:167], v[48:51]
	v_mfma_f32_16x16x32_bf16 v[36:39], v[136:139], v[176:179], v[36:39]
	v_mfma_f32_16x16x32_bf16 v[32:35], v[144:147], v[176:179], v[32:35]
	v_mfma_f32_16x16x32_bf16 v[20:23], v[136:139], v[200:203], v[20:23]
	v_mfma_f32_16x16x32_bf16 v[16:19], v[144:147], v[200:203], v[16:19]
	v_mfma_f32_16x16x32_bf16 v[68:71], v[140:143], v[160:163], v[68:71]
	v_mfma_f32_16x16x32_bf16 v[64:67], v[148:151], v[160:163], v[64:67]
	v_mfma_f32_16x16x32_bf16 v[52:55], v[140:143], v[172:175], v[52:55]
	v_mfma_f32_16x16x32_bf16 v[48:51], v[148:151], v[172:175], v[48:51]
	v_mfma_f32_16x16x32_bf16 v[36:39], v[140:143], v[196:199], v[36:39]
	v_mfma_f32_16x16x32_bf16 v[32:35], v[148:151], v[196:199], v[32:35]
	v_mfma_f32_16x16x32_bf16 v[20:23], v[140:143], v[204:207], v[20:23]
	v_mfma_f32_16x16x32_bf16 v[16:19], v[148:151], v[204:207], v[16:19]
	s_setprio 0
	s_barrier
; #define G_STAGE(bufoff, gbase, o0, h64) do { \
;         __builtin_amdgcn_global_load_lds((const unsigned*)((const char*)(gbase) + (o0)), (LAS unsigned*)(lds + (bufoff) + ldsw), 16, 0, 0); \
;         __builtin_amdgcn_global_load_lds((const unsigned*)((const char*)(gbase) + (h64) + (o0)), (LAS unsigned*)(lds + (bufoff) + ldsw + 8192), 16, 0, 0); } while (0)
; #define G_LDA(dst, b, h) do { _Pragma("unroll") for (int m = 0; m < 4; ++m) _Pragma("unroll") for (int k = 0; k < 2; ++k) dst[m][k] = *(const LAS bf16x8*)(lds + G_SA(b, h) + aoff + m * 2048 + k * 1024); } while (0)
; #define G_LDB(dst, b, h) do { _Pragma("unroll") for (int n = 0; n < 2; ++n) _Pragma("unroll") for (int k = 0; k < 2; ++k) dst[n][k] = *(const LAS bf16x8*)(lds + G_SB(b, h) + boff + n * 2048 + k * 1024); } while (0)
; #define G_WAIT_V(n) asm volatile("s_waitcnt vmcnt(" #n ")" ::: "memory")
; #define G_WAIT_L(n) asm volatile("s_waitcnt lgkmcnt(" #n ")" ::: "memory")
; #define G_BAR __builtin_amdgcn_s_barrier()
; #define G_SCHED __builtin_amdgcn_sched_barrier(0)
;     ...
;             G_STAGE(G_SB(0, 1), b2 + chB, cB0, qB);
;             G_WAIT_V(6); G_BAR; G_MMA(1, 1, At, B1); G_BAR;
;             G_LDB(B0, 1, 0); G_SCHED; G_LDA(At, 1, 0); G_STAGE(G_SA(0, 1), a2 + chA, cA0, qA);
;             G_WAIT_L(8); G_BAR; G_WAIT_L(0); G_MMA(0, 0, At, B0); G_BAR; G_SCHED;
;             G_LDB(B1, 1, 1); G_STAGE(G_SB(1, 0), b3, cB0, qB);
;             G_BAR; G_WAIT_L(0); G_MMA(0, 1, At, B1); G_BAR;
;             G_LDA(At, 1, 1); G_STAGE(G_SA(1, 0), a3, cA0, qA);
;             G_BAR; G_WAIT_L(0); G_MMA(1, 0, At, B0); G_BAR; G_SCHED;
;             G_STAGE(G_SB(1, 1), b3 + chB, cB0, qB);
	s_add_i32 s4, s44, s27
	v_lshl_add_u64 v[136:137], v[184:185], 0, s[54:55]
	s_mov_b32 m0, s4
	s_nop 0
	global_load_lds_dwordx4 v[136:137], off
	v_lshl_add_u64 v[136:137], v[184:185], 0, s[58:59]
	s_add_i32 m0, s4, 0x2000
	s_nop 0
	global_load_lds_dwordx4 v[136:137], off
	s_waitcnt vmcnt(6)
	s_barrier
	s_setprio 3
	v_mfma_f32_16x16x32_bf16 v[60:63], v[208:211], v[152:155], v[60:63]
	v_mfma_f32_16x16x32_bf16 v[56:59], v[216:219], v[152:155], v[56:59]
	v_mfma_f32_16x16x32_bf16 v[44:47], v[208:211], v[164:167], v[44:47]
	v_mfma_f32_16x16x32_bf16 v[40:43], v[216:219], v[164:167], v[40:43]
	v_mfma_f32_16x16x32_bf16 v[28:31], v[208:211], v[176:179], v[28:31]
	v_mfma_f32_16x16x32_bf16 v[24:27], v[216:219], v[176:179], v[24:27]
	v_mfma_f32_16x16x32_bf16 v[12:15], v[208:211], v[200:203], v[12:15]
	v_mfma_f32_16x16x32_bf16 v[8:11], v[216:219], v[200:203], v[8:11]
	v_mfma_f32_16x16x32_bf16 v[60:63], v[212:215], v[160:163], v[60:63]
	v_mfma_f32_16x16x32_bf16 v[56:59], v[220:223], v[160:163], v[56:59]
	v_mfma_f32_16x16x32_bf16 v[44:47], v[212:215], v[172:175], v[44:47]
	v_mfma_f32_16x16x32_bf16 v[40:43], v[220:223], v[172:175], v[40:43]
	v_mfma_f32_16x16x32_bf16 v[28:31], v[212:215], v[196:199], v[28:31]
	v_mfma_f32_16x16x32_bf16 v[24:27], v[220:223], v[196:199], v[24:27]
	v_mfma_f32_16x16x32_bf16 v[12:15], v[212:215], v[204:207], v[12:15]
	v_mfma_f32_16x16x32_bf16 v[8:11], v[220:223], v[204:207], v[8:11]
	s_setprio 0
	s_add_i32 s4, 0, 0x18000
	v_add_u32_e32 v0, s4, v181
	s_barrier
	ds_read_b128 v[136:139], v0
	ds_read_b128 v[140:143], v0 offset:1024
	ds_read_b128 v[144:147], v0 offset:2048
	ds_read_b128 v[148:151], v0 offset:3072
	s_mov_b32 m0, s31
	v_lshl_add_u64 v[208:209], v[224:225], 0, s[54:55]
	ds_read_b128 v[152:155], v182 offset:32768
	ds_read_b128 v[160:163], v182 offset:33792
	ds_read_b128 v[164:167], v182 offset:34816
	ds_read_b128 v[172:175], v182 offset:35840
	ds_read_b128 v[176:179], v182 offset:36864
	ds_read_b128 v[196:199], v182 offset:37888
	ds_read_b128 v[200:203], v182 offset:38912
	ds_read_b128 v[204:207], v182 offset:39936
	global_load_lds_dwordx4 v[208:209], off
	v_lshl_add_u64 v[208:209], v[224:225], 0, s[58:59]
	s_mov_b32 m0, s34
	s_nop 0
	global_load_lds_dwordx4 v[208:209], off
	s_waitcnt lgkmcnt(8)
	s_barrier
	s_waitcnt lgkmcnt(0)
	s_setprio 3
	s_waitcnt lgkmcnt(0)
	v_mfma_f32_16x16x32_bf16 v[132:135], v[136:139], v[152:155], v[132:135]
	v_mfma_f32_16x16x32_bf16 v[128:131], v[144:147], v[152:155], v[128:131]
	v_mfma_f32_16x16x32_bf16 v[116:119], v[136:139], v[164:167], v[116:119]
	v_mfma_f32_16x16x32_bf16 v[112:115], v[144:147], v[164:167], v[112:115]
	v_mfma_f32_16x16x32_bf16 v[100:103], v[136:139], v[176:179], v[100:103]
	v_mfma_f32_16x16x32_bf16 v[96:99], v[144:147], v[176:179], v[96:99]
	v_mfma_f32_16x16x32_bf16 v[84:87], v[136:139], v[200:203], v[84:87]
	v_mfma_f32_16x16x32_bf16 v[80:83], v[144:147], v[200:203], v[80:83]
	v_mfma_f32_16x16x32_bf16 v[132:135], v[140:143], v[160:163], v[132:135]
	v_mfma_f32_16x16x32_bf16 v[128:131], v[148:151], v[160:163], v[128:131]
	v_mfma_f32_16x16x32_bf16 v[116:119], v[140:143], v[172:175], v[116:119]
	v_mfma_f32_16x16x32_bf16 v[112:115], v[148:151], v[172:175], v[112:115]
	v_mfma_f32_16x16x32_bf16 v[100:103], v[140:143], v[196:199], v[100:103]
	v_mfma_f32_16x16x32_bf16 v[96:99], v[148:151], v[196:199], v[96:99]
	v_mfma_f32_16x16x32_bf16 v[84:87], v[140:143], v[204:207], v[84:87]
	v_mfma_f32_16x16x32_bf16 v[80:83], v[148:151], v[204:207], v[80:83]
	s_setprio 0
	s_barrier
	s_add_i32 s5, 0, 0x1c000
	s_add_i32 s4, s4, s27
	v_add_u32_e32 v0, s5, v181
	v_lshl_add_u64 v[226:227], v[184:185], 0, s[46:47]
	s_mov_b32 m0, s4
	ds_read_b128 v[208:211], v0
	ds_read_b128 v[212:215], v0 offset:1024
	ds_read_b128 v[216:219], v0 offset:2048
	ds_read_b128 v[220:223], v0 offset:3072
	global_load_lds_dwordx4 v[226:227], off
	v_lshl_add_u64 v[226:227], v[184:185], 0, s[62:63]
	s_add_i32 m0, s4, 0x2000
	s_nop 0
	global_load_lds_dwordx4 v[226:227], off
	s_barrier
; #define G_STAGE(bufoff, gbase, o0, h64) do { \
;         __builtin_amdgcn_global_load_lds((const unsigned*)((const char*)(gbase) + (o0)), (LAS unsigned*)(lds + (bufoff) + ldsw), 16, 0, 0); \
;         __builtin_amdgcn_global_load_lds((const unsigned*)((const char*)(gbase) + (h64) + (o0)), (LAS unsigned*)(lds + (bufoff) + ldsw + 8192), 16, 0, 0); } while (0)
; #define G_LDA(dst, b, h) do { _Pragma("unroll") for (int m = 0; m < 4; ++m) _Pragma("unroll") for (int k = 0; k < 2; ++k) dst[m][k] = *(const LAS bf16x8*)(lds + G_SA(b, h) + aoff + m * 2048 + k * 1024); } while (0)
; #define G_WAIT_V(n) asm volatile("s_waitcnt vmcnt(" #n ")" ::: "memory")
; #define G_WAIT_L(n) asm volatile("s_waitcnt lgkmcnt(" #n ")" ::: "memory")
; #define G_BAR __builtin_amdgcn_s_barrier()
; #define G_SCHED __builtin_amdgcn_sched_barrier(0)
;     ...
;             G_LDA(At, 1, 1); G_STAGE(G_SA(1, 0), a3, cA0, qA);
;             G_BAR; G_WAIT_L(0); G_MMA(1, 0, At, B0); G_BAR; G_SCHED;
;             G_STAGE(G_SB(1, 1), b3 + chB, cB0, qB);
;             G_WAIT_V(6); G_BAR; G_MMA(1, 1, At, B1); G_BAR;
;         }
;         E.template run<cs.kind>(acc, cur, tid);
;         if (!has_next) break;
	s_waitcnt lgkmcnt(0)
	s_setprio 3
	s_waitcnt lgkmcnt(0)
	v_mfma_f32_16x16x32_bf16 v[124:127], v[208:211], v[152:155], v[124:127]
	v_mfma_f32_16x16x32_bf16 v[120:123], v[216:219], v[152:155], v[120:123]
	v_mfma_f32_16x16x32_bf16 v[108:111], v[208:211], v[164:167], v[108:111]
	v_mfma_f32_16x16x32_bf16 v[104:107], v[216:219], v[164:167], v[104:107]
	v_mfma_f32_16x16x32_bf16 v[92:95], v[208:211], v[176:179], v[92:95]
	v_mfma_f32_16x16x32_bf16 v[88:91], v[216:219], v[176:179], v[88:91]
	v_mfma_f32_16x16x32_bf16 v[76:79], v[208:211], v[200:203], v[76:79]
	v_mfma_f32_16x16x32_bf16 v[72:75], v[216:219], v[200:203], v[72:75]
	v_mfma_f32_16x16x32_bf16 v[124:127], v[212:215], v[160:163], v[124:127]
	v_mfma_f32_16x16x32_bf16 v[120:123], v[220:223], v[160:163], v[120:123]
	v_mfma_f32_16x16x32_bf16 v[108:111], v[212:215], v[172:175], v[108:111]
	v_mfma_f32_16x16x32_bf16 v[104:107], v[220:223], v[172:175], v[104:107]
	v_mfma_f32_16x16x32_bf16 v[92:95], v[212:215], v[196:199], v[92:95]
	v_mfma_f32_16x16x32_bf16 v[88:91], v[220:223], v[196:199], v[88:91]
	v_mfma_f32_16x16x32_bf16 v[76:79], v[212:215], v[204:207], v[76:79]
	v_mfma_f32_16x16x32_bf16 v[72:75], v[220:223], v[204:207], v[72:75]
	s_setprio 0
	s_mov_b32 m0, s35
	v_lshl_add_u64 v[226:227], v[224:225], 0, s[46:47]
	s_barrier
	ds_read_b128 v[152:155], v182 offset:49152
	ds_read_b128 v[160:163], v182 offset:50176
	ds_read_b128 v[164:167], v182 offset:51200
	ds_read_b128 v[172:175], v182 offset:52224
	ds_read_b128 v[176:179], v182 offset:53248
	ds_read_b128 v[196:199], v182 offset:54272
	ds_read_b128 v[200:203], v182 offset:55296
	ds_read_b128 v[204:207], v182 offset:56320
	global_load_lds_dwordx4 v[226:227], off
	v_lshl_add_u64 v[224:225], v[224:225], 0, s[62:63]
	s_mov_b32 m0, s36
	s_nop 0
	global_load_lds_dwordx4 v[224:225], off
	s_barrier
	s_waitcnt lgkmcnt(0)
	s_setprio 3
	s_waitcnt lgkmcnt(0)
	v_mfma_f32_16x16x32_bf16 v[68:71], v[136:139], v[152:155], v[68:71]
	v_mfma_f32_16x16x32_bf16 v[64:67], v[144:147], v[152:155], v[64:67]
	v_mfma_f32_16x16x32_bf16 v[52:55], v[136:139], v[164:167], v[52:55]
	v_mfma_f32_16x16x32_bf16 v[48:51], v[144:147], v[164:167], v[48:51]
	v_mfma_f32_16x16x32_bf16 v[36:39], v[136:139], v[176:179], v[36:39]
	v_mfma_f32_16x16x32_bf16 v[32:35], v[144:147], v[176:179], v[32:35]
	v_mfma_f32_16x16x32_bf16 v[20:23], v[136:139], v[200:203], v[20:23]
	v_mfma_f32_16x16x32_bf16 v[16:19], v[144:147], v[200:203], v[16:19]
	v_mfma_f32_16x16x32_bf16 v[68:71], v[140:143], v[160:163], v[68:71]
	v_mfma_f32_16x16x32_bf16 v[64:67], v[148:151], v[160:163], v[64:67]
	v_mfma_f32_16x16x32_bf16 v[52:55], v[140:143], v[172:175], v[52:55]
	v_mfma_f32_16x16x32_bf16 v[48:51], v[148:151], v[172:175], v[48:51]
	v_mfma_f32_16x16x32_bf16 v[36:39], v[140:143], v[196:199], v[36:39]
	v_mfma_f32_16x16x32_bf16 v[32:35], v[148:151], v[196:199], v[32:35]
	v_mfma_f32_16x16x32_bf16 v[20:23], v[140:143], v[204:207], v[20:23]
	v_mfma_f32_16x16x32_bf16 v[16:19], v[148:151], v[204:207], v[16:19]
	s_setprio 0
	s_barrier
	s_add_i32 s4, s5, s27
	v_lshl_add_u64 v[136:137], v[184:185], 0, s[64:65]
	s_mov_b32 m0, s4
	s_nop 0
	global_load_lds_dwordx4 v[136:137], off
	v_lshl_add_u64 v[136:137], v[184:185], 0, s[66:67]
	s_add_i32 m0, s4, 0x2000
	s_nop 0
	global_load_lds_dwordx4 v[136:137], off
	s_waitcnt vmcnt(6)
	s_barrier
	s_setprio 3
	v_mfma_f32_16x16x32_bf16 v[60:63], v[208:211], v[152:155], v[60:63]
	v_mfma_f32_16x16x32_bf16 v[56:59], v[216:219], v[152:155], v[56:59]
	v_mfma_f32_16x16x32_bf16 v[44:47], v[208:211], v[164:167], v[44:47]
	v_mfma_f32_16x16x32_bf16 v[40:43], v[216:219], v[164:167], v[40:43]
	v_mfma_f32_16x16x32_bf16 v[28:31], v[208:211], v[176:179], v[28:31]
	v_mfma_f32_16x16x32_bf16 v[24:27], v[216:219], v[176:179], v[24:27]
	v_mfma_f32_16x16x32_bf16 v[12:15], v[208:211], v[200:203], v[12:15]
	v_mfma_f32_16x16x32_bf16 v[8:11], v[216:219], v[200:203], v[8:11]
	v_mfma_f32_16x16x32_bf16 v[60:63], v[212:215], v[160:163], v[60:63]
	v_mfma_f32_16x16x32_bf16 v[56:59], v[220:223], v[160:163], v[56:59]
	v_mfma_f32_16x16x32_bf16 v[44:47], v[212:215], v[172:175], v[44:47]
	v_mfma_f32_16x16x32_bf16 v[40:43], v[220:223], v[172:175], v[40:43]
	v_mfma_f32_16x16x32_bf16 v[28:31], v[212:215], v[196:199], v[28:31]
	v_mfma_f32_16x16x32_bf16 v[24:27], v[220:223], v[196:199], v[24:27]
	v_mfma_f32_16x16x32_bf16 v[12:15], v[212:215], v[204:207], v[12:15]
	v_mfma_f32_16x16x32_bf16 v[8:11], v[220:223], v[204:207], v[8:11]
	s_setprio 0
	s_add_i32 s24, s24, 2
	s_add_u32 s2, s2, 0x100
	s_addc_u32 s3, s3, 0
	s_add_u32 s22, s22, 0x100
	s_addc_u32 s23, s23, 0
	s_cmp_gt_u32 s24, 13
	s_cbranch_scc0 .Ldb_PLE1_cont
	v_readfirstlane_b32 s101, v186
	s_cmpk_gt_u32 s101, 0xff
	s_cbranch_scc1 .Ldb_PLE1_exit
	s_barrier
	s_branch .Ldb_PLE1_exit

; __device__ __forceinline__ float sigmoidf_(float v) { return __builtin_amdgcn_rcpf(1.0f + __expf(-v)); }
;     __device__ __forceinline__ void get_rs(const Unit& u, int wr, int fr, float (&rs)[8]) const {
; #pragma unroll
;         for (int r8 = 0; r8 < 8; ++r8) rs[r8] = rstab[u.ord * 256 + (r8 >> 2) * 128 + wr * 64 + (r8 & 3) * 16 + fr];
;     }
;     template <int KIND> __device__ __forceinline__ void run(f32x4 (&acc)[2][2][4][2], const Unit& u, int tid_in) const {
;     ...
;         if constexpr (KIND == K_PLE) {
;             const bf16_t* xsrc = mg; float rs[8]; get_rs(u, wr, fr, rs);
; #pragma unroll
;             for (int ai = 0; ai < 2; ++ai)
; #pragma unroll
;                 for (int mh = 0; mh < 2; ++mh) { u32x4 xv[2][2], pv[2][2];
; #pragma unroll
;                     for (int ml = 0; ml < 2; ++ml) { const int m = mh * 2 + ml; int row = rbase + ai * 128 + m * 16; asm volatile("" : "+v"(row));
; #pragma unroll
;                         for (int bj = 0; bj < 2; ++bj) { xv[ml][bj] = *(const u32x4*)(xsrc + (size_t)row * 1024 + u.pn * 256 + bj * 128 + cl); pv[ml][bj] = scr[((ai * 4 + m) * 2 + bj) * 512 + tid]; } }
; #pragma unroll
;                     for (int ml = 0; ml < 2; ++ml) { const int m = mh * 2 + ml; int row = rbase + ai * 128 + m * 16; asm volatile("" : "+v"(row)); float ss = 0.f; const float r = rs[ai * 4 + m];
; #pragma unroll
;                         for (int bj = 0; bj < 2; ++bj) { const size_t off = (size_t)row * 1024 + u.pn * 256 + bj * 128 + cl; f32x4 a = acc[ai][bj][m][0], b = acc[ai][bj][m][1], p0, p1, x0, x1;
;                             unpack8(pv[ml][bj], p0, p1); unpack8(xv[ml][bj], x0, x1);
; #pragma unroll
;                             for (int j = 0; j < 4; ++j) { a[j] = sigmoidf_(a[j] * r) * p0[j]; b[j] = sigmoidf_(b[j] * r) * p1[j]; }
;                             const f32x4 o0 = x0 + a, o1 = x1 + b;
;                             *(u32x4*)(xb0 + off) = pack8(o0, o1);
;                             { u32x2 w8; w8.x = pack4_fp8(o0[0], o0[1], o0[2], o0[3]); w8.y = pack4_fp8(o1[0], o1[1], o1[2], o1[3]); *(u32x2*)((unsigned char*)zb + (size_t)row * (ZW * 2) + u.pn * 256 + bj * 128 + cl) = w8; }
;                             ss += (o0[0] * o0[0] + o0[1] * o0[1]) + (o0[2] * o0[2] + o0[3] * o0[3]) + (o1[0] * o1[0] + o1[1] * o1[1]) + (o1[2] * o1[2] + o1[3] * o1[3]); }
.Ldb_PLE1_exit:
	v_mov_b32_e32 v136, v180
	s_lshl_b32 s2, s33, 17
	v_readfirstlane_b32 s4, v136
	s_bfe_u32 s53, s4, 0x20006
	s_and_b32 s2, s2, 0x20000
	s_add_u32 s2, s43, s2
	s_addc_u32 s3, s50, 0
	s_lshl_b32 s5, s7, 8
	s_ashr_i32 s7, s4, 2
	s_andn2_b32 s7, s7, 63
	s_add_i32 s7, s7, s5
	s_lshl_b32 s5, s33, 10
	s_add_i32 s5, s5, 0
	s_and_b32 s4, s4, 0xffffff00
	v_and_b32_e32 v0, 15, v136
	s_add_i32 s5, s5, s4
	v_or_b32_e32 v183, s7, v0
	v_lshl_add_u32 v0, v0, 2, s5
	v_add_u32_e32 v0, 0x20010, v0
	v_mov_b32_e32 v138, v183
	v_bfe_u32 v140, v136, 4, 2
	ds_read2_b32 v[176:177], v0 offset1:16
	ds_read2_b32 v[172:173], v0 offset0:32 offset1:48
	ds_read2_b32 v[166:167], v0 offset0:128 offset1:144
	ds_read2_b32 v[160:161], v0 offset0:160 offset1:176
	s_lshl_b32 s22, s6, 8
	v_ashrrev_i32_e32 v139, 31, v138
	v_lshlrev_b32_e32 v137, 3, v140
	v_lshlrev_b64 v[138:139], 11, v[138:139]
	s_ashr_i32 s23, s22, 31
	v_lshl_or_b32 v162, s53, 5, v137
	v_lshl_add_u64 v[138:139], s[8:9], 0, v[138:139]
	s_lshl_b64 s[24:25], s[22:23], 1
	v_lshl_add_u64 v[138:139], v[138:139], 0, s[24:25]
	v_lshlrev_b32_e32 v0, 1, v162
	v_ashrrev_i32_e32 v137, 31, v136
	v_lshl_add_u64 v[138:139], v[138:139], 0, v[0:1]
	v_lshl_add_u64 v[164:165], v[136:137], 4, s[2:3]
	global_load_dwordx4 v[196:199], v[138:139], off
	global_load_dwordx4 v[200:203], v[164:165], off
	s_movk_i32 s2, 0x2000
	v_add_co_u32_e32 v136, vcc, s2, v164
	v_cmp_eq_u32_e64 s[40:41], 0, v140
	s_nop 0
	v_addc_co_u32_e32 v137, vcc, 0, v165, vcc
	global_load_dwordx4 v[204:207], v[138:139], off offset:256
	global_load_dwordx4 v[152:155], v[136:137], off
	v_add_co_u32_e32 v140, vcc, s49, v164
	v_or_b32_e32 v174, 16, v183
	s_nop 0
	v_addc_co_u32_e32 v141, vcc, 0, v165, vcc
	s_movk_i32 s2, 0x6000
	v_mov_b32_e32 v148, v174
	s_waitcnt lgkmcnt(0)
	v_mul_f32_e32 v132, v132, v176
	v_mul_f32_e32 v133, v133, v176
	v_add_co_u32_e32 v142, vcc, s2, v164
	v_mul_f32_e32 v132, 0xbfb8aa3b, v132
	v_mul_f32_e32 v133, 0xbfb8aa3b, v133
	v_ashrrev_i32_e32 v149, 31, v148
	v_addc_co_u32_e32 v143, vcc, 0, v165, vcc
	global_load_dwordx4 v[144:147], v[140:141], off
	global_load_dwordx4 v[136:139], v[142:143], off
	v_exp_f32_e32 v140, v132
	v_exp_f32_e32 v195, v133
	v_lshlrev_b64 v[132:133], 11, v[148:149]
	v_lshl_add_u64 v[132:133], s[8:9], 0, v[132:133]
	v_mul_f32_e32 v128, v128, v176
	v_lshl_add_u64 v[132:133], v[132:133], 0, s[24:25]
	v_mul_f32_e32 v128, 0xbfb8aa3b, v128
	v_lshl_add_u64 v[132:133], v[132:133], 0, v[0:1]
	v_exp_f32_e32 v175, v128
	v_add_f32_e32 v128, 1.0, v140
	global_load_dwordx4 v[148:151], v[132:133], off
	global_load_dwordx4 v[140:143], v[132:133], off offset:256
	v_mul_f32_e32 v129, v129, v176
	v_add_f32_e32 v175, 1.0, v175
	v_mul_f32_e32 v129, 0xbfb8aa3b, v129
	v_rcp_f32_e32 v212, v175
	v_add_f32_e32 v175, 1.0, v195
	v_exp_f32_e32 v195, v129
	v_mul_f32_e32 v134, v134, v176
	v_mul_f32_e32 v134, 0xbfb8aa3b, v134
	v_mul_f32_e32 v130, v130, v176
	v_rcp_f32_e32 v129, v175
	v_add_f32_e32 v175, 1.0, v195
	v_exp_f32_e32 v134, v134
	v_mul_f32_e32 v130, 0xbfb8aa3b, v130
	v_rcp_f32_e32 v213, v175
	v_exp_f32_e32 v175, v130
	v_mul_f32_e32 v130, v135, v176
	v_mul_f32_e32 v130, 0xbfb8aa3b, v130
	v_mul_f32_e32 v131, v131, v176
	v_add_f32_e32 v134, 1.0, v134
	v_exp_f32_e32 v135, v130
	v_mul_f32_e32 v131, 0xbfb8aa3b, v131
	v_rcp_f32_e32 v130, v134
	v_add_f32_e32 v134, 1.0, v175
	v_exp_f32_e32 v175, v131
	v_mov_b32_e32 v178, v183
	v_add_f32_e32 v135, 1.0, v135
	v_mov_b64_e32 v[184:185], s[10:11]
	v_rcp_f32_e32 v128, v128
	v_ashrrev_i32_e32 v179, 31, v178
	v_rcp_f32_e32 v131, v135
	v_add_f32_e32 v135, 1.0, v175
	v_mad_i64_i32 v[132:133], s[2:3], v178, s76, v[184:185]
	v_lshlrev_b64 v[184:185], 11, v[178:179]
	v_rcp_f32_e32 v134, v134
	v_rcp_f32_e32 v135, v135
	v_lshl_add_u64 v[184:185], s[12:13], 0, v[184:185]
	v_lshl_add_u64 v[184:185], v[184:185], 0, s[24:25]
	v_lshl_add_u64 v[184:185], v[184:185], 0, v[0:1]
	v_mov_b32_e32 v163, v1
	v_mul_f32_e32 v124, v124, v176
	s_waitcnt vmcnt(0)
; __device__ __forceinline__ float sigmoidf_(float v) { return __builtin_amdgcn_rcpf(1.0f + __expf(-v)); }
; __device__ __forceinline__ u32x4 pack8(const f32x4 a, const f32x4 b) { u32x4 w; w.x = cvt_pk_bf16(a[0], a[1]); w.y = cvt_pk_bf16(a[2], a[3]); w.z = cvt_pk_bf16(b[0], b[1]); w.w = cvt_pk_bf16(b[2], b[3]); return w; }
; __device__ __forceinline__ void unpack8(const u32x4 w, f32x4& a, f32x4& b) { a[0] = bf_lo(w.x); a[1] = bf_hi(w.x); a[2] = bf_lo(w.y); a[3] = bf_hi(w.y); b[0] = bf_lo(w.z); b[1] = bf_hi(w.z); b[2] = bf_lo(w.w); b[3] = bf_hi(w.w); }
; __device__ __forceinline__ unsigned pack4_fp8(float a, float b, float c, float d) { unsigned w = 0u; w = __builtin_amdgcn_cvt_pk_fp8_f32(a, b, w, false); w = __builtin_amdgcn_cvt_pk_fp8_f32(c, d, w, true); return w; }
;     template <int KIND> __device__ __forceinline__ void run(f32x4 (&acc)[2][2][4][2], const Unit& u, int tid_in) const {
;     ...
;                     for (int ml = 0; ml < 2; ++ml) { const int m = mh * 2 + ml; int row = rbase + ai * 128 + m * 16; asm volatile("" : "+v"(row)); float ss = 0.f; const float r = rs[ai * 4 + m];
; #pragma unroll
;                         for (int bj = 0; bj < 2; ++bj) { const size_t off = (size_t)row * 1024 + u.pn * 256 + bj * 128 + cl; f32x4 a = acc[ai][bj][m][0], b = acc[ai][bj][m][1], p0, p1, x0, x1;
;                             unpack8(pv[ml][bj], p0, p1); unpack8(xv[ml][bj], x0, x1);
; #pragma unroll
;                             for (int j = 0; j < 4; ++j) { a[j] = sigmoidf_(a[j] * r) * p0[j]; b[j] = sigmoidf_(b[j] * r) * p1[j]; }
;                             const f32x4 o0 = x0 + a, o1 = x1 + b;
;                             *(u32x4*)(xb0 + off) = pack8(o0, o1);
;                             { u32x2 w8; w8.x = pack4_fp8(o0[0], o0[1], o0[2], o0[3]); w8.y = pack4_fp8(o1[0], o1[1], o1[2], o1[3]); *(u32x2*)((unsigned char*)zb + (size_t)row * (ZW * 2) + u.pn * 256 + bj * 128 + cl) = w8; }
;                             ss += (o0[0] * o0[0] + o0[1] * o0[1]) + (o0[2] * o0[2] + o0[3] * o0[3]) + (o1[0] * o1[0] + o1[1] * o1[1]) + (o1[2] * o1[2] + o1[3] * o1[3]); }
;                         ss += __shfl_xor(ss, 16); ss += __shfl_xor(ss, 32);
;                         if (fq == 0) ssq0[((size_t)u.pn * T_TOK + row) * 4 + wc] = ss; }
	v_lshlrev_b32_e32 v208, 16, v196
	v_and_b32_e32 v209, 0xffff0000, v196
	v_lshlrev_b32_e32 v196, 16, v197
	v_and_b32_e32 v197, 0xffff0000, v197
	v_lshlrev_b32_e32 v214, 16, v200
	v_and_b32_e32 v215, 0xffff0000, v200
	v_lshlrev_b32_e32 v200, 16, v201
	v_and_b32_e32 v201, 0xffff0000, v201
	v_lshlrev_b32_e32 v210, 16, v198
	v_and_b32_e32 v211, 0xffff0000, v198
	v_lshlrev_b32_e32 v198, 16, v199
	v_and_b32_e32 v199, 0xffff0000, v199
	v_lshlrev_b32_e32 v216, 16, v202
	v_and_b32_e32 v217, 0xffff0000, v202
	v_lshlrev_b32_e32 v202, 16, v203
	v_and_b32_e32 v203, 0xffff0000, v203
	v_pk_fma_f32 v[196:197], v[130:131], v[200:201], v[196:197]
	v_pk_fma_f32 v[200:201], v[128:129], v[214:215], v[208:209]
	v_pk_fma_f32 v[134:135], v[134:135], v[202:203], v[198:199]
	v_cvt_pk_bf16_f32 v128, v200, v201
	v_cvt_pk_bf16_f32 v129, v196, v197
	v_pk_fma_f32 v[198:199], v[212:213], v[216:217], v[210:211]
	v_mul_f32_e32 v0, v201, v201
	v_cvt_pk_bf16_f32 v130, v198, v199
	v_cvt_pk_bf16_f32 v131, v134, v135
	global_store_dwordx4 v[184:185], v[128:131], off
	v_mul_f32_e32 v124, 0xbfb8aa3b, v124
	v_mul_f32_e32 v120, v120, v176
	v_lshl_add_u64 v[128:129], v[132:133], 0, s[22:23]
	v_lshl_add_u64 v[130:131], v[128:129], 0, v[162:163]
	v_mul_f32_e32 v128, v197, v197
	v_fmac_f32_e32 v0, v200, v200
	v_fmac_f32_e32 v128, v196, v196
	v_exp_f32_e32 v124, v124
	v_mul_f32_e32 v120, 0xbfb8aa3b, v120
	v_mul_f32_e32 v122, v122, v176
	v_mov_b32_e32 v203, v1
	v_add_f32_e32 v0, v0, v128
	v_mul_f32_e32 v128, v199, v199
	v_exp_f32_e32 v175, v120
	v_mul_f32_e32 v122, 0xbfb8aa3b, v122
	v_cvt_pk_fp8_f32 v203, v198, v199
	v_fmac_f32_e32 v128, v198, v198
	v_mul_f32_e32 v120, v125, v176
	v_lshlrev_b32_e32 v198, 16, v152
	v_and_b32_e32 v199, 0xffff0000, v152
	v_mul_f32_e32 v126, v126, v176
	v_exp_f32_e32 v152, v122
	v_mul_f32_e32 v122, v127, v176
	v_mul_f32_e32 v120, 0xbfb8aa3b, v120
	v_mul_f32_e32 v121, v121, v176
	v_mul_f32_e32 v126, 0xbfb8aa3b, v126
	v_mul_f32_e32 v122, 0xbfb8aa3b, v122
	v_add_f32_e32 v124, 1.0, v124
	v_exp_f32_e32 v125, v120
	v_mul_f32_e32 v121, 0xbfb8aa3b, v121
	v_exp_f32_e32 v126, v126
	v_exp_f32_e32 v127, v122
	v_rcp_f32_e32 v120, v124
	v_add_f32_e32 v124, 1.0, v175
	v_exp_f32_e32 v175, v121
	v_mul_f32_e32 v123, v123, v176
	v_mov_b32_e32 v202, v1
	v_mul_f32_e32 v123, 0xbfb8aa3b, v123
	v_cvt_pk_fp8_f32 v202, v200, v201
	v_add_f32_e32 v125, 1.0, v125
	v_lshlrev_b32_e32 v200, 16, v154
	v_and_b32_e32 v201, 0xffff0000, v154
	v_add_f32_e32 v126, 1.0, v126
	v_add_f32_e32 v127, 1.0, v127
	v_exp_f32_e32 v154, v123
	v_rcp_f32_e32 v121, v125
	v_add_f32_e32 v125, 1.0, v175
	v_rcp_f32_e32 v122, v126
	v_rcp_f32_e32 v123, v127
	v_add_f32_e32 v0, v128, v0
	v_mul_f32_e32 v128, v135, v135
	v_rcp_f32_e32 v124, v124
	v_rcp_f32_e32 v125, v125
	v_fmac_f32_e32 v128, v134, v134
	v_add_f32_e32 v0, v128, v0
	v_lshlrev_b32_e32 v128, 16, v204
	v_and_b32_e32 v129, 0xffff0000, v204
	v_lshlrev_b32_e32 v132, 16, v205
	v_and_b32_e32 v133, 0xffff0000, v205
	v_add_f32_e32 v126, 1.0, v152
	v_lshlrev_b32_e32 v152, 16, v153
	v_and_b32_e32 v153, 0xffff0000, v153
	v_add_f32_e32 v127, 1.0, v154
	v_cvt_pk_fp8_f32 v203, v134, v135 op_sel:[0,0,1]
	v_lshlrev_b32_e32 v134, 16, v206
	v_and_b32_e32 v135, 0xffff0000, v206
	v_rcp_f32_e32 v126, v126
	v_rcp_f32_e32 v127, v127
	v_pk_fma_f32 v[122:123], v[122:123], v[152:153], v[132:133]
	v_pk_fma_f32 v[120:121], v[120:121], v[198:199], v[128:129]
	v_pk_fma_f32 v[128:129], v[124:125], v[200:201], v[134:135]
	v_mul_f32_e32 v124, v121, v121
	v_mul_f32_e32 v125, v123, v123
	v_fmac_f32_e32 v124, v120, v120
	v_fmac_f32_e32 v125, v122, v122
	v_cvt_pk_fp8_f32 v202, v196, v197 op_sel:[0,0,1]
	v_lshlrev_b32_e32 v196, 16, v207
	v_and_b32_e32 v197, 0xffff0000, v207
	v_lshlrev_b32_e32 v154, 16, v155
	v_and_b32_e32 v155, 0xffff0000, v155
	v_add_f32_e32 v124, v124, v125
	v_mul_f32_e32 v125, v129, v129
	v_pk_fma_f32 v[132:133], v[126:127], v[154:155], v[196:197]
	v_fmac_f32_e32 v125, v128, v128
	v_add_f32_e32 v124, v125, v124
	v_mul_f32_e32 v125, v133, v133
	v_fmac_f32_e32 v125, v132, v132
	v_add_f32_e32 v124, v125, v124
	v_add_f32_e32 v0, v0, v124
	v_xor_b32_e32 v124, 16, v190
	v_cmp_lt_i32_e32 vcc, v124, v192
	v_mov_b32_e32 v134, v1
	global_store_dwordx2 v[130:131], v[202:203], off
	v_cndmask_b32_e32 v124, v190, v124, vcc
	v_lshlrev_b32_e32 v124, 2, v124
	ds_bpermute_b32 v125, v124, v0
	v_cvt_pk_fp8_f32 v134, v120, v121
	v_cvt_pk_bf16_f32 v126, v120, v121
	v_xor_b32_e32 v120, 32, v190
	v_mov_b32_e32 v135, v1
	v_cmp_lt_i32_e32 vcc, v120, v192
	v_cvt_pk_fp8_f32 v135, v128, v129
	s_waitcnt lgkmcnt(0)
	v_add_f32_e32 v0, v0, v125
	v_cndmask_b32_e32 v120, v190, v120, vcc
	v_lshlrev_b32_e32 v125, 2, v120
	ds_bpermute_b32 v120, v125, v0
	v_cvt_pk_fp8_f32 v134, v122, v123 op_sel:[0,0,1]
	v_cvt_pk_fp8_f32 v135, v132, v133 op_sel:[0,0,1]
	v_cvt_pk_bf16_f32 v127, v122, v123
	v_cvt_pk_bf16_f32 v128, v128, v129
	v_cvt_pk_bf16_f32 v129, v132, v133
	global_store_dwordx4 v[184:185], v[126:129], off offset:256
	global_store_dwordx2 v[130:131], v[134:135], off offset:128
	s_and_saveexec_b64 s[2:3], s[40:41]
	s_cbranch_execz .LBB0_1286
	s_ashr_i32 s7, s6, 31
	s_lshl_b64 s[4:5], s[6:7], 19
	s_add_u32 s4, s39, s4
	s_addc_u32 s5, s42, s5
	s_waitcnt lgkmcnt(0)
	v_add_f32_e32 v0, v0, v120
	v_lshl_add_u64 v[120:121], v[178:179], 4, s[4:5]
	s_lshl_b32 s74, s53, 2
	v_lshl_add_u64 v[120:121], v[120:121], 0, s[74:75]
	global_store_dword v[120:121], v0, off
